# GEMM K-loops: the M0 wait state before the second tile DMA of a load section is supplied by that section's last ds_read instead of an s_nop
# baseline (speedup 1.0000x reference)
; #define PG8_STAGE(bufoff, gbase, voff) do { _Pragma("unroll") for (int _i = 0; _i < 2; ++_i) \
;         __builtin_amdgcn_global_load_lds((const unsigned*)((const char*)(gbase) + (voff)[_i]), (LAS unsigned*)(lds + (bufoff) + ldsw + _i * 8192), 16, 0, 0); } while (0)
; #define PG8_LDA(dst, b, h) do { _Pragma("unroll") for (int m = 0; m < 4; ++m) _Pragma("unroll") for (int k = 0; k < 2; ++k) dst[m][k] = *(const LAS bf16x8*)(lds + PG8_SA(b, h) + aoff + m * 2048 + k * 1024); } while (0)
; #define PG8_LDB(dst, b, h) do { _Pragma("unroll") for (int n = 0; n < 2; ++n) _Pragma("unroll") for (int k = 0; k < 2; ++k) dst[n][k] = *(const LAS bf16x8*)(lds + PG8_SB(b, h) + boff + n * 2048 + k * 1024); } while (0)
; #define PG8_MMA(ai, bj, At, Bt) do { __builtin_amdgcn_s_setprio(1); _Pragma("unroll") for (int m = 0; m < 4; ++m) _Pragma("unroll") for (int n = 0; n < 2; ++n) _Pragma("unroll") for (int k = 0; k < 2; ++k) \
;         acc[ai][bj][m][n] = __builtin_amdgcn_mfma_f32_16x16x32_bf16(Bt[n][k], At[m][k], acc[ai][bj][m][n], 0, 0, 0); __builtin_amdgcn_s_setprio(0); } while (0)
; #define PG8_WAIT_V(n) asm volatile("s_waitcnt vmcnt(" #n ")" ::: "memory")
; #define PG8_WAIT_L(n) asm volatile("s_waitcnt lgkmcnt(" #n ")" ::: "memory")
; template <class Epi>
; __device__ __forceinline__ void gemm_phase(LAS unsigned char* lds, const Gemm g, const StaticOrder& S, const Epi& E) {
;     ...
;         for (int t = 0; t < nt; t += 2) {
;             const bool last = (t == nt - 2);
;             const char* a1 = cA + (size_t)(t + 1) * kstep;
;             const char* a2 = last ? nA : cA + (size_t)(t + 2) * kstep; const char* b2 = last ? nB : cB + (size_t)(t + 2) * kstep;
;             const char* a3 = a2 + kstep; const char* b3 = b2 + kstep;
;             PG8_LDB(B0, 0, 0); PG8_SCHED; PG8_LDA(At, 0, 0); PG8_STAGE(PG8_SA(1, 1), a1 + hstep, voffA);
;             PG8_WAIT_L(8); PG8_BAR; PG8_WAIT_L(0); PG8_MMA(0, 0, At, B0); PG8_BAR; PG8_SCHED;
;             PG8_LDB(B1, 0, 1); PG8_STAGE(PG8_SB(0, 0), b2, voffB);
;             PG8_BAR; PG8_WAIT_L(0); PG8_MMA(0, 1, At, B1); PG8_BAR;
;             PG8_LDA(At, 0, 1); PG8_STAGE(PG8_SA(0, 0), a2, voffA);
;             PG8_BAR; PG8_WAIT_L(0); PG8_MMA(1, 0, At, B0); PG8_BAR; PG8_SCHED;
;             PG8_STAGE(PG8_SB(0, 1), b2 + hstep, voffB);
;             PG8_WAIT_V(6); PG8_BAR; PG8_MMA(1, 1, At, B1); PG8_BAR;
.LBB0_203:
	ds_read_b128 v[144:147], v153
	ds_read_b128 v[160:163], v153 offset:1024
	ds_read_b128 v[164:167], v153 offset:2048
	ds_read_b128 v[168:171], v153 offset:3072
	s_add_u32 s44, s42, 0xfff80080
	s_addc_u32 s45, s43, -1
	s_cmp_eq_u32 s54, 28
	s_cselect_b32 s47, s25, s45
	s_cselect_b32 s46, s50, s44
	s_cselect_b32 s45, s23, s53
	s_cselect_b32 s44, s51, s52
	s_add_i32 m0, s11, 0xc000
	ds_read_b128 v[172:175], v154
	ds_read_b128 v[176:179], v154 offset:1024
	ds_read_b128 v[180:183], v154 offset:2048
	ds_read_b128 v[184:187], v154 offset:3072
	ds_read_b128 v[188:191], v154 offset:4096
	ds_read_b128 v[192:195], v154 offset:5120
	ds_read_b128 v[196:199], v154 offset:6144
	global_load_lds_dwordx4 v136, s[42:43]
	s_add_i32 m0, s11, 0xe000
	ds_read_b128 v[200:203], v154 offset:7168
	global_load_lds_dwordx4 v138, s[42:43]
	s_waitcnt lgkmcnt(8)
	s_barrier
	s_waitcnt lgkmcnt(0)
	v_mfma_f32_16x16x32_bf16 v[124:127], v[144:147], v[172:175], v[124:127]
	v_mfma_f32_16x16x32_bf16 v[120:123], v[164:167], v[172:175], v[120:123]
	v_mfma_f32_16x16x32_bf16 v[108:111], v[144:147], v[180:183], v[108:111]
	v_mfma_f32_16x16x32_bf16 v[104:107], v[164:167], v[180:183], v[104:107]
	v_mfma_f32_16x16x32_bf16 v[92:95], v[144:147], v[188:191], v[92:95]
	v_mfma_f32_16x16x32_bf16 v[88:91], v[164:167], v[188:191], v[88:91]
	v_mfma_f32_16x16x32_bf16 v[76:79], v[144:147], v[196:199], v[76:79]
	v_mfma_f32_16x16x32_bf16 v[72:75], v[164:167], v[196:199], v[72:75]
	v_mfma_f32_16x16x32_bf16 v[124:127], v[160:163], v[176:179], v[124:127]
	v_mfma_f32_16x16x32_bf16 v[120:123], v[168:171], v[176:179], v[120:123]
	v_mfma_f32_16x16x32_bf16 v[108:111], v[160:163], v[184:187], v[108:111]
	v_mfma_f32_16x16x32_bf16 v[104:107], v[168:171], v[184:187], v[104:107]
	v_mfma_f32_16x16x32_bf16 v[92:95], v[160:163], v[192:195], v[92:95]
	v_mfma_f32_16x16x32_bf16 v[88:91], v[168:171], v[192:195], v[88:91]
	v_mfma_f32_16x16x32_bf16 v[76:79], v[160:163], v[200:203], v[76:79]
	v_mfma_f32_16x16x32_bf16 v[72:75], v[168:171], v[200:203], v[72:75]
	s_barrier
	s_add_i32 s55, s41, s10
	s_add_u32 s98, s44, s8
	s_addc_u32 s99, s45, s9
	s_mov_b32 m0, s55
	ds_read_b128 v[204:207], v155
	ds_read_b128 v[208:211], v155 offset:1024
	ds_read_b128 v[212:215], v155 offset:2048
	global_load_lds_dwordx4 v132, s[44:45]
	s_add_i32 m0, s55, 0x2000
	ds_read_b128 v[216:219], v155 offset:3072
	global_load_lds_dwordx4 v128, s[44:45]
	s_barrier
	s_waitcnt lgkmcnt(0)
	v_mfma_f32_16x16x32_bf16 v[116:119], v[204:207], v[172:175], v[116:119]
	v_mfma_f32_16x16x32_bf16 v[112:115], v[212:215], v[172:175], v[112:115]
	v_mfma_f32_16x16x32_bf16 v[100:103], v[204:207], v[180:183], v[100:103]
	v_mfma_f32_16x16x32_bf16 v[96:99], v[212:215], v[180:183], v[96:99]
	v_mfma_f32_16x16x32_bf16 v[84:87], v[204:207], v[188:191], v[84:87]
	v_mfma_f32_16x16x32_bf16 v[80:83], v[212:215], v[188:191], v[80:83]
	v_mfma_f32_16x16x32_bf16 v[68:71], v[204:207], v[196:199], v[68:71]
	v_mfma_f32_16x16x32_bf16 v[64:67], v[212:215], v[196:199], v[64:67]
	v_mfma_f32_16x16x32_bf16 v[116:119], v[208:211], v[176:179], v[116:119]
	v_mfma_f32_16x16x32_bf16 v[112:115], v[216:219], v[176:179], v[112:115]
	v_mfma_f32_16x16x32_bf16 v[100:103], v[208:211], v[184:187], v[100:103]
	v_mfma_f32_16x16x32_bf16 v[96:99], v[216:219], v[184:187], v[96:99]
	v_mfma_f32_16x16x32_bf16 v[84:87], v[208:211], v[192:195], v[84:87]
	v_mfma_f32_16x16x32_bf16 v[80:83], v[216:219], v[192:195], v[80:83]
	v_mfma_f32_16x16x32_bf16 v[68:71], v[208:211], v[200:203], v[68:71]
	v_mfma_f32_16x16x32_bf16 v[64:67], v[216:219], v[200:203], v[64:67]
	s_mov_b32 m0, s11
	s_add_u32 s100, s46, s8
	s_addc_u32 s101, s47, s9
	s_barrier
	ds_read_b128 v[172:175], v154 offset:16384
	ds_read_b128 v[176:179], v154 offset:17408
	ds_read_b128 v[180:183], v154 offset:18432
	ds_read_b128 v[184:187], v154 offset:19456
	ds_read_b128 v[188:191], v154 offset:20480
	ds_read_b128 v[192:195], v154 offset:21504
	ds_read_b128 v[196:199], v154 offset:22528
	global_load_lds_dwordx4 v134, s[46:47]
	s_mov_b32 m0, s13
	ds_read_b128 v[200:203], v154 offset:23552
	global_load_lds_dwordx4 v130, s[46:47]
	s_barrier
	s_waitcnt lgkmcnt(0)
	v_mfma_f32_16x16x32_bf16 v[60:63], v[144:147], v[172:175], v[60:63]
	v_mfma_f32_16x16x32_bf16 v[56:59], v[164:167], v[172:175], v[56:59]
	v_mfma_f32_16x16x32_bf16 v[44:47], v[144:147], v[180:183], v[44:47]
	v_mfma_f32_16x16x32_bf16 v[40:43], v[164:167], v[180:183], v[40:43]
	v_mfma_f32_16x16x32_bf16 v[28:31], v[144:147], v[188:191], v[28:31]
	v_mfma_f32_16x16x32_bf16 v[24:27], v[164:167], v[188:191], v[24:27]
	v_mfma_f32_16x16x32_bf16 v[12:15], v[144:147], v[196:199], v[12:15]
	v_mfma_f32_16x16x32_bf16 v[8:11], v[164:167], v[196:199], v[8:11]
	v_mfma_f32_16x16x32_bf16 v[60:63], v[160:163], v[176:179], v[60:63]
	v_mfma_f32_16x16x32_bf16 v[56:59], v[168:171], v[176:179], v[56:59]
	v_mfma_f32_16x16x32_bf16 v[44:47], v[160:163], v[184:187], v[44:47]
	v_mfma_f32_16x16x32_bf16 v[40:43], v[168:171], v[184:187], v[40:43]
	v_mfma_f32_16x16x32_bf16 v[28:31], v[160:163], v[192:195], v[28:31]
	v_mfma_f32_16x16x32_bf16 v[24:27], v[168:171], v[192:195], v[24:27]
	v_mfma_f32_16x16x32_bf16 v[12:15], v[160:163], v[200:203], v[12:15]
	v_mfma_f32_16x16x32_bf16 v[8:11], v[168:171], v[200:203], v[8:11]
	s_barrier
	s_add_u32 s56, s44, 0x80000
	s_addc_u32 s57, s45, 0
	s_add_i32 s55, s48, s10
	s_mov_b32 m0, s55
	s_nop 0
	global_load_lds_dwordx4 v132, s[56:57]
	s_add_i32 m0, s55, 0x2000
	s_nop 0
	global_load_lds_dwordx4 v128, s[56:57]
	s_waitcnt vmcnt(6)
	s_barrier
; #define PG8_STAGE(bufoff, gbase, voff) do { _Pragma("unroll") for (int _i = 0; _i < 2; ++_i) \
;         __builtin_amdgcn_global_load_lds((const unsigned*)((const char*)(gbase) + (voff)[_i]), (LAS unsigned*)(lds + (bufoff) + ldsw + _i * 8192), 16, 0, 0); } while (0)
; #define PG8_LDA(dst, b, h) do { _Pragma("unroll") for (int m = 0; m < 4; ++m) _Pragma("unroll") for (int k = 0; k < 2; ++k) dst[m][k] = *(const LAS bf16x8*)(lds + PG8_SA(b, h) + aoff + m * 2048 + k * 1024); } while (0)
; #define PG8_LDB(dst, b, h) do { _Pragma("unroll") for (int n = 0; n < 2; ++n) _Pragma("unroll") for (int k = 0; k < 2; ++k) dst[n][k] = *(const LAS bf16x8*)(lds + PG8_SB(b, h) + boff + n * 2048 + k * 1024); } while (0)
; #define PG8_MMA(ai, bj, At, Bt) do { __builtin_amdgcn_s_setprio(1); _Pragma("unroll") for (int m = 0; m < 4; ++m) _Pragma("unroll") for (int n = 0; n < 2; ++n) _Pragma("unroll") for (int k = 0; k < 2; ++k) \
;         acc[ai][bj][m][n] = __builtin_amdgcn_mfma_f32_16x16x32_bf16(Bt[n][k], At[m][k], acc[ai][bj][m][n], 0, 0, 0); __builtin_amdgcn_s_setprio(0); } while (0)
; #define PG8_WAIT_V(n) asm volatile("s_waitcnt vmcnt(" #n ")" ::: "memory")
; #define PG8_WAIT_L(n) asm volatile("s_waitcnt lgkmcnt(" #n ")" ::: "memory")
; #define PG8_BAR __builtin_amdgcn_s_barrier()
; #define PG8_SCHED __builtin_amdgcn_sched_barrier(0)
; template <class Epi>
; __device__ __forceinline__ void gemm_phase(LAS unsigned char* lds, const Gemm g, const StaticOrder& S, const Epi& E) {
;     ...
;             PG8_WAIT_V(6); PG8_BAR; PG8_MMA(1, 1, At, B1); PG8_BAR;
;             PG8_LDB(B0, 1, 0); PG8_SCHED; PG8_LDA(At, 1, 0); PG8_STAGE(PG8_SA(0, 1), a2 + hstep, voffA);
;             PG8_WAIT_L(8); PG8_BAR; PG8_WAIT_L(0); PG8_MMA(0, 0, At, B0); PG8_BAR; PG8_SCHED;
;             PG8_LDB(B1, 1, 1); PG8_STAGE(PG8_SB(1, 0), b3, voffB);
;             PG8_BAR; PG8_WAIT_L(0); PG8_MMA(0, 1, At, B1); PG8_BAR;
;             PG8_LDA(At, 1, 1); PG8_STAGE(PG8_SA(1, 0), a3, voffA);
;             PG8_BAR; PG8_WAIT_L(0); PG8_MMA(1, 0, At, B0); PG8_BAR; PG8_SCHED;
	v_mfma_f32_16x16x32_bf16 v[52:55], v[204:207], v[172:175], v[52:55]
	v_mfma_f32_16x16x32_bf16 v[48:51], v[212:215], v[172:175], v[48:51]
	v_mfma_f32_16x16x32_bf16 v[36:39], v[204:207], v[180:183], v[36:39]
	v_mfma_f32_16x16x32_bf16 v[32:35], v[212:215], v[180:183], v[32:35]
	v_mfma_f32_16x16x32_bf16 v[20:23], v[204:207], v[188:191], v[20:23]
	v_mfma_f32_16x16x32_bf16 v[16:19], v[212:215], v[188:191], v[16:19]
	v_mfma_f32_16x16x32_bf16 v[4:7], v[204:207], v[196:199], v[4:7]
	v_mfma_f32_16x16x32_bf16 v[0:3], v[212:215], v[196:199], v[0:3]
	v_mfma_f32_16x16x32_bf16 v[52:55], v[208:211], v[176:179], v[52:55]
	v_mfma_f32_16x16x32_bf16 v[48:51], v[216:219], v[176:179], v[48:51]
	v_mfma_f32_16x16x32_bf16 v[36:39], v[208:211], v[184:187], v[36:39]
	v_mfma_f32_16x16x32_bf16 v[32:35], v[216:219], v[184:187], v[32:35]
	v_mfma_f32_16x16x32_bf16 v[20:23], v[208:211], v[192:195], v[20:23]
	v_mfma_f32_16x16x32_bf16 v[16:19], v[216:219], v[192:195], v[16:19]
	v_mfma_f32_16x16x32_bf16 v[4:7], v[208:211], v[200:203], v[4:7]
	v_mfma_f32_16x16x32_bf16 v[0:3], v[216:219], v[200:203], v[0:3]
	s_add_i32 s55, 0, 0x18000
	v_add_u32_e32 v168, s55, v151
	s_barrier
	ds_read_b128 v[144:147], v168
	ds_read_b128 v[160:163], v168 offset:1024
	ds_read_b128 v[164:167], v168 offset:2048
	ds_read_b128 v[168:171], v168 offset:3072
	s_add_u32 s46, s46, 0x80000
	s_addc_u32 s47, s47, 0
	s_mov_b32 m0, s30
	ds_read_b128 v[172:175], v154 offset:32768
	ds_read_b128 v[176:179], v154 offset:33792
	ds_read_b128 v[180:183], v154 offset:34816
	ds_read_b128 v[184:187], v154 offset:35840
	ds_read_b128 v[188:191], v154 offset:36864
	ds_read_b128 v[192:195], v154 offset:37888
	ds_read_b128 v[196:199], v154 offset:38912
	global_load_lds_dwordx4 v134, s[46:47]
	s_mov_b32 m0, s31
	ds_read_b128 v[200:203], v154 offset:39936
	global_load_lds_dwordx4 v130, s[46:47]
	s_waitcnt lgkmcnt(8)
	s_barrier
	s_waitcnt lgkmcnt(0)
	v_mfma_f32_16x16x32_bf16 v[124:127], v[144:147], v[172:175], v[124:127]
	v_mfma_f32_16x16x32_bf16 v[120:123], v[164:167], v[172:175], v[120:123]
	v_mfma_f32_16x16x32_bf16 v[108:111], v[144:147], v[180:183], v[108:111]
	v_mfma_f32_16x16x32_bf16 v[104:107], v[164:167], v[180:183], v[104:107]
	v_mfma_f32_16x16x32_bf16 v[92:95], v[144:147], v[188:191], v[92:95]
	v_mfma_f32_16x16x32_bf16 v[88:91], v[164:167], v[188:191], v[88:91]
	v_mfma_f32_16x16x32_bf16 v[76:79], v[144:147], v[196:199], v[76:79]
	v_mfma_f32_16x16x32_bf16 v[72:75], v[164:167], v[196:199], v[72:75]
	v_mfma_f32_16x16x32_bf16 v[124:127], v[160:163], v[176:179], v[124:127]
	v_mfma_f32_16x16x32_bf16 v[120:123], v[168:171], v[176:179], v[120:123]
	v_mfma_f32_16x16x32_bf16 v[108:111], v[160:163], v[184:187], v[108:111]
	v_mfma_f32_16x16x32_bf16 v[104:107], v[168:171], v[184:187], v[104:107]
	v_mfma_f32_16x16x32_bf16 v[92:95], v[160:163], v[192:195], v[92:95]
	v_mfma_f32_16x16x32_bf16 v[88:91], v[168:171], v[192:195], v[88:91]
	v_mfma_f32_16x16x32_bf16 v[76:79], v[160:163], v[200:203], v[76:79]
	v_mfma_f32_16x16x32_bf16 v[72:75], v[168:171], v[200:203], v[72:75]
	s_barrier
	s_add_i32 s46, 0, 0x1c000
	s_add_i32 s47, s55, s10
	v_add_u32_e32 v216, s46, v151
	s_mov_b32 m0, s47
	ds_read_b128 v[204:207], v216
	ds_read_b128 v[208:211], v216 offset:1024
	ds_read_b128 v[212:215], v216 offset:2048
	global_load_lds_dwordx4 v132, s[98:99]
	s_add_i32 m0, s47, 0x2000
	ds_read_b128 v[216:219], v216 offset:3072
	global_load_lds_dwordx4 v128, s[98:99]
	s_barrier
	s_waitcnt lgkmcnt(0)
	v_mfma_f32_16x16x32_bf16 v[116:119], v[204:207], v[172:175], v[116:119]
	v_mfma_f32_16x16x32_bf16 v[112:115], v[212:215], v[172:175], v[112:115]
	v_mfma_f32_16x16x32_bf16 v[100:103], v[204:207], v[180:183], v[100:103]
	v_mfma_f32_16x16x32_bf16 v[96:99], v[212:215], v[180:183], v[96:99]
	v_mfma_f32_16x16x32_bf16 v[84:87], v[204:207], v[188:191], v[84:87]
	v_mfma_f32_16x16x32_bf16 v[80:83], v[212:215], v[188:191], v[80:83]
	v_mfma_f32_16x16x32_bf16 v[68:71], v[204:207], v[196:199], v[68:71]
	v_mfma_f32_16x16x32_bf16 v[64:67], v[212:215], v[196:199], v[64:67]
	v_mfma_f32_16x16x32_bf16 v[116:119], v[208:211], v[176:179], v[116:119]
	v_mfma_f32_16x16x32_bf16 v[112:115], v[216:219], v[176:179], v[112:115]
	v_mfma_f32_16x16x32_bf16 v[100:103], v[208:211], v[184:187], v[100:103]
	v_mfma_f32_16x16x32_bf16 v[96:99], v[216:219], v[184:187], v[96:99]
	v_mfma_f32_16x16x32_bf16 v[84:87], v[208:211], v[192:195], v[84:87]
	v_mfma_f32_16x16x32_bf16 v[80:83], v[216:219], v[192:195], v[80:83]
	v_mfma_f32_16x16x32_bf16 v[68:71], v[208:211], v[200:203], v[68:71]
	v_mfma_f32_16x16x32_bf16 v[64:67], v[216:219], v[200:203], v[64:67]
	s_mov_b32 m0, s36
	s_barrier
	ds_read_b128 v[172:175], v154 offset:49152
	ds_read_b128 v[176:179], v154 offset:50176
	ds_read_b128 v[180:183], v154 offset:51200
	ds_read_b128 v[184:187], v154 offset:52224
	ds_read_b128 v[188:191], v154 offset:53248
	ds_read_b128 v[192:195], v154 offset:54272
	ds_read_b128 v[196:199], v154 offset:55296
	global_load_lds_dwordx4 v134, s[100:101]
	s_mov_b32 m0, s37
	ds_read_b128 v[200:203], v154 offset:56320
	global_load_lds_dwordx4 v130, s[100:101]
	s_barrier
	s_waitcnt lgkmcnt(0)
	v_mfma_f32_16x16x32_bf16 v[60:63], v[144:147], v[172:175], v[60:63]
	v_mfma_f32_16x16x32_bf16 v[56:59], v[164:167], v[172:175], v[56:59]
	v_mfma_f32_16x16x32_bf16 v[44:47], v[144:147], v[180:183], v[44:47]
	v_mfma_f32_16x16x32_bf16 v[40:43], v[164:167], v[180:183], v[40:43]
	v_mfma_f32_16x16x32_bf16 v[28:31], v[144:147], v[188:191], v[28:31]
	v_mfma_f32_16x16x32_bf16 v[24:27], v[164:167], v[188:191], v[24:27]
	v_mfma_f32_16x16x32_bf16 v[12:15], v[144:147], v[196:199], v[12:15]
	v_mfma_f32_16x16x32_bf16 v[8:11], v[164:167], v[196:199], v[8:11]
	v_mfma_f32_16x16x32_bf16 v[60:63], v[160:163], v[176:179], v[60:63]
	v_mfma_f32_16x16x32_bf16 v[56:59], v[168:171], v[176:179], v[56:59]
	v_mfma_f32_16x16x32_bf16 v[44:47], v[160:163], v[184:187], v[44:47]
	v_mfma_f32_16x16x32_bf16 v[40:43], v[168:171], v[184:187], v[40:43]
	v_mfma_f32_16x16x32_bf16 v[28:31], v[160:163], v[192:195], v[28:31]
	v_mfma_f32_16x16x32_bf16 v[24:27], v[168:171], v[192:195], v[24:27]
	v_mfma_f32_16x16x32_bf16 v[12:15], v[160:163], v[200:203], v[12:15]
	v_mfma_f32_16x16x32_bf16 v[8:11], v[168:171], v[200:203], v[8:11]
	s_barrier
; __device__ __forceinline__ float fast_rcp(float x) { return __builtin_amdgcn_rcpf(x); }
; __device__ __forceinline__ float fast_exp2(float x) { return __builtin_amdgcn_exp2f(x); }
; #define PG8_STAGE(bufoff, gbase, voff) do { _Pragma("unroll") for (int _i = 0; _i < 2; ++_i) \
;         __builtin_amdgcn_global_load_lds((const unsigned*)((const char*)(gbase) + (voff)[_i]), (LAS unsigned*)(lds + (bufoff) + ldsw + _i * 8192), 16, 0, 0); } while (0)
; #define PG8_MMA(ai, bj, At, Bt) do { __builtin_amdgcn_s_setprio(1); _Pragma("unroll") for (int m = 0; m < 4; ++m) _Pragma("unroll") for (int n = 0; n < 2; ++n) _Pragma("unroll") for (int k = 0; k < 2; ++k) \
;         acc[ai][bj][m][n] = __builtin_amdgcn_mfma_f32_16x16x32_bf16(Bt[n][k], At[m][k], acc[ai][bj][m][n], 0, 0, 0); __builtin_amdgcn_s_setprio(0); } while (0)
; #define PG8_WAIT_V(n) asm volatile("s_waitcnt vmcnt(" #n ")" ::: "memory")
; #define PG8_BAR __builtin_amdgcn_s_barrier()
; __device__ __forceinline__ u32x4 pack8(f32x4 v0, f32x4 v1) { u32x4 w; w.x = cvt_pk_bf16(v0[0], v0[1]); w.y = cvt_pk_bf16(v0[2], v0[3]); w.z = cvt_pk_bf16(v1[0], v1[1]); w.w = cvt_pk_bf16(v1[2], v1[3]); return w; }
; template <class Epi>
; __device__ __forceinline__ void gemm_phase(LAS unsigned char* lds, const Gemm g, const StaticOrder& S, const Epi& E) {
;     ...
;             PG8_STAGE(PG8_SB(1, 1), b3 + hstep, voffB);
;             PG8_WAIT_V(6); PG8_BAR; PG8_MMA(1, 1, At, B1); PG8_BAR;
;     __device__ __forceinline__ void operator()(const f32x4 (&acc)[2][2][4][2], const Unit& u, int wr, int wc, int fr, int fq) const {
;         const int row0 = u.pm * BM + wr * 64 + fr, col0 = u.pn * HALF + wc * 32 + 8 * fq;
; #pragma unroll
;         for (int ai = 0; ai < 2; ++ai)
; #pragma unroll
;             for (int m = 0; m < 4; ++m) { bf16_t* rowp = O + (size_t)(row0 + ai * HALF + m * 16) * DFF + col0;
;                 const float r = rs[row0 + ai * HALF + m * 16], r2 = r * r;
;                 f32x4 h0, h1;
; #pragma unroll
;                 for (int j = 0; j < 4; ++j) {
;                     const float g0 = acc[ai][0][m][0][j], g1 = acc[ai][0][m][1][j];
;                     h0[j] = g0 * r2 * fast_rcp(1.0f + fast_exp2(g0 * (-LOG2E * r))) * acc[ai][1][m][0][j];
;                     h1[j] = g1 * r2 * fast_rcp(1.0f + fast_exp2(g1 * (-LOG2E * r))) * acc[ai][1][m][1][j]; }
;                 *(u32x4*)rowp = pack8(h0, h1); }
	s_add_u32 s44, s44, 0x80080
	s_addc_u32 s45, s45, 0
	s_add_i32 s46, s46, s10
	s_mov_b32 m0, s46
	s_nop 0
	global_load_lds_dwordx4 v132, s[44:45]
	s_add_i32 m0, s46, 0x2000
	s_nop 0
	global_load_lds_dwordx4 v128, s[44:45]
	s_waitcnt vmcnt(6)
	s_barrier
	v_mfma_f32_16x16x32_bf16 v[52:55], v[204:207], v[172:175], v[52:55]
	v_mfma_f32_16x16x32_bf16 v[48:51], v[212:215], v[172:175], v[48:51]
	v_mfma_f32_16x16x32_bf16 v[36:39], v[204:207], v[180:183], v[36:39]
	v_mfma_f32_16x16x32_bf16 v[32:35], v[212:215], v[180:183], v[32:35]
	v_mfma_f32_16x16x32_bf16 v[20:23], v[204:207], v[188:191], v[20:23]
	v_mfma_f32_16x16x32_bf16 v[16:19], v[212:215], v[188:191], v[16:19]
	v_mfma_f32_16x16x32_bf16 v[4:7], v[204:207], v[196:199], v[4:7]
	v_mfma_f32_16x16x32_bf16 v[0:3], v[212:215], v[196:199], v[0:3]
	v_mfma_f32_16x16x32_bf16 v[52:55], v[208:211], v[176:179], v[52:55]
	v_mfma_f32_16x16x32_bf16 v[48:51], v[216:219], v[176:179], v[48:51]
	v_mfma_f32_16x16x32_bf16 v[36:39], v[208:211], v[184:187], v[36:39]
	v_mfma_f32_16x16x32_bf16 v[32:35], v[216:219], v[184:187], v[32:35]
	v_mfma_f32_16x16x32_bf16 v[20:23], v[208:211], v[192:195], v[20:23]
	v_mfma_f32_16x16x32_bf16 v[16:19], v[216:219], v[192:195], v[16:19]
	v_mfma_f32_16x16x32_bf16 v[4:7], v[208:211], v[200:203], v[4:7]
	v_mfma_f32_16x16x32_bf16 v[0:3], v[216:219], v[200:203], v[0:3]
	s_add_i32 s54, s54, 2
	s_add_u32 s42, s42, 0x100
	s_addc_u32 s43, s43, 0
	s_add_u32 s52, s52, 0x100
	s_addc_u32 s53, s53, 0
	s_cmp_gt_u32 s54, 29
	s_barrier
	s_cbranch_scc0 .LBB0_203
	v_lshl_add_u32 v144, s40, 8, v150
	v_ashrrev_i32_e32 v145, 31, v144
	v_lshl_add_u64 v[148:149], v[144:145], 2, s[14:15]
	v_mov_b32_e32 v145, v224
	v_mov_b32_e32 v204, v225
	v_mov_b32_e32 v205, v226
	v_mov_b32_e32 v206, v227
	v_mov_b32_e32 v207, v228
	v_mov_b32_e32 v208, v229
	v_mov_b32_e32 v209, v230
	v_mov_b32_e32 v210, v231
	v_lshl_or_b32 v156, s34, 7, v152
	v_ashrrev_i32_e32 v157, 31, v156
	v_mov_b64_e32 v[146:147], s[20:21]
	v_mad_i64_i32 v[160:161], s[42:43], v144, s49, v[146:147]
	s_and_b64 vcc, exec, s[4:5]
	s_mov_b32 s34, s22
	s_mov_b32 s40, s24
	s_mov_b64 s[44:45], s[28:29]
	v_mul_f32_e32 v162, v145, v145
	v_mul_f32_e32 v145, 0xbfb8aa3b, v145
	v_mul_f32_e32 v163, v124, v162
	v_mul_f32_e32 v124, v124, v145
	v_exp_f32_e32 v124, v124
	s_nop 0
	v_add_f32_e32 v124, 1.0, v124
	v_rcp_f32_e32 v124, v124
	s_nop 0
	v_mul_f32_e32 v124, v163, v124
	v_mul_f32_e32 v116, v116, v124
	v_mul_f32_e32 v124, v120, v162
	v_mul_f32_e32 v120, v120, v145
	v_exp_f32_e32 v120, v120
	s_nop 0
	v_add_f32_e32 v120, 1.0, v120
	v_rcp_f32_e32 v120, v120
	s_nop 0
	v_mul_f32_e32 v120, v124, v120
	v_mul_f32_e32 v124, v125, v145
	v_exp_f32_e32 v124, v124
	v_mul_f32_e32 v120, v112, v120
	v_mul_f32_e32 v112, v125, v162
	v_add_f32_e32 v124, 1.0, v124
	v_rcp_f32_e32 v124, v124
	s_nop 0
	v_mul_f32_e32 v112, v112, v124
	v_mul_f32_e32 v117, v117, v112
	v_mul_f32_e32 v112, v121, v162
	v_mul_f32_e32 v121, v121, v145
	v_exp_f32_e32 v121, v121
	s_nop 0
	v_add_f32_e32 v121, 1.0, v121
	v_rcp_f32_e32 v121, v121
	s_nop 0
	v_mul_f32_e32 v112, v112, v121
	v_mul_f32_e32 v121, v113, v112
	v_mul_f32_e32 v113, v126, v145
	v_exp_f32_e32 v113, v113
	v_mul_f32_e32 v112, v126, v162
	v_add_f32_e32 v113, 1.0, v113
	v_rcp_f32_e32 v113, v113
	s_nop 0
	v_mul_f32_e32 v112, v112, v113
	v_mul_f32_e32 v113, v122, v145
	v_exp_f32_e32 v113, v113
	v_mul_f32_e32 v124, v118, v112
	v_mul_f32_e32 v112, v122, v162
	v_add_f32_e32 v113, 1.0, v113
	v_rcp_f32_e32 v113, v113
	s_nop 0
	v_mul_f32_e32 v112, v112, v113
	v_mul_f32_e32 v113, v127, v145
	v_exp_f32_e32 v113, v113
	v_mul_f32_e32 v122, v114, v112
	v_mul_f32_e32 v112, v127, v162
	v_cvt_pk_bf16_f32 v114, v116, v117
	v_add_f32_e32 v113, 1.0, v113
	v_rcp_f32_e32 v113, v113
	s_nop 0
	v_mul_f32_e32 v112, v112, v113
	v_mul_f32_e32 v113, v123, v145
	v_exp_f32_e32 v113, v113
	v_mul_f32_e32 v125, v119, v112
	v_mul_f32_e32 v112, v123, v162
	v_add_f32_e32 v113, 1.0, v113
	v_rcp_f32_e32 v113, v113
	s_nop 0
	v_mul_f32_e32 v112, v112, v113
	v_mul_f32_e32 v123, v115, v112
	v_lshlrev_b64 v[112:113], 1, v[156:157]
	v_lshl_add_u64 v[118:119], v[160:161], 0, v[112:113]
	v_cvt_pk_bf16_f32 v115, v124, v125
	v_cvt_pk_bf16_f32 v116, v120, v121
	v_cvt_pk_bf16_f32 v117, v122, v123
	global_store_dwordx4 v[118:119], v[114:117], off
	s_nop 1
	v_mov_b32_e32 v116, v204
	s_nop 0
	v_or_b32_e32 v114, 16, v144
	v_mad_i64_i32 v[114:115], s[42:43], v114, s49, v[146:147]
	v_mul_f32_e32 v117, v116, v116
	v_mul_f32_e32 v116, 0xbfb8aa3b, v116
	v_mul_f32_e32 v118, v108, v117
	v_mul_f32_e32 v108, v108, v116
	v_exp_f32_e32 v108, v108
	s_nop 0
	v_add_f32_e32 v108, 1.0, v108
	v_rcp_f32_e32 v108, v108
	s_nop 0
	v_mul_f32_e32 v108, v118, v108
	v_mul_f32_e32 v108, v100, v108
	v_mul_f32_e32 v100, v104, v117
	v_mul_f32_e32 v104, v104, v116
	v_exp_f32_e32 v104, v104
	s_nop 0
	v_add_f32_e32 v104, 1.0, v104
	v_rcp_f32_e32 v104, v104
	s_nop 0
	v_mul_f32_e32 v100, v100, v104
	v_mul_f32_e32 v104, v96, v100
	v_mul_f32_e32 v100, v109, v116
	v_exp_f32_e32 v100, v100
	v_mul_f32_e32 v96, v109, v117
	v_add_f32_e32 v100, 1.0, v100
	v_rcp_f32_e32 v100, v100
	s_nop 0
	v_mul_f32_e32 v96, v96, v100
	v_mul_f32_e32 v96, v101, v96
	v_mul_f32_e32 v101, v105, v116
	v_exp_f32_e32 v101, v101
	v_mul_f32_e32 v100, v105, v117
	v_cvt_pk_bf16_f32 v96, v108, v96
	v_add_f32_e32 v101, 1.0, v101
	v_rcp_f32_e32 v101, v101
	s_nop 0
	v_mul_f32_e32 v100, v100, v101
	v_mul_f32_e32 v105, v97, v100
	v_mul_f32_e32 v100, v110, v116
	v_exp_f32_e32 v100, v100
	v_mul_f32_e32 v101, v106, v116
	v_exp_f32_e32 v101, v101
	v_mul_f32_e32 v97, v110, v117
	v_add_f32_e32 v100, 1.0, v100
	v_rcp_f32_e32 v100, v100
	v_add_f32_e32 v101, 1.0, v101
	v_rcp_f32_e32 v101, v101
; __device__ __forceinline__ float fast_rcp(float x) { return __builtin_amdgcn_rcpf(x); }
; __device__ __forceinline__ float fast_exp2(float x) { return __builtin_amdgcn_exp2f(x); }
; __device__ __forceinline__ u32x4 pack8(f32x4 v0, f32x4 v1) { u32x4 w; w.x = cvt_pk_bf16(v0[0], v0[1]); w.y = cvt_pk_bf16(v0[2], v0[3]); w.z = cvt_pk_bf16(v1[0], v1[1]); w.w = cvt_pk_bf16(v1[2], v1[3]); return w; }
;     __device__ __forceinline__ void operator()(const f32x4 (&acc)[2][2][4][2], const Unit& u, int wr, int wc, int fr, int fq) const {
;         const int row0 = u.pm * BM + wr * 64 + fr, col0 = u.pn * HALF + wc * 32 + 8 * fq;
; #pragma unroll
;         for (int ai = 0; ai < 2; ++ai)
; #pragma unroll
;             for (int m = 0; m < 4; ++m) { bf16_t* rowp = O + (size_t)(row0 + ai * HALF + m * 16) * DFF + col0;
;                 const float r = rs[row0 + ai * HALF + m * 16], r2 = r * r;
;                 f32x4 h0, h1;
; #pragma unroll
;                 for (int j = 0; j < 4; ++j) {
;                     const float g0 = acc[ai][0][m][0][j], g1 = acc[ai][0][m][1][j];
;                     h0[j] = g0 * r2 * fast_rcp(1.0f + fast_exp2(g0 * (-LOG2E * r))) * acc[ai][1][m][0][j];
;                     h1[j] = g1 * r2 * fast_rcp(1.0f + fast_exp2(g1 * (-LOG2E * r))) * acc[ai][1][m][1][j]; }
;                 *(u32x4*)rowp = pack8(h0, h1); }
	v_mul_f32_e32 v97, v97, v100
	v_mul_f32_e32 v100, v106, v117
	v_mul_f32_e32 v100, v100, v101
	v_mul_f32_e32 v97, v102, v97
	v_mul_f32_e32 v102, v98, v100
	v_mul_f32_e32 v100, v111, v116
	v_exp_f32_e32 v100, v100
	v_mul_f32_e32 v101, v107, v116
	v_exp_f32_e32 v101, v101
	v_mul_f32_e32 v98, v111, v117
	v_add_f32_e32 v100, 1.0, v100
	v_rcp_f32_e32 v100, v100
	v_add_f32_e32 v101, 1.0, v101
	v_rcp_f32_e32 v101, v101
	v_mul_f32_e32 v98, v98, v100
	v_mul_f32_e32 v100, v107, v117
	v_mul_f32_e32 v100, v100, v101
	v_mul_f32_e32 v98, v103, v98
	v_mul_f32_e32 v99, v99, v100
	v_lshl_add_u64 v[100:101], v[114:115], 0, v[112:113]
	v_cvt_pk_bf16_f32 v97, v97, v98
	v_cvt_pk_bf16_f32 v98, v104, v105
	v_cvt_pk_bf16_f32 v99, v102, v99
	global_store_dwordx4 v[100:101], v[96:99], off
	s_nop 1
	v_mov_b32_e32 v98, v205
	s_nop 0
	v_or_b32_e32 v96, 32, v144
	v_mad_i64_i32 v[96:97], s[42:43], v96, s49, v[146:147]
	v_mul_f32_e32 v99, v98, v98
	v_mul_f32_e32 v98, 0xbfb8aa3b, v98
	v_mul_f32_e32 v100, v92, v99
	v_mul_f32_e32 v92, v92, v98
	v_exp_f32_e32 v92, v92
	s_nop 0
	v_add_f32_e32 v92, 1.0, v92
	v_rcp_f32_e32 v92, v92
	s_nop 0
	v_mul_f32_e32 v92, v100, v92
	v_mul_f32_e32 v92, v84, v92
	v_mul_f32_e32 v84, v88, v99
	v_mul_f32_e32 v88, v88, v98
	v_exp_f32_e32 v88, v88
	s_nop 0
	v_add_f32_e32 v88, 1.0, v88
	v_rcp_f32_e32 v88, v88
	s_nop 0
	v_mul_f32_e32 v84, v84, v88
	v_mul_f32_e32 v88, v80, v84
	v_mul_f32_e32 v84, v93, v98
	v_exp_f32_e32 v84, v84
	v_mul_f32_e32 v80, v93, v99
	v_add_f32_e32 v84, 1.0, v84
	v_rcp_f32_e32 v84, v84
	s_nop 0
	v_mul_f32_e32 v80, v80, v84
	v_mul_f32_e32 v80, v85, v80
	v_mul_f32_e32 v85, v89, v98
	v_exp_f32_e32 v85, v85
	v_mul_f32_e32 v84, v89, v99
	v_cvt_pk_bf16_f32 v80, v92, v80
	v_add_f32_e32 v85, 1.0, v85
	v_rcp_f32_e32 v85, v85
	s_nop 0
	v_mul_f32_e32 v84, v84, v85
	v_mul_f32_e32 v89, v81, v84
	v_mul_f32_e32 v84, v94, v98
	v_exp_f32_e32 v84, v84
	v_mul_f32_e32 v85, v90, v98
	v_exp_f32_e32 v85, v85
	v_mul_f32_e32 v81, v94, v99
	v_add_f32_e32 v84, 1.0, v84
	v_rcp_f32_e32 v84, v84
	v_add_f32_e32 v85, 1.0, v85
	v_rcp_f32_e32 v85, v85
	v_mul_f32_e32 v81, v81, v84
	v_mul_f32_e32 v84, v90, v99
	v_mul_f32_e32 v84, v84, v85
	v_mul_f32_e32 v81, v86, v81
	v_mul_f32_e32 v86, v82, v84
	v_mul_f32_e32 v84, v95, v98
	v_exp_f32_e32 v84, v84
	v_mul_f32_e32 v85, v91, v98
	v_exp_f32_e32 v85, v85
	v_mul_f32_e32 v82, v95, v99
	v_add_f32_e32 v84, 1.0, v84
	v_rcp_f32_e32 v84, v84
	v_add_f32_e32 v85, 1.0, v85
	v_rcp_f32_e32 v85, v85
	v_mul_f32_e32 v82, v82, v84
	v_mul_f32_e32 v84, v91, v99
	v_mul_f32_e32 v84, v84, v85
	v_mul_f32_e32 v82, v87, v82
	v_mul_f32_e32 v83, v83, v84
	v_lshl_add_u64 v[84:85], v[96:97], 0, v[112:113]
	v_cvt_pk_bf16_f32 v81, v81, v82
	v_cvt_pk_bf16_f32 v82, v88, v89
	v_cvt_pk_bf16_f32 v83, v86, v83
	global_store_dwordx4 v[84:85], v[80:83], off
	s_nop 1
	v_mov_b32_e32 v82, v206
	s_nop 0
	v_or_b32_e32 v80, 48, v144
	v_mad_i64_i32 v[80:81], s[42:43], v80, s49, v[146:147]
	v_mul_f32_e32 v83, v82, v82
	v_mul_f32_e32 v82, 0xbfb8aa3b, v82
	v_mul_f32_e32 v84, v76, v83
	v_mul_f32_e32 v76, v76, v82
	v_exp_f32_e32 v76, v76
	s_nop 0
	v_add_f32_e32 v76, 1.0, v76
	v_rcp_f32_e32 v76, v76
	s_nop 0
	v_mul_f32_e32 v76, v84, v76
	v_mul_f32_e32 v76, v68, v76
	v_mul_f32_e32 v68, v72, v83
	v_mul_f32_e32 v72, v72, v82
	v_exp_f32_e32 v72, v72
	s_nop 0
	v_add_f32_e32 v72, 1.0, v72
	v_rcp_f32_e32 v72, v72
	s_nop 0
	v_mul_f32_e32 v68, v68, v72
	v_mul_f32_e32 v72, v64, v68
	v_mul_f32_e32 v68, v77, v82
	v_exp_f32_e32 v68, v68
	v_mul_f32_e32 v64, v77, v83
	v_add_f32_e32 v68, 1.0, v68
	v_rcp_f32_e32 v68, v68
	s_nop 0
	v_mul_f32_e32 v64, v64, v68
	v_mul_f32_e32 v64, v69, v64
	v_mul_f32_e32 v69, v73, v82
	v_exp_f32_e32 v69, v69
	v_mul_f32_e32 v68, v73, v83
	v_cvt_pk_bf16_f32 v64, v76, v64
	v_add_f32_e32 v69, 1.0, v69
	v_rcp_f32_e32 v69, v69
	s_nop 0
	v_mul_f32_e32 v68, v68, v69
	v_mul_f32_e32 v73, v65, v68
	v_mul_f32_e32 v68, v78, v82
	v_exp_f32_e32 v68, v68
	v_mul_f32_e32 v69, v74, v82
	v_exp_f32_e32 v69, v69
	v_mul_f32_e32 v65, v78, v83
	v_add_f32_e32 v68, 1.0, v68
	v_rcp_f32_e32 v68, v68
	v_add_f32_e32 v69, 1.0, v69
	v_rcp_f32_e32 v69, v69
	v_mul_f32_e32 v65, v65, v68
	v_mul_f32_e32 v68, v74, v83
	v_mul_f32_e32 v68, v68, v69
	v_mul_f32_e32 v65, v70, v65
	v_mul_f32_e32 v70, v66, v68
	v_mul_f32_e32 v68, v79, v82
	v_exp_f32_e32 v68, v68
	v_mul_f32_e32 v69, v75, v82
	v_exp_f32_e32 v69, v69
	v_mul_f32_e32 v66, v79, v83
	v_add_f32_e32 v68, 1.0, v68
	v_rcp_f32_e32 v68, v68
	v_add_f32_e32 v69, 1.0, v69
	v_rcp_f32_e32 v69, v69
	v_mul_f32_e32 v66, v66, v68
	v_mul_f32_e32 v68, v75, v83
	v_mul_f32_e32 v68, v68, v69
	v_mul_f32_e32 v66, v71, v66
	v_mul_f32_e32 v67, v67, v68
	v_lshl_add_u64 v[68:69], v[80:81], 0, v[112:113]
	v_cvt_pk_bf16_f32 v65, v65, v66
	v_cvt_pk_bf16_f32 v66, v72, v73
	v_cvt_pk_bf16_f32 v67, v70, v67
	global_store_dwordx4 v[68:69], v[64:67], off
	s_nop 1
	v_mov_b32_e32 v66, v207
	s_nop 0
	v_add_u32_e32 v64, 0x80, v144
	v_mad_i64_i32 v[64:65], s[42:43], v64, s49, v[146:147]
	v_mul_f32_e32 v67, v66, v66
	v_mul_f32_e32 v66, 0xbfb8aa3b, v66
	v_mul_f32_e32 v68, v60, v67
	v_mul_f32_e32 v60, v60, v66
	v_exp_f32_e32 v60, v60
	s_nop 0
	v_add_f32_e32 v60, 1.0, v60
	v_rcp_f32_e32 v60, v60
	s_nop 0
	v_mul_f32_e32 v60, v68, v60
	v_mul_f32_e32 v60, v52, v60
	v_mul_f32_e32 v52, v56, v67
	v_mul_f32_e32 v56, v56, v66
	v_exp_f32_e32 v56, v56
	s_nop 0
	v_add_f32_e32 v56, 1.0, v56
	v_rcp_f32_e32 v56, v56
	s_nop 0
	v_mul_f32_e32 v52, v52, v56
	v_mul_f32_e32 v56, v48, v52
	v_mul_f32_e32 v52, v61, v66
	v_exp_f32_e32 v52, v52
	v_mul_f32_e32 v48, v61, v67
	v_add_f32_e32 v52, 1.0, v52
	v_rcp_f32_e32 v52, v52
	s_nop 0
	v_mul_f32_e32 v48, v48, v52
	v_mul_f32_e32 v48, v53, v48
; __device__ __forceinline__ float fast_rcp(float x) { return __builtin_amdgcn_rcpf(x); }
; __device__ __forceinline__ float fast_exp2(float x) { return __builtin_amdgcn_exp2f(x); }
; __device__ __forceinline__ u32x4 pack8(f32x4 v0, f32x4 v1) { u32x4 w; w.x = cvt_pk_bf16(v0[0], v0[1]); w.y = cvt_pk_bf16(v0[2], v0[3]); w.z = cvt_pk_bf16(v1[0], v1[1]); w.w = cvt_pk_bf16(v1[2], v1[3]); return w; }
;     __device__ __forceinline__ void operator()(const f32x4 (&acc)[2][2][4][2], const Unit& u, int wr, int wc, int fr, int fq) const {
;         const int row0 = u.pm * BM + wr * 64 + fr, col0 = u.pn * HALF + wc * 32 + 8 * fq;
; #pragma unroll
;         for (int ai = 0; ai < 2; ++ai)
; #pragma unroll
;             for (int m = 0; m < 4; ++m) { bf16_t* rowp = O + (size_t)(row0 + ai * HALF + m * 16) * DFF + col0;
;                 const float r = rs[row0 + ai * HALF + m * 16], r2 = r * r;
;                 f32x4 h0, h1;
; #pragma unroll
;                 for (int j = 0; j < 4; ++j) {
;                     const float g0 = acc[ai][0][m][0][j], g1 = acc[ai][0][m][1][j];
;                     h0[j] = g0 * r2 * fast_rcp(1.0f + fast_exp2(g0 * (-LOG2E * r))) * acc[ai][1][m][0][j];
;                     h1[j] = g1 * r2 * fast_rcp(1.0f + fast_exp2(g1 * (-LOG2E * r))) * acc[ai][1][m][1][j]; }
;                 *(u32x4*)rowp = pack8(h0, h1); }
	v_mul_f32_e32 v53, v57, v66
	v_exp_f32_e32 v53, v53
	v_mul_f32_e32 v52, v57, v67
	v_cvt_pk_bf16_f32 v48, v60, v48
	v_add_f32_e32 v53, 1.0, v53
	v_rcp_f32_e32 v53, v53
	s_nop 0
	v_mul_f32_e32 v52, v52, v53
	v_mul_f32_e32 v57, v49, v52
	v_mul_f32_e32 v52, v62, v66
	v_exp_f32_e32 v52, v52
	v_mul_f32_e32 v53, v58, v66
	v_exp_f32_e32 v53, v53
	v_mul_f32_e32 v49, v62, v67
	v_add_f32_e32 v52, 1.0, v52
	v_rcp_f32_e32 v52, v52
	v_add_f32_e32 v53, 1.0, v53
	v_rcp_f32_e32 v53, v53
	v_mul_f32_e32 v49, v49, v52
	v_mul_f32_e32 v52, v58, v67
	v_mul_f32_e32 v52, v52, v53
	v_mul_f32_e32 v49, v54, v49
	v_mul_f32_e32 v54, v50, v52
	v_mul_f32_e32 v52, v63, v66
	v_exp_f32_e32 v52, v52
	v_mul_f32_e32 v53, v59, v66
	v_exp_f32_e32 v53, v53
	v_mul_f32_e32 v50, v63, v67
	v_add_f32_e32 v52, 1.0, v52
	v_rcp_f32_e32 v52, v52
	v_add_f32_e32 v53, 1.0, v53
	v_rcp_f32_e32 v53, v53
	v_mul_f32_e32 v50, v50, v52
	v_mul_f32_e32 v52, v59, v67
	v_mul_f32_e32 v52, v52, v53
	v_mul_f32_e32 v50, v55, v50
	v_mul_f32_e32 v51, v51, v52
	v_lshl_add_u64 v[52:53], v[64:65], 0, v[112:113]
	v_cvt_pk_bf16_f32 v49, v49, v50
	v_cvt_pk_bf16_f32 v50, v56, v57
	v_cvt_pk_bf16_f32 v51, v54, v51
	global_store_dwordx4 v[52:53], v[48:51], off
	s_nop 1
	v_mov_b32_e32 v50, v208
	s_nop 0
	v_add_u32_e32 v48, 0x90, v144
	v_mad_i64_i32 v[48:49], s[42:43], v48, s49, v[146:147]
	v_mul_f32_e32 v51, v50, v50
	v_mul_f32_e32 v50, 0xbfb8aa3b, v50
	v_mul_f32_e32 v52, v44, v51
	v_mul_f32_e32 v44, v44, v50
	v_exp_f32_e32 v44, v44
	s_nop 0
	v_add_f32_e32 v44, 1.0, v44
	v_rcp_f32_e32 v44, v44
	s_nop 0
	v_mul_f32_e32 v44, v52, v44
	v_mul_f32_e32 v44, v36, v44
	v_mul_f32_e32 v36, v40, v51
	v_mul_f32_e32 v40, v40, v50
	v_exp_f32_e32 v40, v40
	s_nop 0
	v_add_f32_e32 v40, 1.0, v40
	v_rcp_f32_e32 v40, v40
	s_nop 0
	v_mul_f32_e32 v36, v36, v40
	v_mul_f32_e32 v40, v32, v36
	v_mul_f32_e32 v36, v45, v50
	v_exp_f32_e32 v36, v36
	v_mul_f32_e32 v32, v45, v51
	v_add_f32_e32 v36, 1.0, v36
	v_rcp_f32_e32 v36, v36
	s_nop 0
	v_mul_f32_e32 v32, v32, v36
	v_mul_f32_e32 v32, v37, v32
	v_mul_f32_e32 v37, v41, v50
	v_exp_f32_e32 v37, v37
	v_mul_f32_e32 v36, v41, v51
	v_cvt_pk_bf16_f32 v32, v44, v32
	v_add_f32_e32 v37, 1.0, v37
	v_rcp_f32_e32 v37, v37
	s_nop 0
	v_mul_f32_e32 v36, v36, v37
	v_mul_f32_e32 v41, v33, v36
	v_mul_f32_e32 v36, v46, v50
	v_exp_f32_e32 v36, v36
	v_mul_f32_e32 v37, v42, v50
	v_exp_f32_e32 v37, v37
	v_mul_f32_e32 v33, v46, v51
	v_add_f32_e32 v36, 1.0, v36
	v_rcp_f32_e32 v36, v36
	v_add_f32_e32 v37, 1.0, v37
	v_rcp_f32_e32 v37, v37
	v_mul_f32_e32 v33, v33, v36
	v_mul_f32_e32 v36, v42, v51
	v_mul_f32_e32 v36, v36, v37
	v_mul_f32_e32 v33, v38, v33
	v_mul_f32_e32 v38, v34, v36
	v_mul_f32_e32 v36, v47, v50
	v_exp_f32_e32 v36, v36
	v_mul_f32_e32 v37, v43, v50
	v_exp_f32_e32 v37, v37
	v_mul_f32_e32 v34, v47, v51
	v_add_f32_e32 v36, 1.0, v36
	v_rcp_f32_e32 v36, v36
	v_add_f32_e32 v37, 1.0, v37
	v_rcp_f32_e32 v37, v37
	v_mul_f32_e32 v34, v34, v36
	v_mul_f32_e32 v36, v43, v51
	v_mul_f32_e32 v36, v36, v37
	v_mul_f32_e32 v34, v39, v34
	v_mul_f32_e32 v35, v35, v36
	v_lshl_add_u64 v[36:37], v[48:49], 0, v[112:113]
	v_cvt_pk_bf16_f32 v33, v33, v34
	v_cvt_pk_bf16_f32 v34, v40, v41
	v_cvt_pk_bf16_f32 v35, v38, v35
	global_store_dwordx4 v[36:37], v[32:35], off
	s_nop 1
	v_mov_b32_e32 v34, v209
	s_nop 0
	v_add_u32_e32 v32, 0xa0, v144
	v_mad_i64_i32 v[32:33], s[42:43], v32, s49, v[146:147]
	v_mul_f32_e32 v35, v34, v34
	v_mul_f32_e32 v34, 0xbfb8aa3b, v34
	v_mul_f32_e32 v36, v28, v35
	v_mul_f32_e32 v28, v28, v34
	v_exp_f32_e32 v28, v28
	s_nop 0
	v_add_f32_e32 v28, 1.0, v28
	v_rcp_f32_e32 v28, v28
	s_nop 0
	v_mul_f32_e32 v28, v36, v28
	v_mul_f32_e32 v28, v20, v28
; __device__ __forceinline__ float fast_rcp(float x) { return __builtin_amdgcn_rcpf(x); }
; __device__ __forceinline__ float fast_exp2(float x) { return __builtin_amdgcn_exp2f(x); }
; #define PG8_WAIT_V(n) asm volatile("s_waitcnt vmcnt(" #n ")" ::: "memory")
; #define PG8_BAR __builtin_amdgcn_s_barrier()
; __device__ __forceinline__ u32x4 pack8(f32x4 v0, f32x4 v1) { u32x4 w; w.x = cvt_pk_bf16(v0[0], v0[1]); w.y = cvt_pk_bf16(v0[2], v0[3]); w.z = cvt_pk_bf16(v1[0], v1[1]); w.w = cvt_pk_bf16(v1[2], v1[3]); return w; }
; template <class Epi>
; __device__ __forceinline__ void gemm_phase(LAS unsigned char* lds, const Gemm g, const StaticOrder& S, const Epi& E) {
;     ...
;         if (!has_next) break;
; #pragma unroll
;         for (int a = 0; a < 2; ++a)
; #pragma unroll
;             for (int b = 0; b < 2; ++b)
; #pragma unroll
;                 for (int m = 0; m < 4; ++m)
; #pragma unroll
;                     for (int n = 0; n < 2; ++n) acc[a][b][m][n] = (f32x4){0.f, 0.f, 0.f, 0.f};
;         cur = nxt; cA = nA; cB = nB; ++ui;
;     }
;     PG8_WAIT_V(0);
;     if (wr == 0) PG8_BAR;
;     __device__ __forceinline__ void operator()(const f32x4 (&acc)[2][2][4][2], const Unit& u, int wr, int wc, int fr, int fq) const {
;         const int row0 = u.pm * BM + wr * 64 + fr, col0 = u.pn * HALF + wc * 32 + 8 * fq;
; #pragma unroll
;         for (int ai = 0; ai < 2; ++ai)
; #pragma unroll
;             for (int m = 0; m < 4; ++m) { bf16_t* rowp = O + (size_t)(row0 + ai * HALF + m * 16) * DFF + col0;
;                 const float r = rs[row0 + ai * HALF + m * 16], r2 = r * r;
;                 f32x4 h0, h1;
; #pragma unroll
;                 for (int j = 0; j < 4; ++j) {
;                     const float g0 = acc[ai][0][m][0][j], g1 = acc[ai][0][m][1][j];
;                     h0[j] = g0 * r2 * fast_rcp(1.0f + fast_exp2(g0 * (-LOG2E * r))) * acc[ai][1][m][0][j];
;                     h1[j] = g1 * r2 * fast_rcp(1.0f + fast_exp2(g1 * (-LOG2E * r))) * acc[ai][1][m][1][j]; }
;                 *(u32x4*)rowp = pack8(h0, h1); }
	v_mul_f32_e32 v20, v24, v35
	v_mul_f32_e32 v24, v24, v34
	v_exp_f32_e32 v24, v24
	s_nop 0
	v_add_f32_e32 v24, 1.0, v24
	v_rcp_f32_e32 v24, v24
	s_nop 0
	v_mul_f32_e32 v20, v20, v24
	v_mul_f32_e32 v24, v16, v20
	v_mul_f32_e32 v20, v29, v34
	v_exp_f32_e32 v20, v20
	v_mul_f32_e32 v16, v29, v35
	v_add_f32_e32 v20, 1.0, v20
	v_rcp_f32_e32 v20, v20
	s_nop 0
	v_mul_f32_e32 v16, v16, v20
	v_mul_f32_e32 v16, v21, v16
	v_mul_f32_e32 v21, v25, v34
	v_exp_f32_e32 v21, v21
	v_mul_f32_e32 v20, v25, v35
	v_cvt_pk_bf16_f32 v16, v28, v16
	v_add_f32_e32 v21, 1.0, v21
	v_rcp_f32_e32 v21, v21
	s_nop 0
	v_mul_f32_e32 v20, v20, v21
	v_mul_f32_e32 v25, v17, v20
	v_mul_f32_e32 v20, v30, v34
	v_exp_f32_e32 v20, v20
	v_mul_f32_e32 v21, v26, v34
	v_exp_f32_e32 v21, v21
	v_mul_f32_e32 v17, v30, v35
	v_add_f32_e32 v20, 1.0, v20
	v_rcp_f32_e32 v20, v20
	v_add_f32_e32 v21, 1.0, v21
	v_rcp_f32_e32 v21, v21
	v_mul_f32_e32 v17, v17, v20
	v_mul_f32_e32 v20, v26, v35
	v_mul_f32_e32 v20, v20, v21
	v_mul_f32_e32 v17, v22, v17
	v_mul_f32_e32 v22, v18, v20
	v_mul_f32_e32 v20, v31, v34
	v_exp_f32_e32 v20, v20
	v_mul_f32_e32 v21, v27, v34
	v_exp_f32_e32 v21, v21
	v_mul_f32_e32 v18, v31, v35
	v_add_f32_e32 v20, 1.0, v20
	v_rcp_f32_e32 v20, v20
	v_add_f32_e32 v21, 1.0, v21
	v_rcp_f32_e32 v21, v21
	v_mul_f32_e32 v18, v18, v20
	v_mul_f32_e32 v20, v27, v35
	v_mul_f32_e32 v20, v20, v21
	v_mul_f32_e32 v18, v23, v18
	v_mul_f32_e32 v19, v19, v20
	v_lshl_add_u64 v[20:21], v[32:33], 0, v[112:113]
	v_cvt_pk_bf16_f32 v17, v17, v18
	v_cvt_pk_bf16_f32 v18, v24, v25
	v_cvt_pk_bf16_f32 v19, v22, v19
	global_store_dwordx4 v[20:21], v[16:19], off
	s_nop 1
	v_mov_b32_e32 v18, v210
	s_nop 0
	v_add_u32_e32 v16, 0xb0, v144
	v_mad_i64_i32 v[16:17], s[42:43], v16, s49, v[146:147]
	s_mov_b64 s[42:43], s[26:27]
	v_mul_f32_e32 v19, v18, v18
	v_mul_f32_e32 v18, 0xbfb8aa3b, v18
	v_mul_f32_e32 v20, v12, v19
	v_mul_f32_e32 v12, v12, v18
	v_exp_f32_e32 v12, v12
	s_nop 0
	v_add_f32_e32 v12, 1.0, v12
	v_rcp_f32_e32 v12, v12
	s_nop 0
	v_mul_f32_e32 v12, v20, v12
	v_mul_f32_e32 v12, v4, v12
	v_mul_f32_e32 v4, v8, v19
	v_mul_f32_e32 v8, v8, v18
	v_exp_f32_e32 v8, v8
	s_nop 0
	v_add_f32_e32 v8, 1.0, v8
	v_rcp_f32_e32 v8, v8
	s_nop 0
	v_mul_f32_e32 v4, v4, v8
	v_mul_f32_e32 v8, v0, v4
	v_mul_f32_e32 v4, v13, v18
	v_exp_f32_e32 v4, v4
	v_mul_f32_e32 v0, v13, v19
	v_add_f32_e32 v4, 1.0, v4
	v_rcp_f32_e32 v4, v4
	s_nop 0
	v_mul_f32_e32 v0, v0, v4
	v_mul_f32_e32 v0, v5, v0
	v_mul_f32_e32 v5, v9, v18
	v_exp_f32_e32 v5, v5
	v_mul_f32_e32 v4, v9, v19
	v_cvt_pk_bf16_f32 v0, v12, v0
	v_add_f32_e32 v5, 1.0, v5
	v_rcp_f32_e32 v5, v5
	s_nop 0
	v_mul_f32_e32 v4, v4, v5
	v_mul_f32_e32 v9, v1, v4
	v_mul_f32_e32 v4, v14, v18
	v_exp_f32_e32 v4, v4
	v_mul_f32_e32 v5, v10, v18
	v_exp_f32_e32 v5, v5
	v_mul_f32_e32 v1, v14, v19
	v_add_f32_e32 v4, 1.0, v4
	v_rcp_f32_e32 v4, v4
	v_add_f32_e32 v5, 1.0, v5
	v_rcp_f32_e32 v5, v5
	v_mul_f32_e32 v1, v1, v4
	v_mul_f32_e32 v4, v10, v19
	v_mul_f32_e32 v4, v4, v5
	v_mul_f32_e32 v1, v6, v1
	v_mul_f32_e32 v6, v2, v4
	v_mul_f32_e32 v4, v15, v18
	v_exp_f32_e32 v4, v4
	v_mul_f32_e32 v5, v11, v18
	v_exp_f32_e32 v5, v5
	v_mul_f32_e32 v2, v15, v19
	v_add_f32_e32 v4, 1.0, v4
	v_rcp_f32_e32 v4, v4
	v_add_f32_e32 v5, 1.0, v5
	v_rcp_f32_e32 v5, v5
	v_mul_f32_e32 v2, v2, v4
	v_mul_f32_e32 v4, v11, v19
	v_mul_f32_e32 v4, v4, v5
	v_mul_f32_e32 v2, v7, v2
	v_mul_f32_e32 v3, v3, v4
	v_lshl_add_u64 v[4:5], v[16:17], 0, v[112:113]
	v_cvt_pk_bf16_f32 v1, v1, v2
	v_cvt_pk_bf16_f32 v2, v8, v9
	v_cvt_pk_bf16_f32 v3, v6, v3
	global_store_dwordx4 v[4:5], v[0:3], off
	s_cbranch_vccz .LBB0_200
	s_waitcnt vmcnt(0)
	s_cmpk_gt_u32 s3, 0xff
	s_cbranch_scc1 .LBB0_207
	s_barrier

; #define PG8_STAGE(bufoff, gbase, voff) do { _Pragma("unroll") for (int _i = 0; _i < 2; ++_i) \
;         __builtin_amdgcn_global_load_lds((const unsigned*)((const char*)(gbase) + (voff)[_i]), (LAS unsigned*)(lds + (bufoff) + ldsw + _i * 8192), 16, 0, 0); } while (0)
; #define PG8_LDA(dst, b, h) do { _Pragma("unroll") for (int m = 0; m < 4; ++m) _Pragma("unroll") for (int k = 0; k < 2; ++k) dst[m][k] = *(const LAS bf16x8*)(lds + PG8_SA(b, h) + aoff + m * 2048 + k * 1024); } while (0)
; #define PG8_LDB(dst, b, h) do { _Pragma("unroll") for (int n = 0; n < 2; ++n) _Pragma("unroll") for (int k = 0; k < 2; ++k) dst[n][k] = *(const LAS bf16x8*)(lds + PG8_SB(b, h) + boff + n * 2048 + k * 1024); } while (0)
; #define PG8_MMA(ai, bj, At, Bt) do { __builtin_amdgcn_s_setprio(1); _Pragma("unroll") for (int m = 0; m < 4; ++m) _Pragma("unroll") for (int n = 0; n < 2; ++n) _Pragma("unroll") for (int k = 0; k < 2; ++k) \
;         acc[ai][bj][m][n] = __builtin_amdgcn_mfma_f32_16x16x32_bf16(Bt[n][k], At[m][k], acc[ai][bj][m][n], 0, 0, 0); __builtin_amdgcn_s_setprio(0); } while (0)
; #define PG8_WAIT_V(n) asm volatile("s_waitcnt vmcnt(" #n ")" ::: "memory")
; #define PG8_WAIT_L(n) asm volatile("s_waitcnt lgkmcnt(" #n ")" ::: "memory")
; template <class Epi>
; __device__ __forceinline__ void gemm_phase(LAS unsigned char* lds, const Gemm g, const StaticOrder& S, const Epi& E) {
;     ...
;         for (int t = 0; t < nt; t += 2) {
;             const bool last = (t == nt - 2);
;             const char* a1 = cA + (size_t)(t + 1) * kstep;
;             const char* a2 = last ? nA : cA + (size_t)(t + 2) * kstep; const char* b2 = last ? nB : cB + (size_t)(t + 2) * kstep;
;             const char* a3 = a2 + kstep; const char* b3 = b2 + kstep;
;             PG8_LDB(B0, 0, 0); PG8_SCHED; PG8_LDA(At, 0, 0); PG8_STAGE(PG8_SA(1, 1), a1 + hstep, voffA);
;             PG8_WAIT_L(8); PG8_BAR; PG8_WAIT_L(0); PG8_MMA(0, 0, At, B0); PG8_BAR; PG8_SCHED;
;             PG8_LDB(B1, 0, 1); PG8_STAGE(PG8_SB(0, 0), b2, voffB);
;             PG8_BAR; PG8_WAIT_L(0); PG8_MMA(0, 1, At, B1); PG8_BAR;
;             PG8_LDA(At, 0, 1); PG8_STAGE(PG8_SA(0, 0), a2, voffA);
;             PG8_BAR; PG8_WAIT_L(0); PG8_MMA(1, 0, At, B0); PG8_BAR; PG8_SCHED;
;             PG8_STAGE(PG8_SB(0, 1), b2 + hstep, voffB);
;             PG8_WAIT_V(6); PG8_BAR; PG8_MMA(1, 1, At, B1); PG8_BAR;
.LBB0_283:
	ds_read_b128 v[148:151], v145
	ds_read_b128 v[152:155], v145 offset:1024
	ds_read_b128 v[160:163], v145 offset:2048
	ds_read_b128 v[164:167], v145 offset:3072
	s_add_u32 s50, s48, 0x100
	s_addc_u32 s51, s49, 0
	s_cmpk_eq_i32 s65, 0x54
	s_cselect_b32 s55, s47, s51
	s_cselect_b32 s54, s46, s50
	s_cselect_b32 s53, s5, s64
	s_cselect_b32 s52, s4, s63
	s_add_i32 m0, s23, 0xc000
	ds_read_b128 v[168:171], v146
	ds_read_b128 v[172:175], v146 offset:1024
	ds_read_b128 v[176:179], v146 offset:2048
	ds_read_b128 v[180:183], v146 offset:3072
	ds_read_b128 v[184:187], v146 offset:4096
	ds_read_b128 v[188:191], v146 offset:5120
	ds_read_b128 v[192:195], v146 offset:6144
	global_load_lds_dwordx4 v136, s[48:49]
	s_add_i32 m0, s23, 0xe000
	ds_read_b128 v[196:199], v146 offset:7168
	global_load_lds_dwordx4 v138, s[48:49]
	s_waitcnt lgkmcnt(8)
	s_barrier
	s_waitcnt lgkmcnt(0)
	v_mfma_f32_16x16x32_bf16 v[124:127], v[148:151], v[168:171], v[124:127]
	v_mfma_f32_16x16x32_bf16 v[120:123], v[160:163], v[168:171], v[120:123]
	v_mfma_f32_16x16x32_bf16 v[112:115], v[148:151], v[176:179], v[112:115]
	v_mfma_f32_16x16x32_bf16 v[104:107], v[160:163], v[176:179], v[104:107]
	v_mfma_f32_16x16x32_bf16 v[96:99], v[148:151], v[184:187], v[96:99]
	v_mfma_f32_16x16x32_bf16 v[88:91], v[160:163], v[184:187], v[88:91]
	v_mfma_f32_16x16x32_bf16 v[80:83], v[148:151], v[192:195], v[80:83]
	v_mfma_f32_16x16x32_bf16 v[72:75], v[160:163], v[192:195], v[72:75]
	v_mfma_f32_16x16x32_bf16 v[124:127], v[152:155], v[172:175], v[124:127]
	v_mfma_f32_16x16x32_bf16 v[120:123], v[164:167], v[172:175], v[120:123]
	v_mfma_f32_16x16x32_bf16 v[112:115], v[152:155], v[180:183], v[112:115]
	v_mfma_f32_16x16x32_bf16 v[104:107], v[164:167], v[180:183], v[104:107]
	v_mfma_f32_16x16x32_bf16 v[96:99], v[152:155], v[188:191], v[96:99]
	v_mfma_f32_16x16x32_bf16 v[88:91], v[164:167], v[188:191], v[88:91]
	v_mfma_f32_16x16x32_bf16 v[80:83], v[152:155], v[196:199], v[80:83]
	v_mfma_f32_16x16x32_bf16 v[72:75], v[164:167], v[196:199], v[72:75]
	s_barrier
	s_add_i32 s48, s39, s13
	s_add_u32 s98, s52, s6
	s_addc_u32 s99, s53, s7
	s_mov_b32 m0, s48
	ds_read_b128 v[200:203], v147
	ds_read_b128 v[204:207], v147 offset:1024
	ds_read_b128 v[208:211], v147 offset:2048
	global_load_lds_dwordx4 v132, s[52:53]
	s_add_i32 m0, s48, 0x2000
	ds_read_b128 v[212:215], v147 offset:3072
	global_load_lds_dwordx4 v128, s[52:53]
	s_barrier
	s_waitcnt lgkmcnt(0)
	v_mfma_f32_16x16x32_bf16 v[116:119], v[200:203], v[168:171], v[116:119]
	v_mfma_f32_16x16x32_bf16 v[108:111], v[208:211], v[168:171], v[108:111]
	v_mfma_f32_16x16x32_bf16 v[100:103], v[200:203], v[176:179], v[100:103]
	v_mfma_f32_16x16x32_bf16 v[92:95], v[208:211], v[176:179], v[92:95]
	v_mfma_f32_16x16x32_bf16 v[84:87], v[200:203], v[184:187], v[84:87]
	v_mfma_f32_16x16x32_bf16 v[76:79], v[208:211], v[184:187], v[76:79]
	v_mfma_f32_16x16x32_bf16 v[68:71], v[200:203], v[192:195], v[68:71]
	v_mfma_f32_16x16x32_bf16 v[64:67], v[208:211], v[192:195], v[64:67]
	v_mfma_f32_16x16x32_bf16 v[116:119], v[204:207], v[172:175], v[116:119]
	v_mfma_f32_16x16x32_bf16 v[108:111], v[212:215], v[172:175], v[108:111]
	v_mfma_f32_16x16x32_bf16 v[100:103], v[204:207], v[180:183], v[100:103]
	v_mfma_f32_16x16x32_bf16 v[92:95], v[212:215], v[180:183], v[92:95]
	v_mfma_f32_16x16x32_bf16 v[84:87], v[204:207], v[188:191], v[84:87]
	v_mfma_f32_16x16x32_bf16 v[76:79], v[212:215], v[188:191], v[76:79]
	v_mfma_f32_16x16x32_bf16 v[68:71], v[204:207], v[196:199], v[68:71]
	v_mfma_f32_16x16x32_bf16 v[64:67], v[212:215], v[196:199], v[64:67]
	s_mov_b32 m0, s23
	s_add_u32 s100, s54, s6
	s_addc_u32 s101, s55, s7
	s_barrier
	ds_read_b128 v[168:171], v146 offset:16384
	ds_read_b128 v[172:175], v146 offset:17408
	ds_read_b128 v[176:179], v146 offset:18432
	ds_read_b128 v[180:183], v146 offset:19456
	ds_read_b128 v[184:187], v146 offset:20480
	ds_read_b128 v[188:191], v146 offset:21504
	ds_read_b128 v[192:195], v146 offset:22528
	global_load_lds_dwordx4 v134, s[54:55]
	s_mov_b32 m0, s30
	ds_read_b128 v[196:199], v146 offset:23552
	global_load_lds_dwordx4 v130, s[54:55]
	s_barrier
	s_waitcnt lgkmcnt(0)
	v_mfma_f32_16x16x32_bf16 v[60:63], v[148:151], v[168:171], v[60:63]
	v_mfma_f32_16x16x32_bf16 v[56:59], v[160:163], v[168:171], v[56:59]
	v_mfma_f32_16x16x32_bf16 v[52:55], v[148:151], v[176:179], v[52:55]
	v_mfma_f32_16x16x32_bf16 v[44:47], v[160:163], v[176:179], v[44:47]
	v_mfma_f32_16x16x32_bf16 v[36:39], v[148:151], v[184:187], v[36:39]
	v_mfma_f32_16x16x32_bf16 v[28:31], v[160:163], v[184:187], v[28:31]
	v_mfma_f32_16x16x32_bf16 v[20:23], v[148:151], v[192:195], v[20:23]
	v_mfma_f32_16x16x32_bf16 v[12:15], v[160:163], v[192:195], v[12:15]
	v_mfma_f32_16x16x32_bf16 v[60:63], v[152:155], v[172:175], v[60:63]
	v_mfma_f32_16x16x32_bf16 v[56:59], v[164:167], v[172:175], v[56:59]
	v_mfma_f32_16x16x32_bf16 v[52:55], v[152:155], v[180:183], v[52:55]
	v_mfma_f32_16x16x32_bf16 v[44:47], v[164:167], v[180:183], v[44:47]
	v_mfma_f32_16x16x32_bf16 v[36:39], v[152:155], v[188:191], v[36:39]
	v_mfma_f32_16x16x32_bf16 v[28:31], v[164:167], v[188:191], v[28:31]
	v_mfma_f32_16x16x32_bf16 v[20:23], v[152:155], v[196:199], v[20:23]
	v_mfma_f32_16x16x32_bf16 v[12:15], v[164:167], v[196:199], v[12:15]
	s_barrier
	s_add_u32 s48, s52, 0x160000
	s_addc_u32 s49, s53, 0
	s_add_i32 s66, s40, s13
	s_mov_b32 m0, s66
	s_nop 0
	global_load_lds_dwordx4 v132, s[48:49]
	s_add_i32 m0, s66, 0x2000
	s_nop 0
	global_load_lds_dwordx4 v128, s[48:49]
	s_waitcnt vmcnt(6)
	s_barrier
; #define PG8_STAGE(bufoff, gbase, voff) do { _Pragma("unroll") for (int _i = 0; _i < 2; ++_i) \
;         __builtin_amdgcn_global_load_lds((const unsigned*)((const char*)(gbase) + (voff)[_i]), (LAS unsigned*)(lds + (bufoff) + ldsw + _i * 8192), 16, 0, 0); } while (0)
; #define PG8_LDA(dst, b, h) do { _Pragma("unroll") for (int m = 0; m < 4; ++m) _Pragma("unroll") for (int k = 0; k < 2; ++k) dst[m][k] = *(const LAS bf16x8*)(lds + PG8_SA(b, h) + aoff + m * 2048 + k * 1024); } while (0)
; #define PG8_LDB(dst, b, h) do { _Pragma("unroll") for (int n = 0; n < 2; ++n) _Pragma("unroll") for (int k = 0; k < 2; ++k) dst[n][k] = *(const LAS bf16x8*)(lds + PG8_SB(b, h) + boff + n * 2048 + k * 1024); } while (0)
; #define PG8_MMA(ai, bj, At, Bt) do { __builtin_amdgcn_s_setprio(1); _Pragma("unroll") for (int m = 0; m < 4; ++m) _Pragma("unroll") for (int n = 0; n < 2; ++n) _Pragma("unroll") for (int k = 0; k < 2; ++k) \
;         acc[ai][bj][m][n] = __builtin_amdgcn_mfma_f32_16x16x32_bf16(Bt[n][k], At[m][k], acc[ai][bj][m][n], 0, 0, 0); __builtin_amdgcn_s_setprio(0); } while (0)
; #define PG8_WAIT_V(n) asm volatile("s_waitcnt vmcnt(" #n ")" ::: "memory")
; #define PG8_WAIT_L(n) asm volatile("s_waitcnt lgkmcnt(" #n ")" ::: "memory")
; #define PG8_BAR __builtin_amdgcn_s_barrier()
; #define PG8_SCHED __builtin_amdgcn_sched_barrier(0)
; template <class Epi>
; __device__ __forceinline__ void gemm_phase(LAS unsigned char* lds, const Gemm g, const StaticOrder& S, const Epi& E) {
;     ...
;             PG8_WAIT_V(6); PG8_BAR; PG8_MMA(1, 1, At, B1); PG8_BAR;
;             PG8_LDB(B0, 1, 0); PG8_SCHED; PG8_LDA(At, 1, 0); PG8_STAGE(PG8_SA(0, 1), a2 + hstep, voffA);
;             PG8_WAIT_L(8); PG8_BAR; PG8_WAIT_L(0); PG8_MMA(0, 0, At, B0); PG8_BAR; PG8_SCHED;
;             PG8_LDB(B1, 1, 1); PG8_STAGE(PG8_SB(1, 0), b3, voffB);
;             PG8_BAR; PG8_WAIT_L(0); PG8_MMA(0, 1, At, B1); PG8_BAR;
;             PG8_LDA(At, 1, 1); PG8_STAGE(PG8_SA(1, 0), a3, voffA);
;             PG8_BAR; PG8_WAIT_L(0); PG8_MMA(1, 0, At, B0); PG8_BAR; PG8_SCHED;
	v_mfma_f32_16x16x32_bf16 v[48:51], v[200:203], v[168:171], v[48:51]
	v_mfma_f32_16x16x32_bf16 v[40:43], v[208:211], v[168:171], v[40:43]
	v_mfma_f32_16x16x32_bf16 v[32:35], v[200:203], v[176:179], v[32:35]
	v_mfma_f32_16x16x32_bf16 v[24:27], v[208:211], v[176:179], v[24:27]
	v_mfma_f32_16x16x32_bf16 v[16:19], v[200:203], v[184:187], v[16:19]
	v_mfma_f32_16x16x32_bf16 v[8:11], v[208:211], v[184:187], v[8:11]
	v_mfma_f32_16x16x32_bf16 v[4:7], v[200:203], v[192:195], v[4:7]
	v_mfma_f32_16x16x32_bf16 v[0:3], v[208:211], v[192:195], v[0:3]
	v_mfma_f32_16x16x32_bf16 v[48:51], v[204:207], v[172:175], v[48:51]
	v_mfma_f32_16x16x32_bf16 v[40:43], v[212:215], v[172:175], v[40:43]
	v_mfma_f32_16x16x32_bf16 v[32:35], v[204:207], v[180:183], v[32:35]
	v_mfma_f32_16x16x32_bf16 v[24:27], v[212:215], v[180:183], v[24:27]
	v_mfma_f32_16x16x32_bf16 v[16:19], v[204:207], v[188:191], v[16:19]
	v_mfma_f32_16x16x32_bf16 v[8:11], v[212:215], v[188:191], v[8:11]
	v_mfma_f32_16x16x32_bf16 v[4:7], v[204:207], v[196:199], v[4:7]
	v_mfma_f32_16x16x32_bf16 v[0:3], v[212:215], v[196:199], v[0:3]
	s_add_i32 s66, 0, 0x18000
	v_add_u32_e32 v164, s66, v143
	s_barrier
	ds_read_b128 v[148:151], v164
	ds_read_b128 v[152:155], v164 offset:1024
	ds_read_b128 v[160:163], v164 offset:2048
	ds_read_b128 v[164:167], v164 offset:3072
	s_add_u32 s48, s54, 0x160000
	s_addc_u32 s49, s55, 0
	s_mov_b32 m0, s31
	ds_read_b128 v[168:171], v146 offset:32768
	ds_read_b128 v[172:175], v146 offset:33792
	ds_read_b128 v[176:179], v146 offset:34816
	ds_read_b128 v[180:183], v146 offset:35840
	ds_read_b128 v[184:187], v146 offset:36864
	ds_read_b128 v[188:191], v146 offset:37888
	ds_read_b128 v[192:195], v146 offset:38912
	global_load_lds_dwordx4 v134, s[48:49]
	s_mov_b32 m0, s33
	ds_read_b128 v[196:199], v146 offset:39936
	global_load_lds_dwordx4 v130, s[48:49]
	s_waitcnt lgkmcnt(8)
	s_barrier
	s_waitcnt lgkmcnt(0)
	v_mfma_f32_16x16x32_bf16 v[124:127], v[148:151], v[168:171], v[124:127]
	v_mfma_f32_16x16x32_bf16 v[120:123], v[160:163], v[168:171], v[120:123]
	v_mfma_f32_16x16x32_bf16 v[112:115], v[148:151], v[176:179], v[112:115]
	v_mfma_f32_16x16x32_bf16 v[104:107], v[160:163], v[176:179], v[104:107]
	v_mfma_f32_16x16x32_bf16 v[96:99], v[148:151], v[184:187], v[96:99]
	v_mfma_f32_16x16x32_bf16 v[88:91], v[160:163], v[184:187], v[88:91]
	v_mfma_f32_16x16x32_bf16 v[80:83], v[148:151], v[192:195], v[80:83]
	v_mfma_f32_16x16x32_bf16 v[72:75], v[160:163], v[192:195], v[72:75]
	v_mfma_f32_16x16x32_bf16 v[124:127], v[152:155], v[172:175], v[124:127]
	v_mfma_f32_16x16x32_bf16 v[120:123], v[164:167], v[172:175], v[120:123]
	v_mfma_f32_16x16x32_bf16 v[112:115], v[152:155], v[180:183], v[112:115]
	v_mfma_f32_16x16x32_bf16 v[104:107], v[164:167], v[180:183], v[104:107]
	v_mfma_f32_16x16x32_bf16 v[96:99], v[152:155], v[188:191], v[96:99]
	v_mfma_f32_16x16x32_bf16 v[88:91], v[164:167], v[188:191], v[88:91]
	v_mfma_f32_16x16x32_bf16 v[80:83], v[152:155], v[196:199], v[80:83]
	v_mfma_f32_16x16x32_bf16 v[72:75], v[164:167], v[196:199], v[72:75]
	s_barrier
	s_add_i32 s54, 0, 0x1c000
	s_add_i32 s48, s66, s13
	v_add_u32_e32 v212, s54, v143
	s_mov_b32 m0, s48
	ds_read_b128 v[200:203], v212
	ds_read_b128 v[204:207], v212 offset:1024
	ds_read_b128 v[208:211], v212 offset:2048
	global_load_lds_dwordx4 v132, s[98:99]
	s_add_i32 m0, s48, 0x2000
	ds_read_b128 v[212:215], v212 offset:3072
	global_load_lds_dwordx4 v128, s[98:99]
	s_barrier
	s_waitcnt lgkmcnt(0)
	v_mfma_f32_16x16x32_bf16 v[116:119], v[200:203], v[168:171], v[116:119]
	v_mfma_f32_16x16x32_bf16 v[108:111], v[208:211], v[168:171], v[108:111]
	v_mfma_f32_16x16x32_bf16 v[100:103], v[200:203], v[176:179], v[100:103]
	v_mfma_f32_16x16x32_bf16 v[92:95], v[208:211], v[176:179], v[92:95]
	v_mfma_f32_16x16x32_bf16 v[84:87], v[200:203], v[184:187], v[84:87]
	v_mfma_f32_16x16x32_bf16 v[76:79], v[208:211], v[184:187], v[76:79]
	v_mfma_f32_16x16x32_bf16 v[68:71], v[200:203], v[192:195], v[68:71]
	v_mfma_f32_16x16x32_bf16 v[64:67], v[208:211], v[192:195], v[64:67]
	v_mfma_f32_16x16x32_bf16 v[116:119], v[204:207], v[172:175], v[116:119]
	v_mfma_f32_16x16x32_bf16 v[108:111], v[212:215], v[172:175], v[108:111]
	v_mfma_f32_16x16x32_bf16 v[100:103], v[204:207], v[180:183], v[100:103]
	v_mfma_f32_16x16x32_bf16 v[92:95], v[212:215], v[180:183], v[92:95]
	v_mfma_f32_16x16x32_bf16 v[84:87], v[204:207], v[188:191], v[84:87]
	v_mfma_f32_16x16x32_bf16 v[76:79], v[212:215], v[188:191], v[76:79]
	v_mfma_f32_16x16x32_bf16 v[68:71], v[204:207], v[196:199], v[68:71]
	v_mfma_f32_16x16x32_bf16 v[64:67], v[212:215], v[196:199], v[64:67]
	s_mov_b32 m0, s34
	s_barrier
	ds_read_b128 v[168:171], v146 offset:49152
	ds_read_b128 v[172:175], v146 offset:50176
	ds_read_b128 v[176:179], v146 offset:51200
	ds_read_b128 v[180:183], v146 offset:52224
	ds_read_b128 v[184:187], v146 offset:53248
	ds_read_b128 v[188:191], v146 offset:54272
	ds_read_b128 v[192:195], v146 offset:55296
	global_load_lds_dwordx4 v134, s[100:101]
	s_mov_b32 m0, s36
	ds_read_b128 v[196:199], v146 offset:56320
	global_load_lds_dwordx4 v130, s[100:101]
	s_barrier
	s_waitcnt lgkmcnt(0)
	v_mfma_f32_16x16x32_bf16 v[60:63], v[148:151], v[168:171], v[60:63]
	v_mfma_f32_16x16x32_bf16 v[56:59], v[160:163], v[168:171], v[56:59]
	v_mfma_f32_16x16x32_bf16 v[52:55], v[148:151], v[176:179], v[52:55]
	v_mfma_f32_16x16x32_bf16 v[44:47], v[160:163], v[176:179], v[44:47]
	v_mfma_f32_16x16x32_bf16 v[36:39], v[148:151], v[184:187], v[36:39]
	v_mfma_f32_16x16x32_bf16 v[28:31], v[160:163], v[184:187], v[28:31]
	v_mfma_f32_16x16x32_bf16 v[20:23], v[148:151], v[192:195], v[20:23]
	v_mfma_f32_16x16x32_bf16 v[12:15], v[160:163], v[192:195], v[12:15]
	v_mfma_f32_16x16x32_bf16 v[60:63], v[152:155], v[172:175], v[60:63]
	v_mfma_f32_16x16x32_bf16 v[56:59], v[164:167], v[172:175], v[56:59]
	v_mfma_f32_16x16x32_bf16 v[52:55], v[152:155], v[180:183], v[52:55]
	v_mfma_f32_16x16x32_bf16 v[44:47], v[164:167], v[180:183], v[44:47]
	v_mfma_f32_16x16x32_bf16 v[36:39], v[152:155], v[188:191], v[36:39]
	v_mfma_f32_16x16x32_bf16 v[28:31], v[164:167], v[188:191], v[28:31]
	v_mfma_f32_16x16x32_bf16 v[20:23], v[152:155], v[196:199], v[20:23]
	v_mfma_f32_16x16x32_bf16 v[12:15], v[164:167], v[196:199], v[12:15]
	s_barrier
; #define PG8_STAGE(bufoff, gbase, voff) do { _Pragma("unroll") for (int _i = 0; _i < 2; ++_i) \
;         __builtin_amdgcn_global_load_lds((const unsigned*)((const char*)(gbase) + (voff)[_i]), (LAS unsigned*)(lds + (bufoff) + ldsw + _i * 8192), 16, 0, 0); } while (0)
; #define PG8_MMA(ai, bj, At, Bt) do { __builtin_amdgcn_s_setprio(1); _Pragma("unroll") for (int m = 0; m < 4; ++m) _Pragma("unroll") for (int n = 0; n < 2; ++n) _Pragma("unroll") for (int k = 0; k < 2; ++k) \
;         acc[ai][bj][m][n] = __builtin_amdgcn_mfma_f32_16x16x32_bf16(Bt[n][k], At[m][k], acc[ai][bj][m][n], 0, 0, 0); __builtin_amdgcn_s_setprio(0); } while (0)
; #define PG8_WAIT_V(n) asm volatile("s_waitcnt vmcnt(" #n ")" ::: "memory")
; #define PG8_BAR __builtin_amdgcn_s_barrier()
; __device__ __forceinline__ u32x4 pack8(f32x4 v0, f32x4 v1) { u32x4 w; w.x = cvt_pk_bf16(v0[0], v0[1]); w.y = cvt_pk_bf16(v0[2], v0[3]); w.z = cvt_pk_bf16(v1[0], v1[1]); w.w = cvt_pk_bf16(v1[2], v1[3]); return w; }
; template <class Epi>
; __device__ __forceinline__ void gemm_phase(LAS unsigned char* lds, const Gemm g, const StaticOrder& S, const Epi& E) {
;     ...
;             PG8_STAGE(PG8_SB(1, 1), b3 + hstep, voffB);
;             PG8_WAIT_V(6); PG8_BAR; PG8_MMA(1, 1, At, B1); PG8_BAR;
;         }
;         E(acc, cur, wr, wc, fr, fq);
;     __device__ __forceinline__ void operator()(const f32x4 (&acc)[2][2][4][2], const Unit& u, int wr, int wc, int fr, int fq) const {
;         const int row0 = u.pm * BM + wr * 64 + fr, col0 = u.pn * BM + wc * 32 + 8 * fq;
; #pragma unroll
;         for (int ai = 0; ai < 2; ++ai)
; #pragma unroll
;             for (int m = 0; m < 4; ++m) { bf16_t* rowp = O + (size_t)(row0 + ai * HALF + m * 16) * ldc + col0;
; #pragma unroll
;                 for (int bj = 0; bj < 2; ++bj) *(u32x4*)(rowp + bj * HALF) = pack8(acc[ai][bj][m][0], acc[ai][bj][m][1]); }
;     }
	s_add_u32 s48, s52, 0x160080
	s_addc_u32 s49, s53, 0
	s_add_i32 s52, s54, s13
	s_mov_b32 m0, s52
	s_nop 0
	global_load_lds_dwordx4 v132, s[48:49]
	s_add_i32 m0, s52, 0x2000
	s_nop 0
	global_load_lds_dwordx4 v128, s[48:49]
	s_waitcnt vmcnt(6)
	s_barrier
	v_mfma_f32_16x16x32_bf16 v[48:51], v[200:203], v[168:171], v[48:51]
	v_mfma_f32_16x16x32_bf16 v[40:43], v[208:211], v[168:171], v[40:43]
	v_mfma_f32_16x16x32_bf16 v[32:35], v[200:203], v[176:179], v[32:35]
	v_mfma_f32_16x16x32_bf16 v[24:27], v[208:211], v[176:179], v[24:27]
	v_mfma_f32_16x16x32_bf16 v[16:19], v[200:203], v[184:187], v[16:19]
	v_mfma_f32_16x16x32_bf16 v[8:11], v[208:211], v[184:187], v[8:11]
	v_mfma_f32_16x16x32_bf16 v[4:7], v[200:203], v[192:195], v[4:7]
	v_mfma_f32_16x16x32_bf16 v[0:3], v[208:211], v[192:195], v[0:3]
	v_mfma_f32_16x16x32_bf16 v[48:51], v[204:207], v[172:175], v[48:51]
	v_mfma_f32_16x16x32_bf16 v[40:43], v[212:215], v[172:175], v[40:43]
	v_mfma_f32_16x16x32_bf16 v[32:35], v[204:207], v[180:183], v[32:35]
	v_mfma_f32_16x16x32_bf16 v[24:27], v[212:215], v[180:183], v[24:27]
	v_mfma_f32_16x16x32_bf16 v[16:19], v[204:207], v[188:191], v[16:19]
	v_mfma_f32_16x16x32_bf16 v[8:11], v[212:215], v[188:191], v[8:11]
	v_mfma_f32_16x16x32_bf16 v[4:7], v[204:207], v[196:199], v[4:7]
	v_mfma_f32_16x16x32_bf16 v[0:3], v[212:215], v[196:199], v[0:3]
	s_add_i32 s65, s65, 2
	s_add_u32 s63, s63, 0x100
	s_addc_u32 s64, s64, 0
	s_cmpk_gt_u32 s65, 0x55
	s_mov_b64 s[48:49], s[50:51]
	s_barrier
	s_cbranch_scc0 .LBB0_283
	v_lshl_add_u32 v148, s61, 8, v142
	v_lshl_or_b32 v140, s62, 8, v144
	v_ashrrev_i32_e32 v149, 31, v148
	v_ashrrev_i32_e32 v141, 31, v140
	v_lshlrev_b64 v[150:151], 12, v[148:149]
	v_lshl_add_u64 v[150:151], s[24:25], 0, v[150:151]
	v_lshlrev_b64 v[152:153], 1, v[140:141]
	v_lshl_add_u64 v[140:141], v[150:151], 0, v[152:153]
	v_cvt_pk_bf16_f32 v124, v124, v125
	v_cvt_pk_bf16_f32 v125, v126, v127
	v_cvt_pk_bf16_f32 v126, v120, v121
	v_cvt_pk_bf16_f32 v127, v122, v123
	global_store_dwordx4 v[140:141], v[124:127], off
	v_cvt_pk_bf16_f32 v116, v116, v117
	v_cvt_pk_bf16_f32 v117, v118, v119
	v_cvt_pk_bf16_f32 v118, v108, v109
	v_or_b32_e32 v108, 16, v148
	v_ashrrev_i32_e32 v109, 31, v108
	v_lshlrev_b64 v[108:109], 12, v[108:109]
	v_lshl_add_u64 v[108:109], s[24:25], 0, v[108:109]
	v_cvt_pk_bf16_f32 v119, v110, v111
	global_store_dwordx4 v[140:141], v[116:119], off offset:256
	s_mov_b32 s62, s59
	s_mov_b32 s61, s60
	v_lshl_add_u64 v[116:117], v[108:109], 0, v[152:153]
	v_cvt_pk_bf16_f32 v108, v112, v113
	v_cvt_pk_bf16_f32 v109, v114, v115
	v_cvt_pk_bf16_f32 v110, v104, v105
	v_cvt_pk_bf16_f32 v111, v106, v107
	global_store_dwordx4 v[116:117], v[108:111], off
	v_cvt_pk_bf16_f32 v100, v100, v101
	v_cvt_pk_bf16_f32 v101, v102, v103
	v_cvt_pk_bf16_f32 v102, v92, v93
	v_or_b32_e32 v92, 32, v148
	v_ashrrev_i32_e32 v93, 31, v92
	v_lshlrev_b64 v[92:93], 12, v[92:93]
	v_lshl_add_u64 v[92:93], s[24:25], 0, v[92:93]
	v_cvt_pk_bf16_f32 v103, v94, v95
	global_store_dwordx4 v[116:117], v[100:103], off offset:256
	s_mov_b64 s[50:51], s[4:5]
	s_mov_b64 s[48:49], s[46:47]
	v_lshl_add_u64 v[100:101], v[92:93], 0, v[152:153]
	v_cvt_pk_bf16_f32 v92, v96, v97
	v_cvt_pk_bf16_f32 v93, v98, v99
	v_cvt_pk_bf16_f32 v94, v88, v89
	v_cvt_pk_bf16_f32 v95, v90, v91
	global_store_dwordx4 v[100:101], v[92:95], off
	v_cvt_pk_bf16_f32 v84, v84, v85
	v_cvt_pk_bf16_f32 v85, v86, v87
	v_cvt_pk_bf16_f32 v86, v76, v77
	v_or_b32_e32 v76, 48, v148
	v_ashrrev_i32_e32 v77, 31, v76
	v_lshlrev_b64 v[76:77], 12, v[76:77]
	v_lshl_add_u64 v[76:77], s[24:25], 0, v[76:77]
	v_cvt_pk_bf16_f32 v87, v78, v79
	global_store_dwordx4 v[100:101], v[84:87], off offset:256
	s_nop 1
	v_lshl_add_u64 v[84:85], v[76:77], 0, v[152:153]
	v_cvt_pk_bf16_f32 v76, v80, v81
	v_cvt_pk_bf16_f32 v77, v82, v83
	v_cvt_pk_bf16_f32 v78, v72, v73
	v_cvt_pk_bf16_f32 v79, v74, v75
	global_store_dwordx4 v[84:85], v[76:79], off
	v_cvt_pk_bf16_f32 v68, v68, v69
	v_cvt_pk_bf16_f32 v69, v70, v71
	v_cvt_pk_bf16_f32 v70, v64, v65
	v_cvt_pk_bf16_f32 v71, v66, v67
	global_store_dwordx4 v[84:85], v[68:71], off offset:256
	v_cvt_pk_bf16_f32 v60, v60, v61
	v_cvt_pk_bf16_f32 v61, v62, v63
	v_cvt_pk_bf16_f32 v62, v56, v57
	v_add_co_u32_e32 v56, vcc, s41, v140
	v_lshl_add_u64 v[64:65], v[140:141], 0, s[8:9]
	s_nop 0
	v_addc_co_u32_e32 v57, vcc, 0, v141, vcc
	v_cvt_pk_bf16_f32 v63, v58, v59
	global_store_dwordx4 v[56:57], v[60:63], off
	v_cvt_pk_bf16_f32 v48, v48, v49
	v_cvt_pk_bf16_f32 v49, v50, v51
	v_cvt_pk_bf16_f32 v50, v40, v41
	v_cvt_pk_bf16_f32 v51, v42, v43
	global_store_dwordx4 v[64:65], v[48:51], off offset:256
	v_cvt_pk_bf16_f32 v40, v52, v53
	v_cvt_pk_bf16_f32 v41, v54, v55
	v_cvt_pk_bf16_f32 v42, v44, v45
	v_add_co_u32_e32 v44, vcc, s56, v140
	s_nop 0
	v_lshl_add_u64 v[48:49], v[140:141], 0, s[26:27]
	v_addc_co_u32_e32 v45, vcc, 0, v141, vcc
	v_cvt_pk_bf16_f32 v43, v46, v47
	global_store_dwordx4 v[44:45], v[40:43], off
	v_cvt_pk_bf16_f32 v32, v32, v33
	v_cvt_pk_bf16_f32 v33, v34, v35
	v_cvt_pk_bf16_f32 v34, v24, v25
	v_cvt_pk_bf16_f32 v35, v26, v27
	global_store_dwordx4 v[48:49], v[32:35], off offset:256
	v_cvt_pk_bf16_f32 v24, v36, v37
	v_cvt_pk_bf16_f32 v25, v38, v39
	v_cvt_pk_bf16_f32 v26, v28, v29
	v_add_co_u32_e32 v28, vcc, s57, v140
	s_nop 0
	v_lshl_add_u64 v[32:33], v[140:141], 0, s[28:29]
	v_addc_co_u32_e32 v29, vcc, 0, v141, vcc
	v_cvt_pk_bf16_f32 v27, v30, v31
	global_store_dwordx4 v[28:29], v[24:27], off
	v_cvt_pk_bf16_f32 v16, v16, v17
	v_cvt_pk_bf16_f32 v17, v18, v19
	v_cvt_pk_bf16_f32 v18, v8, v9
	v_cvt_pk_bf16_f32 v19, v10, v11
	global_store_dwordx4 v[32:33], v[16:19], off offset:256
	v_cvt_pk_bf16_f32 v8, v20, v21
	v_cvt_pk_bf16_f32 v9, v22, v23
	v_cvt_pk_bf16_f32 v10, v12, v13
	v_add_co_u32_e32 v12, vcc, s58, v140
	s_nop 0
	v_lshl_add_u64 v[16:17], v[140:141], 0, s[42:43]
	v_addc_co_u32_e32 v13, vcc, 0, v141, vcc
	s_and_b64 vcc, exec, s[44:45]
	v_cvt_pk_bf16_f32 v11, v14, v15
	global_store_dwordx4 v[12:13], v[8:11], off
	v_cvt_pk_bf16_f32 v4, v4, v5
	v_cvt_pk_bf16_f32 v5, v6, v7
	v_cvt_pk_bf16_f32 v6, v0, v1
	v_cvt_pk_bf16_f32 v7, v2, v3
	global_store_dwordx4 v[16:17], v[4:7], off offset:256
	s_cbranch_vccz .LBB0_276
	s_waitcnt vmcnt(0)
	s_cmpk_gt_u32 s3, 0xff
	v_readlane_b32 s62, v232, 20
	s_cbranch_scc1 .LBB0_287
	s_barrier

; #define PG8_STAGE(bufoff, gbase, voff) do { _Pragma("unroll") for (int _i = 0; _i < 2; ++_i) \
;         __builtin_amdgcn_global_load_lds((const unsigned*)((const char*)(gbase) + (voff)[_i]), (LAS unsigned*)(lds + (bufoff) + ldsw + _i * 8192), 16, 0, 0); } while (0)
; #define PG8_LDA(dst, b, h) do { _Pragma("unroll") for (int m = 0; m < 4; ++m) _Pragma("unroll") for (int k = 0; k < 2; ++k) dst[m][k] = *(const LAS bf16x8*)(lds + PG8_SA(b, h) + aoff + m * 2048 + k * 1024); } while (0)
; #define PG8_LDB(dst, b, h) do { _Pragma("unroll") for (int n = 0; n < 2; ++n) _Pragma("unroll") for (int k = 0; k < 2; ++k) dst[n][k] = *(const LAS bf16x8*)(lds + PG8_SB(b, h) + boff + n * 2048 + k * 1024); } while (0)
; #define PG8_MMA(ai, bj, At, Bt) do { __builtin_amdgcn_s_setprio(1); _Pragma("unroll") for (int m = 0; m < 4; ++m) _Pragma("unroll") for (int n = 0; n < 2; ++n) _Pragma("unroll") for (int k = 0; k < 2; ++k) \
;         acc[ai][bj][m][n] = __builtin_amdgcn_mfma_f32_16x16x32_bf16(Bt[n][k], At[m][k], acc[ai][bj][m][n], 0, 0, 0); __builtin_amdgcn_s_setprio(0); } while (0)
; #define PG8_WAIT_V(n) asm volatile("s_waitcnt vmcnt(" #n ")" ::: "memory")
; #define PG8_WAIT_L(n) asm volatile("s_waitcnt lgkmcnt(" #n ")" ::: "memory")
; template <class Epi>
; __device__ __forceinline__ void gemm_phase(LAS unsigned char* lds, const Gemm g, const StaticOrder& S, const Epi& E) {
;     ...
;         for (int t = 0; t < nt; t += 2) {
;             const bool last = (t == nt - 2);
;             const char* a1 = cA + (size_t)(t + 1) * kstep;
;             const char* a2 = last ? nA : cA + (size_t)(t + 2) * kstep; const char* b2 = last ? nB : cB + (size_t)(t + 2) * kstep;
;             const char* a3 = a2 + kstep; const char* b3 = b2 + kstep;
;             PG8_LDB(B0, 0, 0); PG8_SCHED; PG8_LDA(At, 0, 0); PG8_STAGE(PG8_SA(1, 1), a1 + hstep, voffA);
;             PG8_WAIT_L(8); PG8_BAR; PG8_WAIT_L(0); PG8_MMA(0, 0, At, B0); PG8_BAR; PG8_SCHED;
;             PG8_LDB(B1, 0, 1); PG8_STAGE(PG8_SB(0, 0), b2, voffB);
;             PG8_BAR; PG8_WAIT_L(0); PG8_MMA(0, 1, At, B1); PG8_BAR;
;             PG8_LDA(At, 0, 1); PG8_STAGE(PG8_SA(0, 0), a2, voffA);
;             PG8_BAR; PG8_WAIT_L(0); PG8_MMA(1, 0, At, B0); PG8_BAR; PG8_SCHED;
;             PG8_STAGE(PG8_SB(0, 1), b2 + hstep, voffB);
;             PG8_WAIT_V(6); PG8_BAR; PG8_MMA(1, 1, At, B1); PG8_BAR;
.LBB0_407:
	ds_read_b128 v[150:153], v164
	ds_read_b128 v[154:157], v164 offset:1024
	ds_read_b128 v[168:171], v164 offset:2048
	ds_read_b128 v[172:175], v164 offset:3072
	s_add_u32 s48, s46, 0xfff80080
	s_addc_u32 s49, s47, -1
	s_cmp_eq_u32 s57, 28
	s_cselect_b32 s51, s9, s49
	s_cselect_b32 s50, s45, s48
	s_cselect_b32 s49, s7, s56
	s_cselect_b32 s48, s54, s55
	s_add_i32 m0, s27, 0xc000
	ds_read_b128 v[176:179], v165
	ds_read_b128 v[180:183], v165 offset:1024
	ds_read_b128 v[184:187], v165 offset:2048
	ds_read_b128 v[188:191], v165 offset:3072
	ds_read_b128 v[192:195], v165 offset:4096
	ds_read_b128 v[196:199], v165 offset:5120
	ds_read_b128 v[200:203], v165 offset:6144
	global_load_lds_dwordx4 v142, s[46:47]
	s_add_i32 m0, s27, 0xe000
	ds_read_b128 v[204:207], v165 offset:7168
	global_load_lds_dwordx4 v144, s[46:47]
	s_waitcnt lgkmcnt(8)
	s_barrier
	s_waitcnt lgkmcnt(0)
	v_mfma_f32_16x16x32_bf16 v[124:127], v[150:153], v[176:179], v[124:127]
	v_mfma_f32_16x16x32_bf16 v[120:123], v[168:171], v[176:179], v[120:123]
	v_mfma_f32_16x16x32_bf16 v[108:111], v[150:153], v[184:187], v[108:111]
	v_mfma_f32_16x16x32_bf16 v[104:107], v[168:171], v[184:187], v[104:107]
	v_mfma_f32_16x16x32_bf16 v[92:95], v[150:153], v[192:195], v[92:95]
	v_mfma_f32_16x16x32_bf16 v[88:91], v[168:171], v[192:195], v[88:91]
	v_mfma_f32_16x16x32_bf16 v[76:79], v[150:153], v[200:203], v[76:79]
	v_mfma_f32_16x16x32_bf16 v[72:75], v[168:171], v[200:203], v[72:75]
	v_mfma_f32_16x16x32_bf16 v[124:127], v[154:157], v[180:183], v[124:127]
	v_mfma_f32_16x16x32_bf16 v[120:123], v[172:175], v[180:183], v[120:123]
	v_mfma_f32_16x16x32_bf16 v[108:111], v[154:157], v[188:191], v[108:111]
	v_mfma_f32_16x16x32_bf16 v[104:107], v[172:175], v[188:191], v[104:107]
	v_mfma_f32_16x16x32_bf16 v[92:95], v[154:157], v[196:199], v[92:95]
	v_mfma_f32_16x16x32_bf16 v[88:91], v[172:175], v[196:199], v[88:91]
	v_mfma_f32_16x16x32_bf16 v[76:79], v[154:157], v[204:207], v[76:79]
	v_mfma_f32_16x16x32_bf16 v[72:75], v[172:175], v[204:207], v[72:75]
	s_barrier
	s_add_i32 s58, s41, s23
	s_add_u32 s98, s48, s2
	s_addc_u32 s99, s49, s3
	s_mov_b32 m0, s58
	ds_read_b128 v[208:211], v166
	ds_read_b128 v[212:215], v166 offset:1024
	ds_read_b128 v[216:219], v166 offset:2048
	global_load_lds_dwordx4 v132, s[48:49]
	s_add_i32 m0, s58, 0x2000
	ds_read_b128 v[220:223], v166 offset:3072
	global_load_lds_dwordx4 v128, s[48:49]
	s_barrier
	s_waitcnt lgkmcnt(0)
	v_mfma_f32_16x16x32_bf16 v[116:119], v[208:211], v[176:179], v[116:119]
	v_mfma_f32_16x16x32_bf16 v[112:115], v[216:219], v[176:179], v[112:115]
	v_mfma_f32_16x16x32_bf16 v[100:103], v[208:211], v[184:187], v[100:103]
	v_mfma_f32_16x16x32_bf16 v[96:99], v[216:219], v[184:187], v[96:99]
	v_mfma_f32_16x16x32_bf16 v[84:87], v[208:211], v[192:195], v[84:87]
	v_mfma_f32_16x16x32_bf16 v[80:83], v[216:219], v[192:195], v[80:83]
	v_mfma_f32_16x16x32_bf16 v[68:71], v[208:211], v[200:203], v[68:71]
	v_mfma_f32_16x16x32_bf16 v[64:67], v[216:219], v[200:203], v[64:67]
	v_mfma_f32_16x16x32_bf16 v[116:119], v[212:215], v[180:183], v[116:119]
	v_mfma_f32_16x16x32_bf16 v[112:115], v[220:223], v[180:183], v[112:115]
	v_mfma_f32_16x16x32_bf16 v[100:103], v[212:215], v[188:191], v[100:103]
	v_mfma_f32_16x16x32_bf16 v[96:99], v[220:223], v[188:191], v[96:99]
	v_mfma_f32_16x16x32_bf16 v[84:87], v[212:215], v[196:199], v[84:87]
	v_mfma_f32_16x16x32_bf16 v[80:83], v[220:223], v[196:199], v[80:83]
	v_mfma_f32_16x16x32_bf16 v[68:71], v[212:215], v[204:207], v[68:71]
	v_mfma_f32_16x16x32_bf16 v[64:67], v[220:223], v[204:207], v[64:67]
	s_mov_b32 m0, s27
	s_add_u32 s100, s50, s2
	s_addc_u32 s101, s51, s3
	s_barrier
	ds_read_b128 v[176:179], v165 offset:16384
	ds_read_b128 v[180:183], v165 offset:17408
	ds_read_b128 v[184:187], v165 offset:18432
	ds_read_b128 v[188:191], v165 offset:19456
	ds_read_b128 v[192:195], v165 offset:20480
	ds_read_b128 v[196:199], v165 offset:21504
	ds_read_b128 v[200:203], v165 offset:22528
	global_load_lds_dwordx4 v134, s[50:51]
	s_mov_b32 m0, s30
	ds_read_b128 v[204:207], v165 offset:23552
	global_load_lds_dwordx4 v130, s[50:51]
	s_barrier
	s_waitcnt lgkmcnt(0)
	v_mfma_f32_16x16x32_bf16 v[60:63], v[150:153], v[176:179], v[60:63]
	v_mfma_f32_16x16x32_bf16 v[56:59], v[168:171], v[176:179], v[56:59]
	v_mfma_f32_16x16x32_bf16 v[44:47], v[150:153], v[184:187], v[44:47]
	v_mfma_f32_16x16x32_bf16 v[40:43], v[168:171], v[184:187], v[40:43]
	v_mfma_f32_16x16x32_bf16 v[28:31], v[150:153], v[192:195], v[28:31]
	v_mfma_f32_16x16x32_bf16 v[24:27], v[168:171], v[192:195], v[24:27]
	v_mfma_f32_16x16x32_bf16 v[12:15], v[150:153], v[200:203], v[12:15]
	v_mfma_f32_16x16x32_bf16 v[8:11], v[168:171], v[200:203], v[8:11]
	v_mfma_f32_16x16x32_bf16 v[60:63], v[154:157], v[180:183], v[60:63]
	v_mfma_f32_16x16x32_bf16 v[56:59], v[172:175], v[180:183], v[56:59]
	v_mfma_f32_16x16x32_bf16 v[44:47], v[154:157], v[188:191], v[44:47]
	v_mfma_f32_16x16x32_bf16 v[40:43], v[172:175], v[188:191], v[40:43]
	v_mfma_f32_16x16x32_bf16 v[28:31], v[154:157], v[196:199], v[28:31]
	v_mfma_f32_16x16x32_bf16 v[24:27], v[172:175], v[196:199], v[24:27]
	v_mfma_f32_16x16x32_bf16 v[12:15], v[154:157], v[204:207], v[12:15]
	v_mfma_f32_16x16x32_bf16 v[8:11], v[172:175], v[204:207], v[8:11]
	s_barrier
	s_add_u32 s58, s48, 0x80000
	s_addc_u32 s59, s49, 0
	s_add_i32 s60, s52, s23
	s_mov_b32 m0, s60
	s_nop 0
	global_load_lds_dwordx4 v132, s[58:59]
	s_add_i32 m0, s60, 0x2000
	s_nop 0
	global_load_lds_dwordx4 v128, s[58:59]
	s_waitcnt vmcnt(6)
	s_barrier
; #define PG8_STAGE(bufoff, gbase, voff) do { _Pragma("unroll") for (int _i = 0; _i < 2; ++_i) \
;         __builtin_amdgcn_global_load_lds((const unsigned*)((const char*)(gbase) + (voff)[_i]), (LAS unsigned*)(lds + (bufoff) + ldsw + _i * 8192), 16, 0, 0); } while (0)
; #define PG8_LDA(dst, b, h) do { _Pragma("unroll") for (int m = 0; m < 4; ++m) _Pragma("unroll") for (int k = 0; k < 2; ++k) dst[m][k] = *(const LAS bf16x8*)(lds + PG8_SA(b, h) + aoff + m * 2048 + k * 1024); } while (0)
; #define PG8_LDB(dst, b, h) do { _Pragma("unroll") for (int n = 0; n < 2; ++n) _Pragma("unroll") for (int k = 0; k < 2; ++k) dst[n][k] = *(const LAS bf16x8*)(lds + PG8_SB(b, h) + boff + n * 2048 + k * 1024); } while (0)
; #define PG8_MMA(ai, bj, At, Bt) do { __builtin_amdgcn_s_setprio(1); _Pragma("unroll") for (int m = 0; m < 4; ++m) _Pragma("unroll") for (int n = 0; n < 2; ++n) _Pragma("unroll") for (int k = 0; k < 2; ++k) \
;         acc[ai][bj][m][n] = __builtin_amdgcn_mfma_f32_16x16x32_bf16(Bt[n][k], At[m][k], acc[ai][bj][m][n], 0, 0, 0); __builtin_amdgcn_s_setprio(0); } while (0)
; #define PG8_WAIT_V(n) asm volatile("s_waitcnt vmcnt(" #n ")" ::: "memory")
; #define PG8_WAIT_L(n) asm volatile("s_waitcnt lgkmcnt(" #n ")" ::: "memory")
; #define PG8_BAR __builtin_amdgcn_s_barrier()
; #define PG8_SCHED __builtin_amdgcn_sched_barrier(0)
; template <class Epi>
; __device__ __forceinline__ void gemm_phase(LAS unsigned char* lds, const Gemm g, const StaticOrder& S, const Epi& E) {
;     ...
;             PG8_WAIT_V(6); PG8_BAR; PG8_MMA(1, 1, At, B1); PG8_BAR;
;             PG8_LDB(B0, 1, 0); PG8_SCHED; PG8_LDA(At, 1, 0); PG8_STAGE(PG8_SA(0, 1), a2 + hstep, voffA);
;             PG8_WAIT_L(8); PG8_BAR; PG8_WAIT_L(0); PG8_MMA(0, 0, At, B0); PG8_BAR; PG8_SCHED;
;             PG8_LDB(B1, 1, 1); PG8_STAGE(PG8_SB(1, 0), b3, voffB);
;             PG8_BAR; PG8_WAIT_L(0); PG8_MMA(0, 1, At, B1); PG8_BAR;
;             PG8_LDA(At, 1, 1); PG8_STAGE(PG8_SA(1, 0), a3, voffA);
;             PG8_BAR; PG8_WAIT_L(0); PG8_MMA(1, 0, At, B0); PG8_BAR; PG8_SCHED;
	v_mfma_f32_16x16x32_bf16 v[52:55], v[208:211], v[176:179], v[52:55]
	v_mfma_f32_16x16x32_bf16 v[48:51], v[216:219], v[176:179], v[48:51]
	v_mfma_f32_16x16x32_bf16 v[36:39], v[208:211], v[184:187], v[36:39]
	v_mfma_f32_16x16x32_bf16 v[32:35], v[216:219], v[184:187], v[32:35]
	v_mfma_f32_16x16x32_bf16 v[20:23], v[208:211], v[192:195], v[20:23]
	v_mfma_f32_16x16x32_bf16 v[16:19], v[216:219], v[192:195], v[16:19]
	v_mfma_f32_16x16x32_bf16 v[4:7], v[208:211], v[200:203], v[4:7]
	v_mfma_f32_16x16x32_bf16 v[0:3], v[216:219], v[200:203], v[0:3]
	v_mfma_f32_16x16x32_bf16 v[52:55], v[212:215], v[180:183], v[52:55]
	v_mfma_f32_16x16x32_bf16 v[48:51], v[220:223], v[180:183], v[48:51]
	v_mfma_f32_16x16x32_bf16 v[36:39], v[212:215], v[188:191], v[36:39]
	v_mfma_f32_16x16x32_bf16 v[32:35], v[220:223], v[188:191], v[32:35]
	v_mfma_f32_16x16x32_bf16 v[20:23], v[212:215], v[196:199], v[20:23]
	v_mfma_f32_16x16x32_bf16 v[16:19], v[220:223], v[196:199], v[16:19]
	v_mfma_f32_16x16x32_bf16 v[4:7], v[212:215], v[204:207], v[4:7]
	v_mfma_f32_16x16x32_bf16 v[0:3], v[220:223], v[204:207], v[0:3]
	s_add_i32 s58, 0, 0x18000
	v_add_u32_e32 v136, s58, v161
	s_barrier
	ds_read_b128 v[150:153], v136
	ds_read_b128 v[154:157], v136 offset:1024
	ds_read_b128 v[168:171], v136 offset:2048
	ds_read_b128 v[172:175], v136 offset:3072
	s_add_u32 s50, s50, 0x80000
	s_addc_u32 s51, s51, 0
	s_mov_b32 m0, s31
	ds_read_b128 v[176:179], v165 offset:32768
	ds_read_b128 v[180:183], v165 offset:33792
	ds_read_b128 v[184:187], v165 offset:34816
	ds_read_b128 v[188:191], v165 offset:35840
	ds_read_b128 v[192:195], v165 offset:36864
	ds_read_b128 v[196:199], v165 offset:37888
	ds_read_b128 v[200:203], v165 offset:38912
	global_load_lds_dwordx4 v134, s[50:51]
	s_mov_b32 m0, s33
	ds_read_b128 v[204:207], v165 offset:39936
	global_load_lds_dwordx4 v130, s[50:51]
	s_waitcnt lgkmcnt(8)
	s_barrier
	s_waitcnt lgkmcnt(0)
	v_mfma_f32_16x16x32_bf16 v[124:127], v[150:153], v[176:179], v[124:127]
	v_mfma_f32_16x16x32_bf16 v[120:123], v[168:171], v[176:179], v[120:123]
	v_mfma_f32_16x16x32_bf16 v[108:111], v[150:153], v[184:187], v[108:111]
	v_mfma_f32_16x16x32_bf16 v[104:107], v[168:171], v[184:187], v[104:107]
	v_mfma_f32_16x16x32_bf16 v[92:95], v[150:153], v[192:195], v[92:95]
	v_mfma_f32_16x16x32_bf16 v[88:91], v[168:171], v[192:195], v[88:91]
	v_mfma_f32_16x16x32_bf16 v[76:79], v[150:153], v[200:203], v[76:79]
	v_mfma_f32_16x16x32_bf16 v[72:75], v[168:171], v[200:203], v[72:75]
	v_mfma_f32_16x16x32_bf16 v[124:127], v[154:157], v[180:183], v[124:127]
	v_mfma_f32_16x16x32_bf16 v[120:123], v[172:175], v[180:183], v[120:123]
	v_mfma_f32_16x16x32_bf16 v[108:111], v[154:157], v[188:191], v[108:111]
	v_mfma_f32_16x16x32_bf16 v[104:107], v[172:175], v[188:191], v[104:107]
	v_mfma_f32_16x16x32_bf16 v[92:95], v[154:157], v[196:199], v[92:95]
	v_mfma_f32_16x16x32_bf16 v[88:91], v[172:175], v[196:199], v[88:91]
	v_mfma_f32_16x16x32_bf16 v[76:79], v[154:157], v[204:207], v[76:79]
	v_mfma_f32_16x16x32_bf16 v[72:75], v[172:175], v[204:207], v[72:75]
	s_barrier
	s_add_i32 s50, 0, 0x1c000
	s_add_i32 s51, s58, s23
	v_add_u32_e32 v136, s50, v161
	s_mov_b32 m0, s51
	ds_read_b128 v[208:211], v136
	ds_read_b128 v[212:215], v136 offset:1024
	ds_read_b128 v[216:219], v136 offset:2048
	global_load_lds_dwordx4 v132, s[98:99]
	s_add_i32 m0, s51, 0x2000
	ds_read_b128 v[220:223], v136 offset:3072
	global_load_lds_dwordx4 v128, s[98:99]
	s_barrier
	s_waitcnt lgkmcnt(0)
	v_mfma_f32_16x16x32_bf16 v[116:119], v[208:211], v[176:179], v[116:119]
	v_mfma_f32_16x16x32_bf16 v[112:115], v[216:219], v[176:179], v[112:115]
	v_mfma_f32_16x16x32_bf16 v[100:103], v[208:211], v[184:187], v[100:103]
	v_mfma_f32_16x16x32_bf16 v[96:99], v[216:219], v[184:187], v[96:99]
	v_mfma_f32_16x16x32_bf16 v[84:87], v[208:211], v[192:195], v[84:87]
	v_mfma_f32_16x16x32_bf16 v[80:83], v[216:219], v[192:195], v[80:83]
	v_mfma_f32_16x16x32_bf16 v[68:71], v[208:211], v[200:203], v[68:71]
	v_mfma_f32_16x16x32_bf16 v[64:67], v[216:219], v[200:203], v[64:67]
	v_mfma_f32_16x16x32_bf16 v[116:119], v[212:215], v[180:183], v[116:119]
	v_mfma_f32_16x16x32_bf16 v[112:115], v[220:223], v[180:183], v[112:115]
	v_mfma_f32_16x16x32_bf16 v[100:103], v[212:215], v[188:191], v[100:103]
	v_mfma_f32_16x16x32_bf16 v[96:99], v[220:223], v[188:191], v[96:99]
	v_mfma_f32_16x16x32_bf16 v[84:87], v[212:215], v[196:199], v[84:87]
	v_mfma_f32_16x16x32_bf16 v[80:83], v[220:223], v[196:199], v[80:83]
	v_mfma_f32_16x16x32_bf16 v[68:71], v[212:215], v[204:207], v[68:71]
	v_mfma_f32_16x16x32_bf16 v[64:67], v[220:223], v[204:207], v[64:67]
	s_mov_b32 m0, s37
	s_barrier
	ds_read_b128 v[176:179], v165 offset:49152
	ds_read_b128 v[180:183], v165 offset:50176
	ds_read_b128 v[184:187], v165 offset:51200
	ds_read_b128 v[188:191], v165 offset:52224
	ds_read_b128 v[192:195], v165 offset:53248
	ds_read_b128 v[196:199], v165 offset:54272
	ds_read_b128 v[200:203], v165 offset:55296
	global_load_lds_dwordx4 v134, s[100:101]
	s_mov_b32 m0, s38
	ds_read_b128 v[204:207], v165 offset:56320
	global_load_lds_dwordx4 v130, s[100:101]
	s_barrier
	s_waitcnt lgkmcnt(0)
	v_mfma_f32_16x16x32_bf16 v[60:63], v[150:153], v[176:179], v[60:63]
	v_mfma_f32_16x16x32_bf16 v[56:59], v[168:171], v[176:179], v[56:59]
	v_mfma_f32_16x16x32_bf16 v[44:47], v[150:153], v[184:187], v[44:47]
	v_mfma_f32_16x16x32_bf16 v[40:43], v[168:171], v[184:187], v[40:43]
	v_mfma_f32_16x16x32_bf16 v[28:31], v[150:153], v[192:195], v[28:31]
	v_mfma_f32_16x16x32_bf16 v[24:27], v[168:171], v[192:195], v[24:27]
	v_mfma_f32_16x16x32_bf16 v[12:15], v[150:153], v[200:203], v[12:15]
	v_mfma_f32_16x16x32_bf16 v[8:11], v[168:171], v[200:203], v[8:11]
	v_mfma_f32_16x16x32_bf16 v[60:63], v[154:157], v[180:183], v[60:63]
	v_mfma_f32_16x16x32_bf16 v[56:59], v[172:175], v[180:183], v[56:59]
	v_mfma_f32_16x16x32_bf16 v[44:47], v[154:157], v[188:191], v[44:47]
	v_mfma_f32_16x16x32_bf16 v[40:43], v[172:175], v[188:191], v[40:43]
	v_mfma_f32_16x16x32_bf16 v[28:31], v[154:157], v[196:199], v[28:31]
	v_mfma_f32_16x16x32_bf16 v[24:27], v[172:175], v[196:199], v[24:27]
	v_mfma_f32_16x16x32_bf16 v[12:15], v[154:157], v[204:207], v[12:15]
	v_mfma_f32_16x16x32_bf16 v[8:11], v[172:175], v[204:207], v[8:11]
	s_barrier
; #define PG8_STAGE(bufoff, gbase, voff) do { _Pragma("unroll") for (int _i = 0; _i < 2; ++_i) \
;         __builtin_amdgcn_global_load_lds((const unsigned*)((const char*)(gbase) + (voff)[_i]), (LAS unsigned*)(lds + (bufoff) + ldsw + _i * 8192), 16, 0, 0); } while (0)
; #define PG8_MMA(ai, bj, At, Bt) do { __builtin_amdgcn_s_setprio(1); _Pragma("unroll") for (int m = 0; m < 4; ++m) _Pragma("unroll") for (int n = 0; n < 2; ++n) _Pragma("unroll") for (int k = 0; k < 2; ++k) \
;         acc[ai][bj][m][n] = __builtin_amdgcn_mfma_f32_16x16x32_bf16(Bt[n][k], At[m][k], acc[ai][bj][m][n], 0, 0, 0); __builtin_amdgcn_s_setprio(0); } while (0)
; #define PG8_WAIT_V(n) asm volatile("s_waitcnt vmcnt(" #n ")" ::: "memory")
; #define PG8_BAR __builtin_amdgcn_s_barrier()
; __device__ __forceinline__ u32x4 pack8(f32x4 v0, f32x4 v1) { u32x4 w; w.x = cvt_pk_bf16(v0[0], v0[1]); w.y = cvt_pk_bf16(v0[2], v0[3]); w.z = cvt_pk_bf16(v1[0], v1[1]); w.w = cvt_pk_bf16(v1[2], v1[3]); return w; }
; template <class Epi>
; __device__ __forceinline__ void gemm_phase(LAS unsigned char* lds, const Gemm g, const StaticOrder& S, const Epi& E) {
;     ...
;             PG8_STAGE(PG8_SB(1, 1), b3 + hstep, voffB);
;             PG8_WAIT_V(6); PG8_BAR; PG8_MMA(1, 1, At, B1); PG8_BAR;
;         }
;         E(acc, cur, wr, wc, fr, fq);
;     __device__ __forceinline__ void operator()(const f32x4 (&acc)[2][2][4][2], const Unit& u, int wr, int wc, int fr, int fq) const {
;     ...
;         } else {
;             const int col0 = u.pn * BM + wc * 32 + 8 * fq; const float sc = (u.pn < 2) ? QSCALE : 1.0f;
; #pragma unroll
;             for (int ai = 0; ai < 2; ++ai)
; #pragma unroll
;                 for (int m = 0; m < 4; ++m) { bf16_t* rowp = O + (size_t)(row0 + ai * HALF + m * 16) * NQKV + col0; const float scr_ = sc * rowsc[row0 + ai * HALF + m * 16];
; #pragma unroll
;                     for (int bj = 0; bj < 2; ++bj) *(u32x4*)(rowp + bj * HALF) = pack8(acc[ai][bj][m][0] * scr_, acc[ai][bj][m][1] * scr_); }
	s_add_u32 s48, s48, 0x80080
	s_addc_u32 s49, s49, 0
	s_add_i32 s50, s50, s23
	s_mov_b32 m0, s50
	s_nop 0
	global_load_lds_dwordx4 v132, s[48:49]
	s_add_i32 m0, s50, 0x2000
	s_nop 0
	global_load_lds_dwordx4 v128, s[48:49]
	s_waitcnt vmcnt(6)
	s_barrier
	v_mfma_f32_16x16x32_bf16 v[52:55], v[208:211], v[176:179], v[52:55]
	v_mfma_f32_16x16x32_bf16 v[48:51], v[216:219], v[176:179], v[48:51]
	v_mfma_f32_16x16x32_bf16 v[36:39], v[208:211], v[184:187], v[36:39]
	v_mfma_f32_16x16x32_bf16 v[32:35], v[216:219], v[184:187], v[32:35]
	v_mfma_f32_16x16x32_bf16 v[20:23], v[208:211], v[192:195], v[20:23]
	v_mfma_f32_16x16x32_bf16 v[16:19], v[216:219], v[192:195], v[16:19]
	v_mfma_f32_16x16x32_bf16 v[4:7], v[208:211], v[200:203], v[4:7]
	v_mfma_f32_16x16x32_bf16 v[0:3], v[216:219], v[200:203], v[0:3]
	v_mfma_f32_16x16x32_bf16 v[52:55], v[212:215], v[180:183], v[52:55]
	v_mfma_f32_16x16x32_bf16 v[48:51], v[220:223], v[180:183], v[48:51]
	v_mfma_f32_16x16x32_bf16 v[36:39], v[212:215], v[188:191], v[36:39]
	v_mfma_f32_16x16x32_bf16 v[32:35], v[220:223], v[188:191], v[32:35]
	v_mfma_f32_16x16x32_bf16 v[20:23], v[212:215], v[196:199], v[20:23]
	v_mfma_f32_16x16x32_bf16 v[16:19], v[220:223], v[196:199], v[16:19]
	v_mfma_f32_16x16x32_bf16 v[4:7], v[212:215], v[204:207], v[4:7]
	v_mfma_f32_16x16x32_bf16 v[0:3], v[220:223], v[204:207], v[0:3]
	s_add_i32 s57, s57, 2
	s_add_u32 s46, s46, 0x100
	s_addc_u32 s47, s47, 0
	s_add_u32 s55, s55, 0x100
	s_addc_u32 s56, s56, 0
	s_cmp_gt_u32 s57, 29
	s_barrier
	s_cbranch_scc0 .LBB0_407
	v_lshl_add_u32 v154, s44, 8, v160
	s_add_i32 s9, s34, -6
	s_lshl_b32 s7, s34, 8
	s_cmp_gt_u32 s9, 11
	s_mov_b64 s[44:45], -1
	v_ashrrev_i32_e32 v155, 31, v154
	v_or_b32_e32 v174, 16, v154
	v_or_b32_e32 v173, 32, v154
	v_or_b32_e32 v172, 48, v154
	v_add_u32_e32 v171, 0x80, v154
	v_add_u32_e32 v170, 0x90, v154
	v_add_u32_e32 v169, 0xa0, v154
	v_add_u32_e32 v168, 0xb0, v154
	s_cbranch_scc0 .LBB0_410
	v_lshl_add_u64 v[150:151], v[154:155], 2, s[14:15]
	global_load_dword v136, v[150:151], off
	global_load_dword v204, v[150:151], off offset:64
	global_load_dword v205, v[150:151], off offset:128
	global_load_dword v206, v[150:151], off offset:192
	global_load_dword v207, v[150:151], off offset:512
	global_load_dword v208, v[150:151], off offset:576
	global_load_dword v209, v[150:151], off offset:640
	global_load_dword v210, v[150:151], off offset:704
	s_cmp_lt_i32 s34, 2
	v_or_b32_e32 v156, s7, v162
	s_cselect_b64 vcc, -1, 0
	v_mov_b64_e32 v[152:153], s[20:21]
	v_cndmask_b32_e32 v175, 1.0, v167, vcc
	v_ashrrev_i32_e32 v157, 31, v156
	v_mad_i64_i32 v[176:177], s[44:45], v154, s53, v[152:153]
	v_lshlrev_b64 v[156:157], 1, v[156:157]
	v_lshl_add_u64 v[180:181], v[176:177], 0, v[156:157]
	s_waitcnt vmcnt(0)
	v_mul_f32_e32 v136, v175, v136
	v_pk_mul_f32 v[178:179], v[126:127], v[136:137] op_sel_hi:[1,0]
	v_pk_mul_f32 v[176:177], v[124:125], v[136:137] op_sel_hi:[1,0]
	v_pk_mul_f32 v[182:183], v[122:123], v[136:137] op_sel_hi:[1,0]
	v_pk_mul_f32 v[184:185], v[120:121], v[136:137] op_sel_hi:[1,0]
	v_cvt_pk_bf16_f32 v176, v176, v177
	v_cvt_pk_bf16_f32 v177, v178, v179
	v_pk_mul_f32 v[186:187], v[118:119], v[136:137] op_sel_hi:[1,0]
	v_cvt_pk_bf16_f32 v178, v184, v185
	v_cvt_pk_bf16_f32 v179, v182, v183
	v_pk_mul_f32 v[188:189], v[116:117], v[136:137] op_sel_hi:[1,0]
	v_pk_mul_f32 v[190:191], v[114:115], v[136:137] op_sel_hi:[1,0]
	v_pk_mul_f32 v[192:193], v[112:113], v[136:137] op_sel_hi:[1,0]
	global_store_dwordx4 v[180:181], v[176:179], off
	s_nop 1
	v_cvt_pk_bf16_f32 v176, v188, v189
	v_cvt_pk_bf16_f32 v177, v186, v187
	v_cvt_pk_bf16_f32 v178, v192, v193
	v_cvt_pk_bf16_f32 v179, v190, v191
	global_store_dwordx4 v[180:181], v[176:179], off offset:256
	s_nop 1
	v_mov_b32_e32 v136, v204
	v_mul_f32_e32 v136, v175, v136
	v_mad_i64_i32 v[176:177], s[44:45], v174, s53, v[152:153]
	v_lshl_add_u64 v[180:181], v[176:177], 0, v[156:157]
	v_pk_mul_f32 v[178:179], v[110:111], v[136:137] op_sel_hi:[1,0]
	v_pk_mul_f32 v[176:177], v[108:109], v[136:137] op_sel_hi:[1,0]
	v_pk_mul_f32 v[182:183], v[106:107], v[136:137] op_sel_hi:[1,0]
	v_pk_mul_f32 v[184:185], v[104:105], v[136:137] op_sel_hi:[1,0]
	v_cvt_pk_bf16_f32 v176, v176, v177
	v_cvt_pk_bf16_f32 v177, v178, v179
	v_pk_mul_f32 v[186:187], v[102:103], v[136:137] op_sel_hi:[1,0]
	v_cvt_pk_bf16_f32 v178, v184, v185
	v_cvt_pk_bf16_f32 v179, v182, v183
	v_pk_mul_f32 v[188:189], v[100:101], v[136:137] op_sel_hi:[1,0]
	v_pk_mul_f32 v[190:191], v[98:99], v[136:137] op_sel_hi:[1,0]
	v_pk_mul_f32 v[192:193], v[96:97], v[136:137] op_sel_hi:[1,0]
	global_store_dwordx4 v[180:181], v[176:179], off
	s_nop 1
	v_cvt_pk_bf16_f32 v176, v188, v189
	v_cvt_pk_bf16_f32 v177, v186, v187
	v_cvt_pk_bf16_f32 v178, v192, v193
	v_cvt_pk_bf16_f32 v179, v190, v191
	global_store_dwordx4 v[180:181], v[176:179], off offset:256
	s_nop 1
	v_mov_b32_e32 v136, v205
	v_mul_f32_e32 v136, v175, v136
	v_mad_i64_i32 v[176:177], s[44:45], v173, s53, v[152:153]
	v_lshl_add_u64 v[180:181], v[176:177], 0, v[156:157]
	v_pk_mul_f32 v[178:179], v[94:95], v[136:137] op_sel_hi:[1,0]
	v_pk_mul_f32 v[176:177], v[92:93], v[136:137] op_sel_hi:[1,0]
	v_pk_mul_f32 v[182:183], v[90:91], v[136:137] op_sel_hi:[1,0]
	v_pk_mul_f32 v[184:185], v[88:89], v[136:137] op_sel_hi:[1,0]
	v_cvt_pk_bf16_f32 v176, v176, v177
	v_cvt_pk_bf16_f32 v177, v178, v179
	v_pk_mul_f32 v[186:187], v[86:87], v[136:137] op_sel_hi:[1,0]
	v_cvt_pk_bf16_f32 v178, v184, v185
	v_cvt_pk_bf16_f32 v179, v182, v183
	v_pk_mul_f32 v[188:189], v[84:85], v[136:137] op_sel_hi:[1,0]
	v_pk_mul_f32 v[190:191], v[82:83], v[136:137] op_sel_hi:[1,0]
	v_pk_mul_f32 v[192:193], v[80:81], v[136:137] op_sel_hi:[1,0]
; __device__ __forceinline__ u32x4 pack8(f32x4 v0, f32x4 v1) { u32x4 w; w.x = cvt_pk_bf16(v0[0], v0[1]); w.y = cvt_pk_bf16(v0[2], v0[3]); w.z = cvt_pk_bf16(v1[0], v1[1]); w.w = cvt_pk_bf16(v1[2], v1[3]); return w; }
;     __device__ __forceinline__ void operator()(const f32x4 (&acc)[2][2][4][2], const Unit& u, int wr, int wc, int fr, int fq) const {
;     ...
;         } else {
;             const int col0 = u.pn * BM + wc * 32 + 8 * fq; const float sc = (u.pn < 2) ? QSCALE : 1.0f;
; #pragma unroll
;             for (int ai = 0; ai < 2; ++ai)
; #pragma unroll
;                 for (int m = 0; m < 4; ++m) { bf16_t* rowp = O + (size_t)(row0 + ai * HALF + m * 16) * NQKV + col0; const float scr_ = sc * rowsc[row0 + ai * HALF + m * 16];
; #pragma unroll
;                     for (int bj = 0; bj < 2; ++bj) *(u32x4*)(rowp + bj * HALF) = pack8(acc[ai][bj][m][0] * scr_, acc[ai][bj][m][1] * scr_); }
	global_store_dwordx4 v[180:181], v[176:179], off
	s_nop 1
	v_cvt_pk_bf16_f32 v176, v188, v189
	v_cvt_pk_bf16_f32 v177, v186, v187
	v_cvt_pk_bf16_f32 v178, v192, v193
	v_cvt_pk_bf16_f32 v179, v190, v191
	global_store_dwordx4 v[180:181], v[176:179], off offset:256
	s_nop 1
	v_mov_b32_e32 v136, v206
	v_mul_f32_e32 v136, v175, v136
	v_mad_i64_i32 v[176:177], s[44:45], v172, s53, v[152:153]
	v_lshl_add_u64 v[180:181], v[176:177], 0, v[156:157]
	v_pk_mul_f32 v[178:179], v[78:79], v[136:137] op_sel_hi:[1,0]
	v_pk_mul_f32 v[176:177], v[76:77], v[136:137] op_sel_hi:[1,0]
	v_pk_mul_f32 v[182:183], v[74:75], v[136:137] op_sel_hi:[1,0]
	v_pk_mul_f32 v[184:185], v[72:73], v[136:137] op_sel_hi:[1,0]
	v_cvt_pk_bf16_f32 v176, v176, v177
	v_cvt_pk_bf16_f32 v177, v178, v179
	v_pk_mul_f32 v[186:187], v[70:71], v[136:137] op_sel_hi:[1,0]
	v_cvt_pk_bf16_f32 v178, v184, v185
	v_cvt_pk_bf16_f32 v179, v182, v183
	v_pk_mul_f32 v[188:189], v[68:69], v[136:137] op_sel_hi:[1,0]
	v_pk_mul_f32 v[190:191], v[66:67], v[136:137] op_sel_hi:[1,0]
	v_pk_mul_f32 v[192:193], v[64:65], v[136:137] op_sel_hi:[1,0]
	global_store_dwordx4 v[180:181], v[176:179], off
	s_nop 1
	v_cvt_pk_bf16_f32 v176, v188, v189
	v_cvt_pk_bf16_f32 v177, v186, v187
	v_cvt_pk_bf16_f32 v178, v192, v193
	v_cvt_pk_bf16_f32 v179, v190, v191
	global_store_dwordx4 v[180:181], v[176:179], off offset:256
	s_nop 1
	v_mov_b32_e32 v136, v207
	v_mul_f32_e32 v136, v175, v136
	v_mad_i64_i32 v[176:177], s[44:45], v171, s53, v[152:153]
	v_lshl_add_u64 v[180:181], v[176:177], 0, v[156:157]
	v_pk_mul_f32 v[178:179], v[62:63], v[136:137] op_sel_hi:[1,0]
	v_pk_mul_f32 v[176:177], v[60:61], v[136:137] op_sel_hi:[1,0]
	v_pk_mul_f32 v[182:183], v[58:59], v[136:137] op_sel_hi:[1,0]
	v_pk_mul_f32 v[184:185], v[56:57], v[136:137] op_sel_hi:[1,0]
	v_cvt_pk_bf16_f32 v176, v176, v177
	v_cvt_pk_bf16_f32 v177, v178, v179
	v_pk_mul_f32 v[186:187], v[54:55], v[136:137] op_sel_hi:[1,0]
	v_cvt_pk_bf16_f32 v178, v184, v185
	v_cvt_pk_bf16_f32 v179, v182, v183
	v_pk_mul_f32 v[188:189], v[52:53], v[136:137] op_sel_hi:[1,0]
	v_pk_mul_f32 v[190:191], v[50:51], v[136:137] op_sel_hi:[1,0]
	v_pk_mul_f32 v[192:193], v[48:49], v[136:137] op_sel_hi:[1,0]
	global_store_dwordx4 v[180:181], v[176:179], off
	s_nop 1
	v_cvt_pk_bf16_f32 v176, v188, v189
	v_cvt_pk_bf16_f32 v177, v186, v187
	v_cvt_pk_bf16_f32 v178, v192, v193
	v_cvt_pk_bf16_f32 v179, v190, v191
	global_store_dwordx4 v[180:181], v[176:179], off offset:256
	s_nop 1
	v_mov_b32_e32 v136, v208
	v_mul_f32_e32 v136, v175, v136
	v_mad_i64_i32 v[176:177], s[44:45], v170, s53, v[152:153]
	v_lshl_add_u64 v[180:181], v[176:177], 0, v[156:157]
	v_pk_mul_f32 v[178:179], v[46:47], v[136:137] op_sel_hi:[1,0]
	v_pk_mul_f32 v[176:177], v[44:45], v[136:137] op_sel_hi:[1,0]
	v_pk_mul_f32 v[182:183], v[42:43], v[136:137] op_sel_hi:[1,0]
	v_pk_mul_f32 v[184:185], v[40:41], v[136:137] op_sel_hi:[1,0]
	v_cvt_pk_bf16_f32 v176, v176, v177
	v_cvt_pk_bf16_f32 v177, v178, v179
	v_pk_mul_f32 v[186:187], v[38:39], v[136:137] op_sel_hi:[1,0]
	v_cvt_pk_bf16_f32 v178, v184, v185
	v_cvt_pk_bf16_f32 v179, v182, v183
	v_pk_mul_f32 v[188:189], v[36:37], v[136:137] op_sel_hi:[1,0]
	v_pk_mul_f32 v[190:191], v[34:35], v[136:137] op_sel_hi:[1,0]
	v_pk_mul_f32 v[192:193], v[32:33], v[136:137] op_sel_hi:[1,0]
	global_store_dwordx4 v[180:181], v[176:179], off
	s_nop 1
	v_cvt_pk_bf16_f32 v176, v188, v189
	v_cvt_pk_bf16_f32 v177, v186, v187
	v_cvt_pk_bf16_f32 v178, v192, v193
	v_cvt_pk_bf16_f32 v179, v190, v191
	global_store_dwordx4 v[180:181], v[176:179], off offset:256
	s_nop 1
	v_mov_b32_e32 v136, v209
	v_mul_f32_e32 v136, v175, v136
	v_mad_i64_i32 v[176:177], s[44:45], v169, s53, v[152:153]
	v_lshl_add_u64 v[180:181], v[176:177], 0, v[156:157]
	v_pk_mul_f32 v[178:179], v[30:31], v[136:137] op_sel_hi:[1,0]
	v_pk_mul_f32 v[176:177], v[28:29], v[136:137] op_sel_hi:[1,0]
	v_pk_mul_f32 v[182:183], v[26:27], v[136:137] op_sel_hi:[1,0]
	v_pk_mul_f32 v[184:185], v[24:25], v[136:137] op_sel_hi:[1,0]
	v_cvt_pk_bf16_f32 v176, v176, v177
	v_cvt_pk_bf16_f32 v177, v178, v179
	v_pk_mul_f32 v[186:187], v[22:23], v[136:137] op_sel_hi:[1,0]
	v_cvt_pk_bf16_f32 v178, v184, v185
	v_cvt_pk_bf16_f32 v179, v182, v183
	v_pk_mul_f32 v[188:189], v[20:21], v[136:137] op_sel_hi:[1,0]
	v_pk_mul_f32 v[190:191], v[18:19], v[136:137] op_sel_hi:[1,0]
	v_pk_mul_f32 v[192:193], v[16:17], v[136:137] op_sel_hi:[1,0]
	global_store_dwordx4 v[180:181], v[176:179], off
	s_nop 1
	v_cvt_pk_bf16_f32 v176, v188, v189
	v_cvt_pk_bf16_f32 v177, v186, v187
	v_cvt_pk_bf16_f32 v178, v192, v193
	v_cvt_pk_bf16_f32 v179, v190, v191
	global_store_dwordx4 v[180:181], v[176:179], off offset:256
	s_nop 1
	v_mov_b32_e32 v136, v210
	v_mad_i64_i32 v[150:151], s[44:45], v168, s53, v[152:153]
	v_lshl_add_u64 v[156:157], v[150:151], 0, v[156:157]
	s_mov_b64 s[44:45], 0
	v_mul_f32_e32 v136, v175, v136
	v_pk_mul_f32 v[152:153], v[14:15], v[136:137] op_sel_hi:[1,0]
	v_pk_mul_f32 v[150:151], v[12:13], v[136:137] op_sel_hi:[1,0]
	v_pk_mul_f32 v[176:177], v[10:11], v[136:137] op_sel_hi:[1,0]
	v_pk_mul_f32 v[178:179], v[8:9], v[136:137] op_sel_hi:[1,0]
	v_cvt_pk_bf16_f32 v150, v150, v151
	v_cvt_pk_bf16_f32 v151, v152, v153
	v_pk_mul_f32 v[180:181], v[6:7], v[136:137] op_sel_hi:[1,0]
	v_cvt_pk_bf16_f32 v152, v178, v179
	v_cvt_pk_bf16_f32 v153, v176, v177
	v_pk_mul_f32 v[182:183], v[4:5], v[136:137] op_sel_hi:[1,0]
	v_pk_mul_f32 v[184:185], v[2:3], v[136:137] op_sel_hi:[1,0]
	v_pk_mul_f32 v[186:187], v[0:1], v[136:137] op_sel_hi:[1,0]
	global_store_dwordx4 v[156:157], v[150:153], off
	s_nop 1
	v_cvt_pk_bf16_f32 v150, v182, v183
	v_cvt_pk_bf16_f32 v151, v180, v181
	v_cvt_pk_bf16_f32 v152, v186, v187
	v_cvt_pk_bf16_f32 v153, v184, v185
	global_store_dwordx4 v[156:157], v[150:153], off offset:256

; #define PG8_STAGE(bufoff, gbase, voff) do { _Pragma("unroll") for (int _i = 0; _i < 2; ++_i) \
;         __builtin_amdgcn_global_load_lds((const unsigned*)((const char*)(gbase) + (voff)[_i]), (LAS unsigned*)(lds + (bufoff) + ldsw + _i * 8192), 16, 0, 0); } while (0)
; #define PG8_LDA(dst, b, h) do { _Pragma("unroll") for (int m = 0; m < 4; ++m) _Pragma("unroll") for (int k = 0; k < 2; ++k) dst[m][k] = *(const LAS bf16x8*)(lds + PG8_SA(b, h) + aoff + m * 2048 + k * 1024); } while (0)
; #define PG8_LDB(dst, b, h) do { _Pragma("unroll") for (int n = 0; n < 2; ++n) _Pragma("unroll") for (int k = 0; k < 2; ++k) dst[n][k] = *(const LAS bf16x8*)(lds + PG8_SB(b, h) + boff + n * 2048 + k * 1024); } while (0)
; #define PG8_MMA(ai, bj, At, Bt) do { __builtin_amdgcn_s_setprio(1); _Pragma("unroll") for (int m = 0; m < 4; ++m) _Pragma("unroll") for (int n = 0; n < 2; ++n) _Pragma("unroll") for (int k = 0; k < 2; ++k) \
;         acc[ai][bj][m][n] = __builtin_amdgcn_mfma_f32_16x16x32_bf16(Bt[n][k], At[m][k], acc[ai][bj][m][n], 0, 0, 0); __builtin_amdgcn_s_setprio(0); } while (0)
; #define PG8_WAIT_V(n) asm volatile("s_waitcnt vmcnt(" #n ")" ::: "memory")
; #define PG8_WAIT_L(n) asm volatile("s_waitcnt lgkmcnt(" #n ")" ::: "memory")
; template <class Epi>
; __device__ __forceinline__ void gemm_phase(LAS unsigned char* lds, const Gemm g, const StaticOrder& S, const Epi& E) {
;     ...
;         for (int t = 0; t < nt; t += 2) {
;             const bool last = (t == nt - 2);
;             const char* a1 = cA + (size_t)(t + 1) * kstep;
;             const char* a2 = last ? nA : cA + (size_t)(t + 2) * kstep; const char* b2 = last ? nB : cB + (size_t)(t + 2) * kstep;
;             const char* a3 = a2 + kstep; const char* b3 = b2 + kstep;
;             PG8_LDB(B0, 0, 0); PG8_SCHED; PG8_LDA(At, 0, 0); PG8_STAGE(PG8_SA(1, 1), a1 + hstep, voffA);
;             PG8_WAIT_L(8); PG8_BAR; PG8_WAIT_L(0); PG8_MMA(0, 0, At, B0); PG8_BAR; PG8_SCHED;
;             PG8_LDB(B1, 0, 1); PG8_STAGE(PG8_SB(0, 0), b2, voffB);
;             PG8_BAR; PG8_WAIT_L(0); PG8_MMA(0, 1, At, B1); PG8_BAR;
;             PG8_LDA(At, 0, 1); PG8_STAGE(PG8_SA(0, 0), a2, voffA);
;             PG8_BAR; PG8_WAIT_L(0); PG8_MMA(1, 0, At, B0); PG8_BAR; PG8_SCHED;
;             PG8_STAGE(PG8_SB(0, 1), b2 + hstep, voffB);
;             PG8_WAIT_V(6); PG8_BAR; PG8_MMA(1, 1, At, B1); PG8_BAR;
.LBB0_673:
	ds_read_b128 v[148:151], v145
	ds_read_b128 v[152:155], v145 offset:1024
	ds_read_b128 v[160:163], v145 offset:2048
	ds_read_b128 v[164:167], v145 offset:3072
	s_add_u32 s52, s50, 0xfff80080
	s_addc_u32 s53, s51, -1
	s_cmp_eq_u32 s69, 28
	s_cselect_b32 s55, s43, s53
	s_cselect_b32 s54, s65, s52
	s_cselect_b32 s53, s41, s68
	s_cselect_b32 s52, s66, s67
	s_add_i32 m0, s28, 0xc000
	ds_read_b128 v[168:171], v146
	ds_read_b128 v[172:175], v146 offset:1024
	ds_read_b128 v[176:179], v146 offset:2048
	ds_read_b128 v[180:183], v146 offset:3072
	ds_read_b128 v[184:187], v146 offset:4096
	ds_read_b128 v[188:191], v146 offset:5120
	ds_read_b128 v[192:195], v146 offset:6144
	global_load_lds_dwordx4 v136, s[50:51]
	s_add_i32 m0, s28, 0xe000
	ds_read_b128 v[196:199], v146 offset:7168
	global_load_lds_dwordx4 v138, s[50:51]
	s_waitcnt lgkmcnt(8)
	s_barrier
	s_waitcnt lgkmcnt(0)
	v_mfma_f32_16x16x32_bf16 v[124:127], v[148:151], v[168:171], v[124:127]
	v_mfma_f32_16x16x32_bf16 v[120:123], v[160:163], v[168:171], v[120:123]
	v_mfma_f32_16x16x32_bf16 v[112:115], v[148:151], v[176:179], v[112:115]
	v_mfma_f32_16x16x32_bf16 v[104:107], v[160:163], v[176:179], v[104:107]
	v_mfma_f32_16x16x32_bf16 v[96:99], v[148:151], v[184:187], v[96:99]
	v_mfma_f32_16x16x32_bf16 v[88:91], v[160:163], v[184:187], v[88:91]
	v_mfma_f32_16x16x32_bf16 v[80:83], v[148:151], v[192:195], v[80:83]
	v_mfma_f32_16x16x32_bf16 v[72:75], v[160:163], v[192:195], v[72:75]
	v_mfma_f32_16x16x32_bf16 v[124:127], v[152:155], v[172:175], v[124:127]
	v_mfma_f32_16x16x32_bf16 v[120:123], v[164:167], v[172:175], v[120:123]
	v_mfma_f32_16x16x32_bf16 v[112:115], v[152:155], v[180:183], v[112:115]
	v_mfma_f32_16x16x32_bf16 v[104:107], v[164:167], v[180:183], v[104:107]
	v_mfma_f32_16x16x32_bf16 v[96:99], v[152:155], v[188:191], v[96:99]
	v_mfma_f32_16x16x32_bf16 v[88:91], v[164:167], v[188:191], v[88:91]
	v_mfma_f32_16x16x32_bf16 v[80:83], v[152:155], v[196:199], v[80:83]
	v_mfma_f32_16x16x32_bf16 v[72:75], v[164:167], v[196:199], v[72:75]
	s_barrier
	s_add_i32 s70, s58, s23
	s_add_u32 s98, s52, s6
	s_addc_u32 s99, s53, s7
	s_mov_b32 m0, s70
	ds_read_b128 v[200:203], v147
	ds_read_b128 v[204:207], v147 offset:1024
	ds_read_b128 v[208:211], v147 offset:2048
	global_load_lds_dwordx4 v132, s[52:53]
	s_add_i32 m0, s70, 0x2000
	ds_read_b128 v[212:215], v147 offset:3072
	global_load_lds_dwordx4 v128, s[52:53]
	s_barrier
	s_waitcnt lgkmcnt(0)
	v_mfma_f32_16x16x32_bf16 v[116:119], v[200:203], v[168:171], v[116:119]
	v_mfma_f32_16x16x32_bf16 v[108:111], v[208:211], v[168:171], v[108:111]
	v_mfma_f32_16x16x32_bf16 v[100:103], v[200:203], v[176:179], v[100:103]
	v_mfma_f32_16x16x32_bf16 v[92:95], v[208:211], v[176:179], v[92:95]
	v_mfma_f32_16x16x32_bf16 v[84:87], v[200:203], v[184:187], v[84:87]
	v_mfma_f32_16x16x32_bf16 v[76:79], v[208:211], v[184:187], v[76:79]
	v_mfma_f32_16x16x32_bf16 v[68:71], v[200:203], v[192:195], v[68:71]
	v_mfma_f32_16x16x32_bf16 v[64:67], v[208:211], v[192:195], v[64:67]
	v_mfma_f32_16x16x32_bf16 v[116:119], v[204:207], v[172:175], v[116:119]
	v_mfma_f32_16x16x32_bf16 v[108:111], v[212:215], v[172:175], v[108:111]
	v_mfma_f32_16x16x32_bf16 v[100:103], v[204:207], v[180:183], v[100:103]
	v_mfma_f32_16x16x32_bf16 v[92:95], v[212:215], v[180:183], v[92:95]
	v_mfma_f32_16x16x32_bf16 v[84:87], v[204:207], v[188:191], v[84:87]
	v_mfma_f32_16x16x32_bf16 v[76:79], v[212:215], v[188:191], v[76:79]
	v_mfma_f32_16x16x32_bf16 v[68:71], v[204:207], v[196:199], v[68:71]
	v_mfma_f32_16x16x32_bf16 v[64:67], v[212:215], v[196:199], v[64:67]
	s_mov_b32 m0, s28
	s_add_u32 s100, s54, s6
	s_addc_u32 s101, s55, s7
	s_barrier
	ds_read_b128 v[168:171], v146 offset:16384
	ds_read_b128 v[172:175], v146 offset:17408
	ds_read_b128 v[176:179], v146 offset:18432
	ds_read_b128 v[180:183], v146 offset:19456
	ds_read_b128 v[184:187], v146 offset:20480
	ds_read_b128 v[188:191], v146 offset:21504
	ds_read_b128 v[192:195], v146 offset:22528
	global_load_lds_dwordx4 v134, s[54:55]
	s_mov_b32 m0, s29
	ds_read_b128 v[196:199], v146 offset:23552
	global_load_lds_dwordx4 v130, s[54:55]
	s_barrier
	s_waitcnt lgkmcnt(0)
	v_mfma_f32_16x16x32_bf16 v[60:63], v[148:151], v[168:171], v[60:63]
	v_mfma_f32_16x16x32_bf16 v[56:59], v[160:163], v[168:171], v[56:59]
	v_mfma_f32_16x16x32_bf16 v[52:55], v[148:151], v[176:179], v[52:55]
	v_mfma_f32_16x16x32_bf16 v[44:47], v[160:163], v[176:179], v[44:47]
	v_mfma_f32_16x16x32_bf16 v[36:39], v[148:151], v[184:187], v[36:39]
	v_mfma_f32_16x16x32_bf16 v[28:31], v[160:163], v[184:187], v[28:31]
	v_mfma_f32_16x16x32_bf16 v[20:23], v[148:151], v[192:195], v[20:23]
	v_mfma_f32_16x16x32_bf16 v[12:15], v[160:163], v[192:195], v[12:15]
	v_mfma_f32_16x16x32_bf16 v[60:63], v[152:155], v[172:175], v[60:63]
	v_mfma_f32_16x16x32_bf16 v[56:59], v[164:167], v[172:175], v[56:59]
	v_mfma_f32_16x16x32_bf16 v[52:55], v[152:155], v[180:183], v[52:55]
	v_mfma_f32_16x16x32_bf16 v[44:47], v[164:167], v[180:183], v[44:47]
	v_mfma_f32_16x16x32_bf16 v[36:39], v[152:155], v[188:191], v[36:39]
	v_mfma_f32_16x16x32_bf16 v[28:31], v[164:167], v[188:191], v[28:31]
	v_mfma_f32_16x16x32_bf16 v[20:23], v[152:155], v[196:199], v[20:23]
	v_mfma_f32_16x16x32_bf16 v[12:15], v[164:167], v[196:199], v[12:15]
	s_barrier
	s_add_u32 s70, s52, 0x80000
	s_addc_u32 s71, s53, 0
	s_add_i32 s72, s59, s23
	s_mov_b32 m0, s72
	s_nop 0
	global_load_lds_dwordx4 v132, s[70:71]
	s_add_i32 m0, s72, 0x2000
	s_nop 0
	global_load_lds_dwordx4 v128, s[70:71]
	s_waitcnt vmcnt(6)
	s_barrier
; #define PG8_STAGE(bufoff, gbase, voff) do { _Pragma("unroll") for (int _i = 0; _i < 2; ++_i) \
;         __builtin_amdgcn_global_load_lds((const unsigned*)((const char*)(gbase) + (voff)[_i]), (LAS unsigned*)(lds + (bufoff) + ldsw + _i * 8192), 16, 0, 0); } while (0)
; #define PG8_LDA(dst, b, h) do { _Pragma("unroll") for (int m = 0; m < 4; ++m) _Pragma("unroll") for (int k = 0; k < 2; ++k) dst[m][k] = *(const LAS bf16x8*)(lds + PG8_SA(b, h) + aoff + m * 2048 + k * 1024); } while (0)
; #define PG8_LDB(dst, b, h) do { _Pragma("unroll") for (int n = 0; n < 2; ++n) _Pragma("unroll") for (int k = 0; k < 2; ++k) dst[n][k] = *(const LAS bf16x8*)(lds + PG8_SB(b, h) + boff + n * 2048 + k * 1024); } while (0)
; #define PG8_MMA(ai, bj, At, Bt) do { __builtin_amdgcn_s_setprio(1); _Pragma("unroll") for (int m = 0; m < 4; ++m) _Pragma("unroll") for (int n = 0; n < 2; ++n) _Pragma("unroll") for (int k = 0; k < 2; ++k) \
;         acc[ai][bj][m][n] = __builtin_amdgcn_mfma_f32_16x16x32_bf16(Bt[n][k], At[m][k], acc[ai][bj][m][n], 0, 0, 0); __builtin_amdgcn_s_setprio(0); } while (0)
; #define PG8_WAIT_V(n) asm volatile("s_waitcnt vmcnt(" #n ")" ::: "memory")
; #define PG8_WAIT_L(n) asm volatile("s_waitcnt lgkmcnt(" #n ")" ::: "memory")
; #define PG8_BAR __builtin_amdgcn_s_barrier()
; #define PG8_SCHED __builtin_amdgcn_sched_barrier(0)
; template <class Epi>
; __device__ __forceinline__ void gemm_phase(LAS unsigned char* lds, const Gemm g, const StaticOrder& S, const Epi& E) {
;     ...
;             PG8_WAIT_V(6); PG8_BAR; PG8_MMA(1, 1, At, B1); PG8_BAR;
;             PG8_LDB(B0, 1, 0); PG8_SCHED; PG8_LDA(At, 1, 0); PG8_STAGE(PG8_SA(0, 1), a2 + hstep, voffA);
;             PG8_WAIT_L(8); PG8_BAR; PG8_WAIT_L(0); PG8_MMA(0, 0, At, B0); PG8_BAR; PG8_SCHED;
;             PG8_LDB(B1, 1, 1); PG8_STAGE(PG8_SB(1, 0), b3, voffB);
;             PG8_BAR; PG8_WAIT_L(0); PG8_MMA(0, 1, At, B1); PG8_BAR;
;             PG8_LDA(At, 1, 1); PG8_STAGE(PG8_SA(1, 0), a3, voffA);
;             PG8_BAR; PG8_WAIT_L(0); PG8_MMA(1, 0, At, B0); PG8_BAR; PG8_SCHED;
	v_mfma_f32_16x16x32_bf16 v[48:51], v[200:203], v[168:171], v[48:51]
	v_mfma_f32_16x16x32_bf16 v[40:43], v[208:211], v[168:171], v[40:43]
	v_mfma_f32_16x16x32_bf16 v[32:35], v[200:203], v[176:179], v[32:35]
	v_mfma_f32_16x16x32_bf16 v[24:27], v[208:211], v[176:179], v[24:27]
	v_mfma_f32_16x16x32_bf16 v[16:19], v[200:203], v[184:187], v[16:19]
	v_mfma_f32_16x16x32_bf16 v[8:11], v[208:211], v[184:187], v[8:11]
	v_mfma_f32_16x16x32_bf16 v[4:7], v[200:203], v[192:195], v[4:7]
	v_mfma_f32_16x16x32_bf16 v[0:3], v[208:211], v[192:195], v[0:3]
	v_mfma_f32_16x16x32_bf16 v[48:51], v[204:207], v[172:175], v[48:51]
	v_mfma_f32_16x16x32_bf16 v[40:43], v[212:215], v[172:175], v[40:43]
	v_mfma_f32_16x16x32_bf16 v[32:35], v[204:207], v[180:183], v[32:35]
	v_mfma_f32_16x16x32_bf16 v[24:27], v[212:215], v[180:183], v[24:27]
	v_mfma_f32_16x16x32_bf16 v[16:19], v[204:207], v[188:191], v[16:19]
	v_mfma_f32_16x16x32_bf16 v[8:11], v[212:215], v[188:191], v[8:11]
	v_mfma_f32_16x16x32_bf16 v[4:7], v[204:207], v[196:199], v[4:7]
	v_mfma_f32_16x16x32_bf16 v[0:3], v[212:215], v[196:199], v[0:3]
	s_add_i32 s70, 0, 0x18000
	v_add_u32_e32 v164, s70, v143
	s_barrier
	ds_read_b128 v[148:151], v164
	ds_read_b128 v[152:155], v164 offset:1024
	ds_read_b128 v[160:163], v164 offset:2048
	ds_read_b128 v[164:167], v164 offset:3072
	s_add_u32 s54, s54, 0x80000
	s_addc_u32 s55, s55, 0
	s_mov_b32 m0, s33
	ds_read_b128 v[168:171], v146 offset:32768
	ds_read_b128 v[172:175], v146 offset:33792
	ds_read_b128 v[176:179], v146 offset:34816
	ds_read_b128 v[180:183], v146 offset:35840
	ds_read_b128 v[184:187], v146 offset:36864
	ds_read_b128 v[188:191], v146 offset:37888
	ds_read_b128 v[192:195], v146 offset:38912
	global_load_lds_dwordx4 v134, s[54:55]
	s_mov_b32 m0, s36
	ds_read_b128 v[196:199], v146 offset:39936
	global_load_lds_dwordx4 v130, s[54:55]
	s_waitcnt lgkmcnt(8)
	s_barrier
	s_waitcnt lgkmcnt(0)
	v_mfma_f32_16x16x32_bf16 v[124:127], v[148:151], v[168:171], v[124:127]
	v_mfma_f32_16x16x32_bf16 v[120:123], v[160:163], v[168:171], v[120:123]
	v_mfma_f32_16x16x32_bf16 v[112:115], v[148:151], v[176:179], v[112:115]
	v_mfma_f32_16x16x32_bf16 v[104:107], v[160:163], v[176:179], v[104:107]
	v_mfma_f32_16x16x32_bf16 v[96:99], v[148:151], v[184:187], v[96:99]
	v_mfma_f32_16x16x32_bf16 v[88:91], v[160:163], v[184:187], v[88:91]
	v_mfma_f32_16x16x32_bf16 v[80:83], v[148:151], v[192:195], v[80:83]
	v_mfma_f32_16x16x32_bf16 v[72:75], v[160:163], v[192:195], v[72:75]
	v_mfma_f32_16x16x32_bf16 v[124:127], v[152:155], v[172:175], v[124:127]
	v_mfma_f32_16x16x32_bf16 v[120:123], v[164:167], v[172:175], v[120:123]
	v_mfma_f32_16x16x32_bf16 v[112:115], v[152:155], v[180:183], v[112:115]
	v_mfma_f32_16x16x32_bf16 v[104:107], v[164:167], v[180:183], v[104:107]
	v_mfma_f32_16x16x32_bf16 v[96:99], v[152:155], v[188:191], v[96:99]
	v_mfma_f32_16x16x32_bf16 v[88:91], v[164:167], v[188:191], v[88:91]
	v_mfma_f32_16x16x32_bf16 v[80:83], v[152:155], v[196:199], v[80:83]
	v_mfma_f32_16x16x32_bf16 v[72:75], v[164:167], v[196:199], v[72:75]
	s_barrier
	s_add_i32 s54, 0, 0x1c000
	s_add_i32 s55, s70, s23
	v_add_u32_e32 v212, s54, v143
	s_mov_b32 m0, s55
	ds_read_b128 v[200:203], v212
	ds_read_b128 v[204:207], v212 offset:1024
	ds_read_b128 v[208:211], v212 offset:2048
	global_load_lds_dwordx4 v132, s[98:99]
	s_add_i32 m0, s55, 0x2000
	ds_read_b128 v[212:215], v212 offset:3072
	global_load_lds_dwordx4 v128, s[98:99]
	s_barrier
	s_waitcnt lgkmcnt(0)
	v_mfma_f32_16x16x32_bf16 v[116:119], v[200:203], v[168:171], v[116:119]
	v_mfma_f32_16x16x32_bf16 v[108:111], v[208:211], v[168:171], v[108:111]
	v_mfma_f32_16x16x32_bf16 v[100:103], v[200:203], v[176:179], v[100:103]
	v_mfma_f32_16x16x32_bf16 v[92:95], v[208:211], v[176:179], v[92:95]
	v_mfma_f32_16x16x32_bf16 v[84:87], v[200:203], v[184:187], v[84:87]
	v_mfma_f32_16x16x32_bf16 v[76:79], v[208:211], v[184:187], v[76:79]
	v_mfma_f32_16x16x32_bf16 v[68:71], v[200:203], v[192:195], v[68:71]
	v_mfma_f32_16x16x32_bf16 v[64:67], v[208:211], v[192:195], v[64:67]
	v_mfma_f32_16x16x32_bf16 v[116:119], v[204:207], v[172:175], v[116:119]
	v_mfma_f32_16x16x32_bf16 v[108:111], v[212:215], v[172:175], v[108:111]
	v_mfma_f32_16x16x32_bf16 v[100:103], v[204:207], v[180:183], v[100:103]
	v_mfma_f32_16x16x32_bf16 v[92:95], v[212:215], v[180:183], v[92:95]
	v_mfma_f32_16x16x32_bf16 v[84:87], v[204:207], v[188:191], v[84:87]
	v_mfma_f32_16x16x32_bf16 v[76:79], v[212:215], v[188:191], v[76:79]
	v_mfma_f32_16x16x32_bf16 v[68:71], v[204:207], v[196:199], v[68:71]
	v_mfma_f32_16x16x32_bf16 v[64:67], v[212:215], v[196:199], v[64:67]
	s_mov_b32 m0, s49
	s_barrier
	ds_read_b128 v[168:171], v146 offset:49152
	ds_read_b128 v[172:175], v146 offset:50176
	ds_read_b128 v[176:179], v146 offset:51200
	ds_read_b128 v[180:183], v146 offset:52224
	ds_read_b128 v[184:187], v146 offset:53248
	ds_read_b128 v[188:191], v146 offset:54272
	ds_read_b128 v[192:195], v146 offset:55296
	global_load_lds_dwordx4 v134, s[100:101]
	s_mov_b32 m0, s56
	ds_read_b128 v[196:199], v146 offset:56320
	global_load_lds_dwordx4 v130, s[100:101]
	s_barrier
	s_waitcnt lgkmcnt(0)
	v_mfma_f32_16x16x32_bf16 v[60:63], v[148:151], v[168:171], v[60:63]
	v_mfma_f32_16x16x32_bf16 v[56:59], v[160:163], v[168:171], v[56:59]
	v_mfma_f32_16x16x32_bf16 v[52:55], v[148:151], v[176:179], v[52:55]
	v_mfma_f32_16x16x32_bf16 v[44:47], v[160:163], v[176:179], v[44:47]
	v_mfma_f32_16x16x32_bf16 v[36:39], v[148:151], v[184:187], v[36:39]
	v_mfma_f32_16x16x32_bf16 v[28:31], v[160:163], v[184:187], v[28:31]
	v_mfma_f32_16x16x32_bf16 v[20:23], v[148:151], v[192:195], v[20:23]
	v_mfma_f32_16x16x32_bf16 v[12:15], v[160:163], v[192:195], v[12:15]
	v_mfma_f32_16x16x32_bf16 v[60:63], v[152:155], v[172:175], v[60:63]
	v_mfma_f32_16x16x32_bf16 v[56:59], v[164:167], v[172:175], v[56:59]
	v_mfma_f32_16x16x32_bf16 v[52:55], v[152:155], v[180:183], v[52:55]
	v_mfma_f32_16x16x32_bf16 v[44:47], v[164:167], v[180:183], v[44:47]
	v_mfma_f32_16x16x32_bf16 v[36:39], v[152:155], v[188:191], v[36:39]
	v_mfma_f32_16x16x32_bf16 v[28:31], v[164:167], v[188:191], v[28:31]
	v_mfma_f32_16x16x32_bf16 v[20:23], v[152:155], v[196:199], v[20:23]
	v_mfma_f32_16x16x32_bf16 v[12:15], v[164:167], v[196:199], v[12:15]
	s_barrier
; #define PG8_STAGE(bufoff, gbase, voff) do { _Pragma("unroll") for (int _i = 0; _i < 2; ++_i) \
;         __builtin_amdgcn_global_load_lds((const unsigned*)((const char*)(gbase) + (voff)[_i]), (LAS unsigned*)(lds + (bufoff) + ldsw + _i * 8192), 16, 0, 0); } while (0)
; #define PG8_MMA(ai, bj, At, Bt) do { __builtin_amdgcn_s_setprio(1); _Pragma("unroll") for (int m = 0; m < 4; ++m) _Pragma("unroll") for (int n = 0; n < 2; ++n) _Pragma("unroll") for (int k = 0; k < 2; ++k) \
;         acc[ai][bj][m][n] = __builtin_amdgcn_mfma_f32_16x16x32_bf16(Bt[n][k], At[m][k], acc[ai][bj][m][n], 0, 0, 0); __builtin_amdgcn_s_setprio(0); } while (0)
; #define PG8_WAIT_V(n) asm volatile("s_waitcnt vmcnt(" #n ")" ::: "memory")
; #define PG8_BAR __builtin_amdgcn_s_barrier()
; __device__ __forceinline__ u32x4 pack8(f32x4 v0, f32x4 v1) { u32x4 w; w.x = cvt_pk_bf16(v0[0], v0[1]); w.y = cvt_pk_bf16(v0[2], v0[3]); w.z = cvt_pk_bf16(v1[0], v1[1]); w.w = cvt_pk_bf16(v1[2], v1[3]); return w; }
; template <class Epi>
; __device__ __forceinline__ void gemm_phase(LAS unsigned char* lds, const Gemm g, const StaticOrder& S, const Epi& E) {
;     ...
;             PG8_STAGE(PG8_SB(1, 1), b3 + hstep, voffB);
;             PG8_WAIT_V(6); PG8_BAR; PG8_MMA(1, 1, At, B1); PG8_BAR;
;         }
;         E(acc, cur, wr, wc, fr, fq);
;         if (!has_next) break;
;     __device__ __forceinline__ void operator()(const f32x4 (&acc)[2][2][4][2], const Unit& u, int wr, int wc, int fr, int fq) const {
;         const int row0 = u.pm * BM + wr * 64 + fr, col0 = u.pn * BM + wc * 32 + 8 * fq;
; #pragma unroll
;         for (int ai = 0; ai < 2; ++ai)
; #pragma unroll
;             for (int m = 0; m < 4; ++m) { bf16_t* rowp = O + (size_t)(row0 + ai * HALF + m * 16) * ldc + col0;
; #pragma unroll
;                 for (int bj = 0; bj < 2; ++bj) *(u32x4*)(rowp + bj * HALF) = pack8(acc[ai][bj][m][0], acc[ai][bj][m][1]); }
;     }
	s_add_u32 s52, s52, 0x80080
	s_addc_u32 s53, s53, 0
	s_add_i32 s54, s54, s23
	s_mov_b32 m0, s54
	s_nop 0
	global_load_lds_dwordx4 v132, s[52:53]
	s_add_i32 m0, s54, 0x2000
	s_nop 0
	global_load_lds_dwordx4 v128, s[52:53]
	s_waitcnt vmcnt(6)
	s_barrier
	v_mfma_f32_16x16x32_bf16 v[48:51], v[200:203], v[168:171], v[48:51]
	v_mfma_f32_16x16x32_bf16 v[40:43], v[208:211], v[168:171], v[40:43]
	v_mfma_f32_16x16x32_bf16 v[32:35], v[200:203], v[176:179], v[32:35]
	v_mfma_f32_16x16x32_bf16 v[24:27], v[208:211], v[176:179], v[24:27]
	v_mfma_f32_16x16x32_bf16 v[16:19], v[200:203], v[184:187], v[16:19]
	v_mfma_f32_16x16x32_bf16 v[8:11], v[208:211], v[184:187], v[8:11]
	v_mfma_f32_16x16x32_bf16 v[4:7], v[200:203], v[192:195], v[4:7]
	v_mfma_f32_16x16x32_bf16 v[0:3], v[208:211], v[192:195], v[0:3]
	v_mfma_f32_16x16x32_bf16 v[48:51], v[204:207], v[172:175], v[48:51]
	v_mfma_f32_16x16x32_bf16 v[40:43], v[212:215], v[172:175], v[40:43]
	v_mfma_f32_16x16x32_bf16 v[32:35], v[204:207], v[180:183], v[32:35]
	v_mfma_f32_16x16x32_bf16 v[24:27], v[212:215], v[180:183], v[24:27]
	v_mfma_f32_16x16x32_bf16 v[16:19], v[204:207], v[188:191], v[16:19]
	v_mfma_f32_16x16x32_bf16 v[8:11], v[212:215], v[188:191], v[8:11]
	v_mfma_f32_16x16x32_bf16 v[4:7], v[204:207], v[196:199], v[4:7]
	v_mfma_f32_16x16x32_bf16 v[0:3], v[212:215], v[196:199], v[0:3]
	s_add_i32 s69, s69, 2
	s_add_u32 s50, s50, 0x100
	s_addc_u32 s51, s51, 0
	s_add_u32 s67, s67, 0x100
	s_addc_u32 s68, s68, 0
	s_cmp_gt_u32 s69, 29
	s_barrier
	s_cbranch_scc0 .LBB0_673
	v_lshl_add_u32 v148, s48, 8, v142
	v_lshl_or_b32 v140, s64, 8, v144
	v_ashrrev_i32_e32 v149, 31, v148
	v_ashrrev_i32_e32 v141, 31, v140
	v_lshlrev_b64 v[150:151], 12, v[148:149]
	v_lshl_add_u64 v[150:151], s[24:25], 0, v[150:151]
	v_lshlrev_b64 v[152:153], 1, v[140:141]
	v_lshl_add_u64 v[140:141], v[150:151], 0, v[152:153]
	v_cvt_pk_bf16_f32 v124, v124, v125
	v_cvt_pk_bf16_f32 v125, v126, v127
	v_cvt_pk_bf16_f32 v126, v120, v121
	v_cvt_pk_bf16_f32 v127, v122, v123
	global_store_dwordx4 v[140:141], v[124:127], off
	v_cvt_pk_bf16_f32 v116, v116, v117
	v_cvt_pk_bf16_f32 v117, v118, v119
	v_cvt_pk_bf16_f32 v118, v108, v109
	v_or_b32_e32 v108, 16, v148
	v_ashrrev_i32_e32 v109, 31, v108
	v_lshlrev_b64 v[108:109], 12, v[108:109]
	v_lshl_add_u64 v[108:109], s[24:25], 0, v[108:109]
	v_cvt_pk_bf16_f32 v119, v110, v111
	global_store_dwordx4 v[140:141], v[116:119], off offset:256
	s_mov_b32 s64, s40
	s_mov_b32 s48, s42
	v_lshl_add_u64 v[116:117], v[108:109], 0, v[152:153]
	v_cvt_pk_bf16_f32 v108, v112, v113
	v_cvt_pk_bf16_f32 v109, v114, v115
	v_cvt_pk_bf16_f32 v110, v104, v105
	v_cvt_pk_bf16_f32 v111, v106, v107
	global_store_dwordx4 v[116:117], v[108:111], off
	v_cvt_pk_bf16_f32 v100, v100, v101
	v_cvt_pk_bf16_f32 v101, v102, v103
	v_cvt_pk_bf16_f32 v102, v92, v93
	v_or_b32_e32 v92, 32, v148
	v_ashrrev_i32_e32 v93, 31, v92
	v_lshlrev_b64 v[92:93], 12, v[92:93]
	v_lshl_add_u64 v[92:93], s[24:25], 0, v[92:93]
	v_cvt_pk_bf16_f32 v103, v94, v95
	global_store_dwordx4 v[116:117], v[100:103], off offset:256
	s_mov_b64 s[52:53], s[46:47]
	s_mov_b64 s[50:51], s[44:45]
	v_lshl_add_u64 v[100:101], v[92:93], 0, v[152:153]
	v_cvt_pk_bf16_f32 v92, v96, v97
	v_cvt_pk_bf16_f32 v93, v98, v99
	v_cvt_pk_bf16_f32 v94, v88, v89
	v_cvt_pk_bf16_f32 v95, v90, v91
	global_store_dwordx4 v[100:101], v[92:95], off
	v_cvt_pk_bf16_f32 v84, v84, v85
	v_cvt_pk_bf16_f32 v85, v86, v87
	v_cvt_pk_bf16_f32 v86, v76, v77
	v_or_b32_e32 v76, 48, v148
	v_ashrrev_i32_e32 v77, 31, v76
	v_lshlrev_b64 v[76:77], 12, v[76:77]
	v_lshl_add_u64 v[76:77], s[24:25], 0, v[76:77]
	v_cvt_pk_bf16_f32 v87, v78, v79
	global_store_dwordx4 v[100:101], v[84:87], off offset:256
	s_nop 1
	v_lshl_add_u64 v[84:85], v[76:77], 0, v[152:153]
	v_cvt_pk_bf16_f32 v76, v80, v81
	v_cvt_pk_bf16_f32 v77, v82, v83
	v_cvt_pk_bf16_f32 v78, v72, v73
	v_cvt_pk_bf16_f32 v79, v74, v75
	global_store_dwordx4 v[84:85], v[76:79], off
	v_cvt_pk_bf16_f32 v68, v68, v69
	v_cvt_pk_bf16_f32 v69, v70, v71
	v_cvt_pk_bf16_f32 v70, v64, v65
	v_cvt_pk_bf16_f32 v71, v66, v67
	global_store_dwordx4 v[84:85], v[68:71], off offset:256
	v_cvt_pk_bf16_f32 v60, v60, v61
	v_cvt_pk_bf16_f32 v61, v62, v63
	v_cvt_pk_bf16_f32 v62, v56, v57
	v_add_co_u32_e32 v56, vcc, s60, v140
	v_lshl_add_u64 v[64:65], v[140:141], 0, s[2:3]
	s_nop 0
	v_addc_co_u32_e32 v57, vcc, 0, v141, vcc
	v_cvt_pk_bf16_f32 v63, v58, v59
	global_store_dwordx4 v[56:57], v[60:63], off
	v_cvt_pk_bf16_f32 v48, v48, v49
	v_cvt_pk_bf16_f32 v49, v50, v51
	v_cvt_pk_bf16_f32 v50, v40, v41
	v_cvt_pk_bf16_f32 v51, v42, v43
	global_store_dwordx4 v[64:65], v[48:51], off offset:256
	v_cvt_pk_bf16_f32 v40, v52, v53
	v_cvt_pk_bf16_f32 v41, v54, v55
	v_cvt_pk_bf16_f32 v42, v44, v45
	v_add_co_u32_e32 v44, vcc, s61, v140
	s_nop 0
	v_lshl_add_u64 v[48:49], v[140:141], 0, s[8:9]
	v_addc_co_u32_e32 v45, vcc, 0, v141, vcc
	v_cvt_pk_bf16_f32 v43, v46, v47
	global_store_dwordx4 v[44:45], v[40:43], off
	v_cvt_pk_bf16_f32 v32, v32, v33
	v_cvt_pk_bf16_f32 v33, v34, v35
	v_cvt_pk_bf16_f32 v34, v24, v25
	v_cvt_pk_bf16_f32 v35, v26, v27
	global_store_dwordx4 v[48:49], v[32:35], off offset:256
	v_cvt_pk_bf16_f32 v24, v36, v37
	v_cvt_pk_bf16_f32 v25, v38, v39
	v_cvt_pk_bf16_f32 v26, v28, v29
	v_add_co_u32_e32 v28, vcc, s62, v140
	s_nop 0
	v_lshl_add_u64 v[32:33], v[140:141], 0, s[30:31]
	v_addc_co_u32_e32 v29, vcc, 0, v141, vcc
	v_cvt_pk_bf16_f32 v27, v30, v31
	global_store_dwordx4 v[28:29], v[24:27], off
	v_cvt_pk_bf16_f32 v16, v16, v17
	v_cvt_pk_bf16_f32 v17, v18, v19
	v_cvt_pk_bf16_f32 v18, v8, v9
	v_cvt_pk_bf16_f32 v19, v10, v11
	global_store_dwordx4 v[32:33], v[16:19], off offset:256
	v_cvt_pk_bf16_f32 v8, v20, v21
	v_cvt_pk_bf16_f32 v9, v22, v23
	v_cvt_pk_bf16_f32 v10, v12, v13
	v_add_co_u32_e32 v12, vcc, s63, v140
	s_nop 0
	v_lshl_add_u64 v[16:17], v[140:141], 0, s[34:35]
	v_addc_co_u32_e32 v13, vcc, 0, v141, vcc
	s_and_b64 vcc, exec, s[38:39]
	v_cvt_pk_bf16_f32 v11, v14, v15
	global_store_dwordx4 v[12:13], v[8:11], off
	v_cvt_pk_bf16_f32 v4, v4, v5
	v_cvt_pk_bf16_f32 v5, v6, v7
	v_cvt_pk_bf16_f32 v6, v0, v1
	v_cvt_pk_bf16_f32 v7, v2, v3
	global_store_dwordx4 v[16:17], v[4:7], off offset:256
	s_cbranch_vccz .LBB0_670
	s_waitcnt vmcnt(0)
	s_cmpk_gt_u32 s10, 0xff
	v_readlane_b32 s62, v232, 20
	v_readlane_b32 s61, v232, 21
	s_cbranch_scc1 .LBB0_677
	s_barrier

; #define PG8_STAGE(bufoff, gbase, voff) do { _Pragma("unroll") for (int _i = 0; _i < 2; ++_i) \
;         __builtin_amdgcn_global_load_lds((const unsigned*)((const char*)(gbase) + (voff)[_i]), (LAS unsigned*)(lds + (bufoff) + ldsw + _i * 8192), 16, 0, 0); } while (0)
; #define PG8_LDA(dst, b, h) do { _Pragma("unroll") for (int m = 0; m < 4; ++m) _Pragma("unroll") for (int k = 0; k < 2; ++k) dst[m][k] = *(const LAS bf16x8*)(lds + PG8_SA(b, h) + aoff + m * 2048 + k * 1024); } while (0)
; #define PG8_LDB(dst, b, h) do { _Pragma("unroll") for (int n = 0; n < 2; ++n) _Pragma("unroll") for (int k = 0; k < 2; ++k) dst[n][k] = *(const LAS bf16x8*)(lds + PG8_SB(b, h) + boff + n * 2048 + k * 1024); } while (0)
; #define PG8_MMA(ai, bj, At, Bt) do { __builtin_amdgcn_s_setprio(1); _Pragma("unroll") for (int m = 0; m < 4; ++m) _Pragma("unroll") for (int n = 0; n < 2; ++n) _Pragma("unroll") for (int k = 0; k < 2; ++k) \
;         acc[ai][bj][m][n] = __builtin_amdgcn_mfma_f32_16x16x32_bf16(Bt[n][k], At[m][k], acc[ai][bj][m][n], 0, 0, 0); __builtin_amdgcn_s_setprio(0); } while (0)
; #define PG8_WAIT_V(n) asm volatile("s_waitcnt vmcnt(" #n ")" ::: "memory")
; #define PG8_WAIT_L(n) asm volatile("s_waitcnt lgkmcnt(" #n ")" ::: "memory")
; template <class Epi>
; __device__ __forceinline__ void gemm_phase(LAS unsigned char* lds, const Gemm g, const StaticOrder& S, const Epi& E) {
;     ...
;         for (int t = 0; t < nt; t += 2) {
;             const bool last = (t == nt - 2);
;             const char* a1 = cA + (size_t)(t + 1) * kstep;
;             const char* a2 = last ? nA : cA + (size_t)(t + 2) * kstep; const char* b2 = last ? nB : cB + (size_t)(t + 2) * kstep;
;             const char* a3 = a2 + kstep; const char* b3 = b2 + kstep;
;             PG8_LDB(B0, 0, 0); PG8_SCHED; PG8_LDA(At, 0, 0); PG8_STAGE(PG8_SA(1, 1), a1 + hstep, voffA);
;             PG8_WAIT_L(8); PG8_BAR; PG8_WAIT_L(0); PG8_MMA(0, 0, At, B0); PG8_BAR; PG8_SCHED;
;             PG8_LDB(B1, 0, 1); PG8_STAGE(PG8_SB(0, 0), b2, voffB);
;             PG8_BAR; PG8_WAIT_L(0); PG8_MMA(0, 1, At, B1); PG8_BAR;
;             PG8_LDA(At, 0, 1); PG8_STAGE(PG8_SA(0, 0), a2, voffA);
;             PG8_BAR; PG8_WAIT_L(0); PG8_MMA(1, 0, At, B0); PG8_BAR; PG8_SCHED;
;             PG8_STAGE(PG8_SB(0, 1), b2 + hstep, voffB);
;             PG8_WAIT_V(6); PG8_BAR; PG8_MMA(1, 1, At, B1); PG8_BAR;
.LBB0_796:
	ds_read_b128 v[144:147], v155
	ds_read_b128 v[148:151], v155 offset:1024
	ds_read_b128 v[160:163], v155 offset:2048
	ds_read_b128 v[164:167], v155 offset:3072
	s_add_u32 s42, s40, 0xfff80080
	s_addc_u32 s43, s41, -1
	s_cmp_eq_u32 s58, 28
	s_cselect_b32 s45, s31, s43
	s_cselect_b32 s44, s54, s42
	s_cselect_b32 s43, s9, s57
	s_cselect_b32 s42, s55, s56
	s_add_i32 m0, s27, 0xc000
	ds_read_b128 v[168:171], v156
	ds_read_b128 v[172:175], v156 offset:1024
	ds_read_b128 v[176:179], v156 offset:2048
	ds_read_b128 v[180:183], v156 offset:3072
	ds_read_b128 v[184:187], v156 offset:4096
	ds_read_b128 v[188:191], v156 offset:5120
	ds_read_b128 v[192:195], v156 offset:6144
	global_load_lds_dwordx4 v136, s[40:41]
	s_add_i32 m0, s27, 0xe000
	ds_read_b128 v[196:199], v156 offset:7168
	global_load_lds_dwordx4 v138, s[40:41]
	s_waitcnt lgkmcnt(8)
	s_barrier
	s_waitcnt lgkmcnt(0)
	v_mfma_f32_16x16x32_bf16 v[124:127], v[144:147], v[168:171], v[124:127]
	v_mfma_f32_16x16x32_bf16 v[120:123], v[160:163], v[168:171], v[120:123]
	v_mfma_f32_16x16x32_bf16 v[108:111], v[144:147], v[176:179], v[108:111]
	v_mfma_f32_16x16x32_bf16 v[104:107], v[160:163], v[176:179], v[104:107]
	v_mfma_f32_16x16x32_bf16 v[92:95], v[144:147], v[184:187], v[92:95]
	v_mfma_f32_16x16x32_bf16 v[88:91], v[160:163], v[184:187], v[88:91]
	v_mfma_f32_16x16x32_bf16 v[76:79], v[144:147], v[192:195], v[76:79]
	v_mfma_f32_16x16x32_bf16 v[72:75], v[160:163], v[192:195], v[72:75]
	v_mfma_f32_16x16x32_bf16 v[124:127], v[148:151], v[172:175], v[124:127]
	v_mfma_f32_16x16x32_bf16 v[120:123], v[164:167], v[172:175], v[120:123]
	v_mfma_f32_16x16x32_bf16 v[108:111], v[148:151], v[180:183], v[108:111]
	v_mfma_f32_16x16x32_bf16 v[104:107], v[164:167], v[180:183], v[104:107]
	v_mfma_f32_16x16x32_bf16 v[92:95], v[148:151], v[188:191], v[92:95]
	v_mfma_f32_16x16x32_bf16 v[88:91], v[164:167], v[188:191], v[88:91]
	v_mfma_f32_16x16x32_bf16 v[76:79], v[148:151], v[196:199], v[76:79]
	v_mfma_f32_16x16x32_bf16 v[72:75], v[164:167], v[196:199], v[72:75]
	s_barrier
	s_add_i32 s59, s50, s23
	s_add_u32 s98, s42, s2
	s_addc_u32 s99, s43, s3
	s_mov_b32 m0, s59
	ds_read_b128 v[200:203], v157
	ds_read_b128 v[204:207], v157 offset:1024
	ds_read_b128 v[208:211], v157 offset:2048
	global_load_lds_dwordx4 v132, s[42:43]
	s_add_i32 m0, s59, 0x2000
	ds_read_b128 v[212:215], v157 offset:3072
	global_load_lds_dwordx4 v128, s[42:43]
	s_barrier
	s_waitcnt lgkmcnt(0)
	v_mfma_f32_16x16x32_bf16 v[116:119], v[200:203], v[168:171], v[116:119]
	v_mfma_f32_16x16x32_bf16 v[112:115], v[208:211], v[168:171], v[112:115]
	v_mfma_f32_16x16x32_bf16 v[100:103], v[200:203], v[176:179], v[100:103]
	v_mfma_f32_16x16x32_bf16 v[96:99], v[208:211], v[176:179], v[96:99]
	v_mfma_f32_16x16x32_bf16 v[84:87], v[200:203], v[184:187], v[84:87]
	v_mfma_f32_16x16x32_bf16 v[80:83], v[208:211], v[184:187], v[80:83]
	v_mfma_f32_16x16x32_bf16 v[68:71], v[200:203], v[192:195], v[68:71]
	v_mfma_f32_16x16x32_bf16 v[64:67], v[208:211], v[192:195], v[64:67]
	v_mfma_f32_16x16x32_bf16 v[116:119], v[204:207], v[172:175], v[116:119]
	v_mfma_f32_16x16x32_bf16 v[112:115], v[212:215], v[172:175], v[112:115]
	v_mfma_f32_16x16x32_bf16 v[100:103], v[204:207], v[180:183], v[100:103]
	v_mfma_f32_16x16x32_bf16 v[96:99], v[212:215], v[180:183], v[96:99]
	v_mfma_f32_16x16x32_bf16 v[84:87], v[204:207], v[188:191], v[84:87]
	v_mfma_f32_16x16x32_bf16 v[80:83], v[212:215], v[188:191], v[80:83]
	v_mfma_f32_16x16x32_bf16 v[68:71], v[204:207], v[196:199], v[68:71]
	v_mfma_f32_16x16x32_bf16 v[64:67], v[212:215], v[196:199], v[64:67]
	s_mov_b32 m0, s27
	s_add_u32 s100, s44, s2
	s_addc_u32 s101, s45, s3
	s_barrier
	ds_read_b128 v[168:171], v156 offset:16384
	ds_read_b128 v[172:175], v156 offset:17408
	ds_read_b128 v[176:179], v156 offset:18432
	ds_read_b128 v[180:183], v156 offset:19456
	ds_read_b128 v[184:187], v156 offset:20480
	ds_read_b128 v[188:191], v156 offset:21504
	ds_read_b128 v[192:195], v156 offset:22528
	global_load_lds_dwordx4 v134, s[44:45]
	s_mov_b32 m0, s28
	ds_read_b128 v[196:199], v156 offset:23552
	global_load_lds_dwordx4 v130, s[44:45]
	s_barrier
	s_waitcnt lgkmcnt(0)
	v_mfma_f32_16x16x32_bf16 v[60:63], v[144:147], v[168:171], v[60:63]
	v_mfma_f32_16x16x32_bf16 v[56:59], v[160:163], v[168:171], v[56:59]
	v_mfma_f32_16x16x32_bf16 v[44:47], v[144:147], v[176:179], v[44:47]
	v_mfma_f32_16x16x32_bf16 v[40:43], v[160:163], v[176:179], v[40:43]
	v_mfma_f32_16x16x32_bf16 v[28:31], v[144:147], v[184:187], v[28:31]
	v_mfma_f32_16x16x32_bf16 v[24:27], v[160:163], v[184:187], v[24:27]
	v_mfma_f32_16x16x32_bf16 v[12:15], v[144:147], v[192:195], v[12:15]
	v_mfma_f32_16x16x32_bf16 v[8:11], v[160:163], v[192:195], v[8:11]
	v_mfma_f32_16x16x32_bf16 v[60:63], v[148:151], v[172:175], v[60:63]
	v_mfma_f32_16x16x32_bf16 v[56:59], v[164:167], v[172:175], v[56:59]
	v_mfma_f32_16x16x32_bf16 v[44:47], v[148:151], v[180:183], v[44:47]
	v_mfma_f32_16x16x32_bf16 v[40:43], v[164:167], v[180:183], v[40:43]
	v_mfma_f32_16x16x32_bf16 v[28:31], v[148:151], v[188:191], v[28:31]
	v_mfma_f32_16x16x32_bf16 v[24:27], v[164:167], v[188:191], v[24:27]
	v_mfma_f32_16x16x32_bf16 v[12:15], v[148:151], v[196:199], v[12:15]
	v_mfma_f32_16x16x32_bf16 v[8:11], v[164:167], v[196:199], v[8:11]
	s_barrier
	s_add_u32 s60, s42, 0x80000
	s_addc_u32 s61, s43, 0
	s_add_i32 s59, s51, s23
	s_mov_b32 m0, s59
	s_nop 0
	global_load_lds_dwordx4 v132, s[60:61]
	s_add_i32 m0, s59, 0x2000
	s_nop 0
	global_load_lds_dwordx4 v128, s[60:61]
	s_waitcnt vmcnt(6)
	s_barrier
; #define PG8_STAGE(bufoff, gbase, voff) do { _Pragma("unroll") for (int _i = 0; _i < 2; ++_i) \
;         __builtin_amdgcn_global_load_lds((const unsigned*)((const char*)(gbase) + (voff)[_i]), (LAS unsigned*)(lds + (bufoff) + ldsw + _i * 8192), 16, 0, 0); } while (0)
; #define PG8_LDA(dst, b, h) do { _Pragma("unroll") for (int m = 0; m < 4; ++m) _Pragma("unroll") for (int k = 0; k < 2; ++k) dst[m][k] = *(const LAS bf16x8*)(lds + PG8_SA(b, h) + aoff + m * 2048 + k * 1024); } while (0)
; #define PG8_LDB(dst, b, h) do { _Pragma("unroll") for (int n = 0; n < 2; ++n) _Pragma("unroll") for (int k = 0; k < 2; ++k) dst[n][k] = *(const LAS bf16x8*)(lds + PG8_SB(b, h) + boff + n * 2048 + k * 1024); } while (0)
; #define PG8_MMA(ai, bj, At, Bt) do { __builtin_amdgcn_s_setprio(1); _Pragma("unroll") for (int m = 0; m < 4; ++m) _Pragma("unroll") for (int n = 0; n < 2; ++n) _Pragma("unroll") for (int k = 0; k < 2; ++k) \
;         acc[ai][bj][m][n] = __builtin_amdgcn_mfma_f32_16x16x32_bf16(Bt[n][k], At[m][k], acc[ai][bj][m][n], 0, 0, 0); __builtin_amdgcn_s_setprio(0); } while (0)
; #define PG8_WAIT_V(n) asm volatile("s_waitcnt vmcnt(" #n ")" ::: "memory")
; #define PG8_WAIT_L(n) asm volatile("s_waitcnt lgkmcnt(" #n ")" ::: "memory")
; #define PG8_BAR __builtin_amdgcn_s_barrier()
; #define PG8_SCHED __builtin_amdgcn_sched_barrier(0)
; template <class Epi>
; __device__ __forceinline__ void gemm_phase(LAS unsigned char* lds, const Gemm g, const StaticOrder& S, const Epi& E) {
;     ...
;             PG8_WAIT_V(6); PG8_BAR; PG8_MMA(1, 1, At, B1); PG8_BAR;
;             PG8_LDB(B0, 1, 0); PG8_SCHED; PG8_LDA(At, 1, 0); PG8_STAGE(PG8_SA(0, 1), a2 + hstep, voffA);
;             PG8_WAIT_L(8); PG8_BAR; PG8_WAIT_L(0); PG8_MMA(0, 0, At, B0); PG8_BAR; PG8_SCHED;
;             PG8_LDB(B1, 1, 1); PG8_STAGE(PG8_SB(1, 0), b3, voffB);
;             PG8_BAR; PG8_WAIT_L(0); PG8_MMA(0, 1, At, B1); PG8_BAR;
;             PG8_LDA(At, 1, 1); PG8_STAGE(PG8_SA(1, 0), a3, voffA);
;             PG8_BAR; PG8_WAIT_L(0); PG8_MMA(1, 0, At, B0); PG8_BAR; PG8_SCHED;
;             PG8_STAGE(PG8_SB(1, 1), b3 + hstep, voffB);
;             PG8_WAIT_V(6); PG8_BAR; PG8_MMA(1, 1, At, B1); PG8_BAR;
	v_mfma_f32_16x16x32_bf16 v[52:55], v[200:203], v[168:171], v[52:55]
	v_mfma_f32_16x16x32_bf16 v[48:51], v[208:211], v[168:171], v[48:51]
	v_mfma_f32_16x16x32_bf16 v[36:39], v[200:203], v[176:179], v[36:39]
	v_mfma_f32_16x16x32_bf16 v[32:35], v[208:211], v[176:179], v[32:35]
	v_mfma_f32_16x16x32_bf16 v[20:23], v[200:203], v[184:187], v[20:23]
	v_mfma_f32_16x16x32_bf16 v[16:19], v[208:211], v[184:187], v[16:19]
	v_mfma_f32_16x16x32_bf16 v[4:7], v[200:203], v[192:195], v[4:7]
	v_mfma_f32_16x16x32_bf16 v[0:3], v[208:211], v[192:195], v[0:3]
	v_mfma_f32_16x16x32_bf16 v[52:55], v[204:207], v[172:175], v[52:55]
	v_mfma_f32_16x16x32_bf16 v[48:51], v[212:215], v[172:175], v[48:51]
	v_mfma_f32_16x16x32_bf16 v[36:39], v[204:207], v[180:183], v[36:39]
	v_mfma_f32_16x16x32_bf16 v[32:35], v[212:215], v[180:183], v[32:35]
	v_mfma_f32_16x16x32_bf16 v[20:23], v[204:207], v[188:191], v[20:23]
	v_mfma_f32_16x16x32_bf16 v[16:19], v[212:215], v[188:191], v[16:19]
	v_mfma_f32_16x16x32_bf16 v[4:7], v[204:207], v[196:199], v[4:7]
	v_mfma_f32_16x16x32_bf16 v[0:3], v[212:215], v[196:199], v[0:3]
	s_add_i32 s59, 0, 0x18000
	v_add_u32_e32 v164, s59, v153
	s_barrier
	ds_read_b128 v[144:147], v164
	ds_read_b128 v[148:151], v164 offset:1024
	ds_read_b128 v[160:163], v164 offset:2048
	ds_read_b128 v[164:167], v164 offset:3072
	s_add_u32 s44, s44, 0x80000
	s_addc_u32 s45, s45, 0
	s_mov_b32 m0, s29
	ds_read_b128 v[168:171], v156 offset:32768
	ds_read_b128 v[172:175], v156 offset:33792
	ds_read_b128 v[176:179], v156 offset:34816
	ds_read_b128 v[180:183], v156 offset:35840
	ds_read_b128 v[184:187], v156 offset:36864
	ds_read_b128 v[188:191], v156 offset:37888
	ds_read_b128 v[192:195], v156 offset:38912
	global_load_lds_dwordx4 v134, s[44:45]
	s_mov_b32 m0, s33
	ds_read_b128 v[196:199], v156 offset:39936
	global_load_lds_dwordx4 v130, s[44:45]
	s_waitcnt lgkmcnt(8)
	s_barrier
	s_waitcnt lgkmcnt(0)
	v_mfma_f32_16x16x32_bf16 v[124:127], v[144:147], v[168:171], v[124:127]
	v_mfma_f32_16x16x32_bf16 v[120:123], v[160:163], v[168:171], v[120:123]
	v_mfma_f32_16x16x32_bf16 v[108:111], v[144:147], v[176:179], v[108:111]
	v_mfma_f32_16x16x32_bf16 v[104:107], v[160:163], v[176:179], v[104:107]
	v_mfma_f32_16x16x32_bf16 v[92:95], v[144:147], v[184:187], v[92:95]
	v_mfma_f32_16x16x32_bf16 v[88:91], v[160:163], v[184:187], v[88:91]
	v_mfma_f32_16x16x32_bf16 v[76:79], v[144:147], v[192:195], v[76:79]
	v_mfma_f32_16x16x32_bf16 v[72:75], v[160:163], v[192:195], v[72:75]
	v_mfma_f32_16x16x32_bf16 v[124:127], v[148:151], v[172:175], v[124:127]
	v_mfma_f32_16x16x32_bf16 v[120:123], v[164:167], v[172:175], v[120:123]
	v_mfma_f32_16x16x32_bf16 v[108:111], v[148:151], v[180:183], v[108:111]
	v_mfma_f32_16x16x32_bf16 v[104:107], v[164:167], v[180:183], v[104:107]
	v_mfma_f32_16x16x32_bf16 v[92:95], v[148:151], v[188:191], v[92:95]
	v_mfma_f32_16x16x32_bf16 v[88:91], v[164:167], v[188:191], v[88:91]
	v_mfma_f32_16x16x32_bf16 v[76:79], v[148:151], v[196:199], v[76:79]
	v_mfma_f32_16x16x32_bf16 v[72:75], v[164:167], v[196:199], v[72:75]
	s_barrier
	s_add_i32 s44, 0, 0x1c000
	s_add_i32 s45, s59, s23
	v_add_u32_e32 v212, s44, v153
	s_mov_b32 m0, s45
	ds_read_b128 v[200:203], v212
	ds_read_b128 v[204:207], v212 offset:1024
	ds_read_b128 v[208:211], v212 offset:2048
	global_load_lds_dwordx4 v132, s[98:99]
	s_add_i32 m0, s45, 0x2000
	ds_read_b128 v[212:215], v212 offset:3072
	global_load_lds_dwordx4 v128, s[98:99]
	s_barrier
	s_waitcnt lgkmcnt(0)
	v_mfma_f32_16x16x32_bf16 v[116:119], v[200:203], v[168:171], v[116:119]
	v_mfma_f32_16x16x32_bf16 v[112:115], v[208:211], v[168:171], v[112:115]
	v_mfma_f32_16x16x32_bf16 v[100:103], v[200:203], v[176:179], v[100:103]
	v_mfma_f32_16x16x32_bf16 v[96:99], v[208:211], v[176:179], v[96:99]
	v_mfma_f32_16x16x32_bf16 v[84:87], v[200:203], v[184:187], v[84:87]
	v_mfma_f32_16x16x32_bf16 v[80:83], v[208:211], v[184:187], v[80:83]
	v_mfma_f32_16x16x32_bf16 v[68:71], v[200:203], v[192:195], v[68:71]
	v_mfma_f32_16x16x32_bf16 v[64:67], v[208:211], v[192:195], v[64:67]
	v_mfma_f32_16x16x32_bf16 v[116:119], v[204:207], v[172:175], v[116:119]
	v_mfma_f32_16x16x32_bf16 v[112:115], v[212:215], v[172:175], v[112:115]
	v_mfma_f32_16x16x32_bf16 v[100:103], v[204:207], v[180:183], v[100:103]
	v_mfma_f32_16x16x32_bf16 v[96:99], v[212:215], v[180:183], v[96:99]
	v_mfma_f32_16x16x32_bf16 v[84:87], v[204:207], v[188:191], v[84:87]
	v_mfma_f32_16x16x32_bf16 v[80:83], v[212:215], v[188:191], v[80:83]
	v_mfma_f32_16x16x32_bf16 v[68:71], v[204:207], v[196:199], v[68:71]
	v_mfma_f32_16x16x32_bf16 v[64:67], v[212:215], v[196:199], v[64:67]
	s_mov_b32 m0, s46
	s_barrier
	ds_read_b128 v[168:171], v156 offset:49152
	ds_read_b128 v[172:175], v156 offset:50176
	ds_read_b128 v[176:179], v156 offset:51200
	ds_read_b128 v[180:183], v156 offset:52224
	ds_read_b128 v[184:187], v156 offset:53248
	ds_read_b128 v[188:191], v156 offset:54272
	ds_read_b128 v[192:195], v156 offset:55296
	global_load_lds_dwordx4 v134, s[100:101]
	s_mov_b32 m0, s47
	ds_read_b128 v[196:199], v156 offset:56320
	global_load_lds_dwordx4 v130, s[100:101]
	s_barrier
	s_waitcnt lgkmcnt(0)
	v_mfma_f32_16x16x32_bf16 v[60:63], v[144:147], v[168:171], v[60:63]
	v_mfma_f32_16x16x32_bf16 v[56:59], v[160:163], v[168:171], v[56:59]
	v_mfma_f32_16x16x32_bf16 v[44:47], v[144:147], v[176:179], v[44:47]
	v_mfma_f32_16x16x32_bf16 v[40:43], v[160:163], v[176:179], v[40:43]
	v_mfma_f32_16x16x32_bf16 v[28:31], v[144:147], v[184:187], v[28:31]
	v_mfma_f32_16x16x32_bf16 v[24:27], v[160:163], v[184:187], v[24:27]
	v_mfma_f32_16x16x32_bf16 v[12:15], v[144:147], v[192:195], v[12:15]
	v_mfma_f32_16x16x32_bf16 v[8:11], v[160:163], v[192:195], v[8:11]
	v_mfma_f32_16x16x32_bf16 v[60:63], v[148:151], v[172:175], v[60:63]
	v_mfma_f32_16x16x32_bf16 v[56:59], v[164:167], v[172:175], v[56:59]
	v_mfma_f32_16x16x32_bf16 v[44:47], v[148:151], v[180:183], v[44:47]
	v_mfma_f32_16x16x32_bf16 v[40:43], v[164:167], v[180:183], v[40:43]
	v_mfma_f32_16x16x32_bf16 v[28:31], v[148:151], v[188:191], v[28:31]
	v_mfma_f32_16x16x32_bf16 v[24:27], v[164:167], v[188:191], v[24:27]
	v_mfma_f32_16x16x32_bf16 v[12:15], v[148:151], v[196:199], v[12:15]
	v_mfma_f32_16x16x32_bf16 v[8:11], v[164:167], v[196:199], v[8:11]
	s_barrier
; __device__ __forceinline__ float fast_rcp(float x) { return __builtin_amdgcn_rcpf(x); }
; __device__ __forceinline__ float fast_exp2(float x) { return __builtin_amdgcn_exp2f(x); }
; #define PG8_MMA(ai, bj, At, Bt) do { __builtin_amdgcn_s_setprio(1); _Pragma("unroll") for (int m = 0; m < 4; ++m) _Pragma("unroll") for (int n = 0; n < 2; ++n) _Pragma("unroll") for (int k = 0; k < 2; ++k) \
;         acc[ai][bj][m][n] = __builtin_amdgcn_mfma_f32_16x16x32_bf16(Bt[n][k], At[m][k], acc[ai][bj][m][n], 0, 0, 0); __builtin_amdgcn_s_setprio(0); } while (0)
; #define PG8_WAIT_V(n) asm volatile("s_waitcnt vmcnt(" #n ")" ::: "memory")
; #define PG8_BAR __builtin_amdgcn_s_barrier()
; __device__ __forceinline__ u32x4 pack8(f32x4 v0, f32x4 v1) { u32x4 w; w.x = cvt_pk_bf16(v0[0], v0[1]); w.y = cvt_pk_bf16(v0[2], v0[3]); w.z = cvt_pk_bf16(v1[0], v1[1]); w.w = cvt_pk_bf16(v1[2], v1[3]); return w; }
; template <class Epi>
; __device__ __forceinline__ void gemm_phase(LAS unsigned char* lds, const Gemm g, const StaticOrder& S, const Epi& E) {
;     ...
;             PG8_WAIT_V(6); PG8_BAR; PG8_MMA(1, 1, At, B1); PG8_BAR;
;         }
;     __device__ __forceinline__ void operator()(const f32x4 (&acc)[2][2][4][2], const Unit& u, int wr, int wc, int fr, int fq) const {
;         const int row0 = u.pm * BM + wr * 64 + fr, col0 = u.pn * HALF + wc * 32 + 8 * fq;
; #pragma unroll
;         for (int ai = 0; ai < 2; ++ai)
; #pragma unroll
;             for (int m = 0; m < 4; ++m) { bf16_t* rowp = O + (size_t)(row0 + ai * HALF + m * 16) * DFF + col0;
;                 const float r = rs[row0 + ai * HALF + m * 16], r2 = r * r;
;                 f32x4 h0, h1;
; #pragma unroll
;                 for (int j = 0; j < 4; ++j) {
;                     const float g0 = acc[ai][0][m][0][j], g1 = acc[ai][0][m][1][j];
;                     h0[j] = g0 * r2 * fast_rcp(1.0f + fast_exp2(g0 * (-LOG2E * r))) * acc[ai][1][m][0][j];
;                     h1[j] = g1 * r2 * fast_rcp(1.0f + fast_exp2(g1 * (-LOG2E * r))) * acc[ai][1][m][1][j]; }
;                 *(u32x4*)rowp = pack8(h0, h1); }
	s_add_u32 s42, s42, 0x80080
	s_addc_u32 s43, s43, 0
	s_add_i32 s44, s44, s23
	s_mov_b32 m0, s44
	s_nop 0
	global_load_lds_dwordx4 v132, s[42:43]
	s_add_i32 m0, s44, 0x2000
	s_nop 0
	global_load_lds_dwordx4 v128, s[42:43]
	s_waitcnt vmcnt(6)
	s_barrier
	v_mfma_f32_16x16x32_bf16 v[52:55], v[200:203], v[168:171], v[52:55]
	v_mfma_f32_16x16x32_bf16 v[48:51], v[208:211], v[168:171], v[48:51]
	v_mfma_f32_16x16x32_bf16 v[36:39], v[200:203], v[176:179], v[36:39]
	v_mfma_f32_16x16x32_bf16 v[32:35], v[208:211], v[176:179], v[32:35]
	v_mfma_f32_16x16x32_bf16 v[20:23], v[200:203], v[184:187], v[20:23]
	v_mfma_f32_16x16x32_bf16 v[16:19], v[208:211], v[184:187], v[16:19]
	v_mfma_f32_16x16x32_bf16 v[4:7], v[200:203], v[192:195], v[4:7]
	v_mfma_f32_16x16x32_bf16 v[0:3], v[208:211], v[192:195], v[0:3]
	v_mfma_f32_16x16x32_bf16 v[52:55], v[204:207], v[172:175], v[52:55]
	v_mfma_f32_16x16x32_bf16 v[48:51], v[212:215], v[172:175], v[48:51]
	v_mfma_f32_16x16x32_bf16 v[36:39], v[204:207], v[180:183], v[36:39]
	v_mfma_f32_16x16x32_bf16 v[32:35], v[212:215], v[180:183], v[32:35]
	v_mfma_f32_16x16x32_bf16 v[20:23], v[204:207], v[188:191], v[20:23]
	v_mfma_f32_16x16x32_bf16 v[16:19], v[212:215], v[188:191], v[16:19]
	v_mfma_f32_16x16x32_bf16 v[4:7], v[204:207], v[196:199], v[4:7]
	v_mfma_f32_16x16x32_bf16 v[0:3], v[212:215], v[196:199], v[0:3]
	s_add_i32 s58, s58, 2
	s_add_u32 s40, s40, 0x100
	s_addc_u32 s41, s41, 0
	s_add_u32 s56, s56, 0x100
	s_addc_u32 s57, s57, 0
	s_cmp_gt_u32 s58, 29
	s_barrier
	s_cbranch_scc0 .LBB0_796
	v_lshl_add_u32 v144, s38, 8, v152
	v_ashrrev_i32_e32 v145, 31, v144
	v_lshl_add_u64 v[150:151], v[144:145], 2, s[14:15]
	v_mov_b32_e32 v145, v224
	v_mov_b32_e32 v204, v225
	v_mov_b32_e32 v205, v226
	v_mov_b32_e32 v206, v227
	v_mov_b32_e32 v207, v228
	v_mov_b32_e32 v208, v229
	v_mov_b32_e32 v209, v230
	v_mov_b32_e32 v210, v231
	v_lshl_or_b32 v148, s53, 7, v154
	v_mov_b64_e32 v[146:147], s[20:21]
	v_ashrrev_i32_e32 v149, 31, v148
	v_mad_i64_i32 v[160:161], s[40:41], v144, s52, v[146:147]
	v_lshlrev_b64 v[148:149], 1, v[148:149]
	v_lshl_add_u64 v[160:161], v[160:161], 0, v[148:149]
	s_and_b64 vcc, exec, s[6:7]
	s_mov_b32 s53, s8
	s_mov_b32 s38, s30
	s_mov_b64 s[42:43], s[36:37]
	v_mul_f32_e32 v162, v145, v145
	v_mul_f32_e32 v145, 0xbfb8aa3b, v145
	v_mul_f32_e32 v163, v124, v162
	v_mul_f32_e32 v164, v120, v162
	v_mul_f32_e32 v120, v120, v145
	v_mul_f32_e32 v165, v125, v162
	v_mul_f32_e32 v125, v125, v145
	v_mul_f32_e32 v166, v121, v162
	v_mul_f32_e32 v121, v121, v145
	v_mul_f32_e32 v167, v126, v162
	v_mul_f32_e32 v126, v126, v145
	v_mul_f32_e32 v168, v122, v162
	v_mul_f32_e32 v122, v122, v145
	v_mul_f32_e32 v169, v127, v162
	v_mul_f32_e32 v127, v127, v145
	v_mul_f32_e32 v162, v123, v162
	v_mul_f32_e32 v123, v123, v145
	v_mul_f32_e32 v124, v124, v145
	v_exp_f32_e32 v120, v120
	v_exp_f32_e32 v125, v125
	v_exp_f32_e32 v121, v121
	v_exp_f32_e32 v126, v126
	v_exp_f32_e32 v122, v122
	v_exp_f32_e32 v127, v127
	v_exp_f32_e32 v123, v123
	v_exp_f32_e32 v124, v124
	v_add_f32_e32 v120, 1.0, v120
	v_add_f32_e32 v125, 1.0, v125
	v_add_f32_e32 v121, 1.0, v121
	v_add_f32_e32 v126, 1.0, v126
	v_add_f32_e32 v122, 1.0, v122
	v_add_f32_e32 v127, 1.0, v127
	v_add_f32_e32 v123, 1.0, v123
	v_add_f32_e32 v124, 1.0, v124
	v_rcp_f32_e32 v120, v120
	v_rcp_f32_e32 v125, v125
	v_rcp_f32_e32 v121, v121
	v_rcp_f32_e32 v126, v126
	v_rcp_f32_e32 v122, v122
	v_rcp_f32_e32 v127, v127
	v_rcp_f32_e32 v123, v123
	v_rcp_f32_e32 v124, v124
	v_mul_f32_e32 v120, v164, v120
	v_mul_f32_e32 v125, v165, v125
	v_mul_f32_e32 v121, v166, v121
	v_mul_f32_e32 v126, v167, v126
	v_mul_f32_e32 v122, v168, v122
	v_mul_f32_e32 v127, v169, v127
	v_mul_f32_e32 v123, v162, v123
	v_mul_f32_e32 v124, v163, v124
	v_mul_f32_e32 v120, v112, v120
	v_mul_f32_e32 v112, v117, v125
	v_mul_f32_e32 v117, v113, v121
	v_mul_f32_e32 v113, v118, v126
	v_mul_f32_e32 v118, v114, v122
	v_mul_f32_e32 v114, v119, v127
	v_mul_f32_e32 v115, v115, v123
	v_mul_f32_e32 v116, v116, v124
	v_cvt_pk_bf16_f32 v112, v116, v112
	v_cvt_pk_bf16_f32 v113, v113, v114
	v_cvt_pk_bf16_f32 v114, v120, v117
	v_cvt_pk_bf16_f32 v115, v118, v115
	global_store_dwordx4 v[160:161], v[112:115], off
	s_nop 1
	v_mov_b32_e32 v114, v204
	s_nop 0
	v_or_b32_e32 v112, 16, v144
	v_mad_i64_i32 v[112:113], s[40:41], v112, s52, v[146:147]
	v_lshl_add_u64 v[112:113], v[112:113], 0, v[148:149]
	v_mul_f32_e32 v115, v114, v114
	v_mul_f32_e32 v114, 0xbfb8aa3b, v114
	v_mul_f32_e32 v116, v108, v115
	v_mul_f32_e32 v117, v104, v115
	v_mul_f32_e32 v104, v104, v114
	v_mul_f32_e32 v118, v109, v115
	v_mul_f32_e32 v109, v109, v114
	v_mul_f32_e32 v119, v105, v115
	v_mul_f32_e32 v105, v105, v114
	v_mul_f32_e32 v120, v110, v115
	v_mul_f32_e32 v110, v110, v114
	v_mul_f32_e32 v121, v106, v115
	v_mul_f32_e32 v106, v106, v114
	v_mul_f32_e32 v122, v111, v115
	v_mul_f32_e32 v111, v111, v114
	v_mul_f32_e32 v115, v107, v115
	v_mul_f32_e32 v107, v107, v114
	v_mul_f32_e32 v108, v108, v114
	v_exp_f32_e32 v104, v104
	v_exp_f32_e32 v109, v109
	v_exp_f32_e32 v105, v105
	v_exp_f32_e32 v110, v110
	v_exp_f32_e32 v106, v106
	v_exp_f32_e32 v111, v111
	v_exp_f32_e32 v107, v107
	v_exp_f32_e32 v108, v108
	v_add_f32_e32 v104, 1.0, v104
	v_add_f32_e32 v109, 1.0, v109
	v_add_f32_e32 v105, 1.0, v105
	v_add_f32_e32 v110, 1.0, v110
	v_add_f32_e32 v106, 1.0, v106
	v_add_f32_e32 v111, 1.0, v111
	v_add_f32_e32 v107, 1.0, v107
	v_add_f32_e32 v108, 1.0, v108
	v_rcp_f32_e32 v104, v104
	v_rcp_f32_e32 v109, v109
	v_rcp_f32_e32 v105, v105
	v_rcp_f32_e32 v110, v110
	v_rcp_f32_e32 v106, v106
	v_rcp_f32_e32 v111, v111
	v_rcp_f32_e32 v107, v107
	v_rcp_f32_e32 v108, v108
	v_mul_f32_e32 v104, v117, v104
; __device__ __forceinline__ float fast_rcp(float x) { return __builtin_amdgcn_rcpf(x); }
; __device__ __forceinline__ float fast_exp2(float x) { return __builtin_amdgcn_exp2f(x); }
; __device__ __forceinline__ u32x4 pack8(f32x4 v0, f32x4 v1) { u32x4 w; w.x = cvt_pk_bf16(v0[0], v0[1]); w.y = cvt_pk_bf16(v0[2], v0[3]); w.z = cvt_pk_bf16(v1[0], v1[1]); w.w = cvt_pk_bf16(v1[2], v1[3]); return w; }
;     __device__ __forceinline__ void operator()(const f32x4 (&acc)[2][2][4][2], const Unit& u, int wr, int wc, int fr, int fq) const {
;         const int row0 = u.pm * BM + wr * 64 + fr, col0 = u.pn * HALF + wc * 32 + 8 * fq;
; #pragma unroll
;         for (int ai = 0; ai < 2; ++ai)
; #pragma unroll
;             for (int m = 0; m < 4; ++m) { bf16_t* rowp = O + (size_t)(row0 + ai * HALF + m * 16) * DFF + col0;
;                 const float r = rs[row0 + ai * HALF + m * 16], r2 = r * r;
;                 f32x4 h0, h1;
; #pragma unroll
;                 for (int j = 0; j < 4; ++j) {
;                     const float g0 = acc[ai][0][m][0][j], g1 = acc[ai][0][m][1][j];
;                     h0[j] = g0 * r2 * fast_rcp(1.0f + fast_exp2(g0 * (-LOG2E * r))) * acc[ai][1][m][0][j];
;                     h1[j] = g1 * r2 * fast_rcp(1.0f + fast_exp2(g1 * (-LOG2E * r))) * acc[ai][1][m][1][j]; }
;                 *(u32x4*)rowp = pack8(h0, h1); }
	v_mul_f32_e32 v109, v118, v109
	v_mul_f32_e32 v105, v119, v105
	v_mul_f32_e32 v110, v120, v110
	v_mul_f32_e32 v106, v121, v106
	v_mul_f32_e32 v111, v122, v111
	v_mul_f32_e32 v107, v115, v107
	v_mul_f32_e32 v108, v116, v108
	v_mul_f32_e32 v104, v96, v104
	v_mul_f32_e32 v96, v101, v109
	v_mul_f32_e32 v101, v97, v105
	v_mul_f32_e32 v97, v102, v110
	v_mul_f32_e32 v102, v98, v106
	v_mul_f32_e32 v98, v103, v111
	v_mul_f32_e32 v99, v99, v107
	v_mul_f32_e32 v100, v100, v108
	v_cvt_pk_bf16_f32 v96, v100, v96
	v_cvt_pk_bf16_f32 v97, v97, v98
	v_cvt_pk_bf16_f32 v98, v104, v101
	v_cvt_pk_bf16_f32 v99, v102, v99
	global_store_dwordx4 v[112:113], v[96:99], off
	s_nop 1
	v_mov_b32_e32 v98, v205
	s_nop 0
	v_or_b32_e32 v96, 32, v144
	v_mad_i64_i32 v[96:97], s[40:41], v96, s52, v[146:147]
	v_lshl_add_u64 v[96:97], v[96:97], 0, v[148:149]
	v_mul_f32_e32 v99, v98, v98
	v_mul_f32_e32 v98, 0xbfb8aa3b, v98
	v_mul_f32_e32 v100, v92, v99
	v_mul_f32_e32 v101, v88, v99
	v_mul_f32_e32 v88, v88, v98
	v_mul_f32_e32 v102, v93, v99
	v_mul_f32_e32 v93, v93, v98
	v_mul_f32_e32 v103, v89, v99
	v_mul_f32_e32 v89, v89, v98
	v_mul_f32_e32 v104, v94, v99
	v_mul_f32_e32 v94, v94, v98
	v_mul_f32_e32 v105, v90, v99
	v_mul_f32_e32 v90, v90, v98
	v_mul_f32_e32 v106, v95, v99
	v_mul_f32_e32 v95, v95, v98
	v_mul_f32_e32 v99, v91, v99
	v_mul_f32_e32 v91, v91, v98
	v_mul_f32_e32 v92, v92, v98
	v_exp_f32_e32 v88, v88
	v_exp_f32_e32 v93, v93
	v_exp_f32_e32 v89, v89
	v_exp_f32_e32 v94, v94
	v_exp_f32_e32 v90, v90
	v_exp_f32_e32 v95, v95
	v_exp_f32_e32 v91, v91
	v_exp_f32_e32 v92, v92
	v_add_f32_e32 v88, 1.0, v88
	v_add_f32_e32 v93, 1.0, v93
	v_add_f32_e32 v89, 1.0, v89
	v_add_f32_e32 v94, 1.0, v94
	v_add_f32_e32 v90, 1.0, v90
	v_add_f32_e32 v95, 1.0, v95
	v_add_f32_e32 v91, 1.0, v91
	v_add_f32_e32 v92, 1.0, v92
	v_rcp_f32_e32 v88, v88
	v_rcp_f32_e32 v93, v93
	v_rcp_f32_e32 v89, v89
	v_rcp_f32_e32 v94, v94
	v_rcp_f32_e32 v90, v90
	v_rcp_f32_e32 v95, v95
	v_rcp_f32_e32 v91, v91
	v_rcp_f32_e32 v92, v92
	v_mul_f32_e32 v88, v101, v88
	v_mul_f32_e32 v93, v102, v93
	v_mul_f32_e32 v89, v103, v89
	v_mul_f32_e32 v94, v104, v94
	v_mul_f32_e32 v90, v105, v90
	v_mul_f32_e32 v95, v106, v95
	v_mul_f32_e32 v91, v99, v91
	v_mul_f32_e32 v92, v100, v92
	v_mul_f32_e32 v88, v80, v88
	v_mul_f32_e32 v80, v85, v93
	v_mul_f32_e32 v85, v81, v89
	v_mul_f32_e32 v81, v86, v94
	v_mul_f32_e32 v86, v82, v90
	v_mul_f32_e32 v82, v87, v95
	v_mul_f32_e32 v83, v83, v91
	v_mul_f32_e32 v84, v84, v92
	v_cvt_pk_bf16_f32 v80, v84, v80
	v_cvt_pk_bf16_f32 v81, v81, v82
	v_cvt_pk_bf16_f32 v82, v88, v85
	v_cvt_pk_bf16_f32 v83, v86, v83
	global_store_dwordx4 v[96:97], v[80:83], off
	s_nop 1
	v_mov_b32_e32 v82, v206
	s_nop 0
	v_or_b32_e32 v80, 48, v144
	v_mad_i64_i32 v[80:81], s[40:41], v80, s52, v[146:147]
	v_lshl_add_u64 v[80:81], v[80:81], 0, v[148:149]
	v_mul_f32_e32 v83, v82, v82
	v_mul_f32_e32 v82, 0xbfb8aa3b, v82
	v_mul_f32_e32 v84, v76, v83
	v_mul_f32_e32 v85, v72, v83
	v_mul_f32_e32 v72, v72, v82
	v_mul_f32_e32 v86, v77, v83
	v_mul_f32_e32 v77, v77, v82
	v_mul_f32_e32 v87, v73, v83
	v_mul_f32_e32 v73, v73, v82
	v_mul_f32_e32 v88, v78, v83
	v_mul_f32_e32 v78, v78, v82
	v_mul_f32_e32 v89, v74, v83
	v_mul_f32_e32 v74, v74, v82
	v_mul_f32_e32 v90, v79, v83
	v_mul_f32_e32 v79, v79, v82
	v_mul_f32_e32 v83, v75, v83
	v_mul_f32_e32 v75, v75, v82
	v_mul_f32_e32 v76, v76, v82
	v_exp_f32_e32 v72, v72
	v_exp_f32_e32 v77, v77
	v_exp_f32_e32 v73, v73
	v_exp_f32_e32 v78, v78
	v_exp_f32_e32 v74, v74
	v_exp_f32_e32 v79, v79
	v_exp_f32_e32 v75, v75
	v_exp_f32_e32 v76, v76
	v_add_f32_e32 v72, 1.0, v72
	v_add_f32_e32 v77, 1.0, v77
	v_add_f32_e32 v73, 1.0, v73
	v_add_f32_e32 v78, 1.0, v78
	v_add_f32_e32 v74, 1.0, v74
	v_add_f32_e32 v79, 1.0, v79
	v_add_f32_e32 v75, 1.0, v75
	v_add_f32_e32 v76, 1.0, v76
	v_rcp_f32_e32 v72, v72
	v_rcp_f32_e32 v77, v77
	v_rcp_f32_e32 v73, v73
	v_rcp_f32_e32 v78, v78
	v_rcp_f32_e32 v74, v74
	v_rcp_f32_e32 v79, v79
	v_rcp_f32_e32 v75, v75
	v_rcp_f32_e32 v76, v76
	v_mul_f32_e32 v72, v85, v72
	v_mul_f32_e32 v77, v86, v77
	v_mul_f32_e32 v73, v87, v73
	v_mul_f32_e32 v78, v88, v78
	v_mul_f32_e32 v74, v89, v74
	v_mul_f32_e32 v79, v90, v79
	v_mul_f32_e32 v75, v83, v75
	v_mul_f32_e32 v76, v84, v76
	v_mul_f32_e32 v72, v64, v72
	v_mul_f32_e32 v64, v69, v77
	v_mul_f32_e32 v69, v65, v73
	v_mul_f32_e32 v65, v70, v78
	v_mul_f32_e32 v70, v66, v74
	v_mul_f32_e32 v66, v71, v79
	v_mul_f32_e32 v67, v67, v75
	v_mul_f32_e32 v68, v68, v76
	v_cvt_pk_bf16_f32 v64, v68, v64
	v_cvt_pk_bf16_f32 v65, v65, v66
	v_cvt_pk_bf16_f32 v66, v72, v69
	v_cvt_pk_bf16_f32 v67, v70, v67
	global_store_dwordx4 v[80:81], v[64:67], off
	s_nop 1
	v_mov_b32_e32 v66, v207
	s_nop 0
	v_add_u32_e32 v64, 0x80, v144
	v_mad_i64_i32 v[64:65], s[40:41], v64, s52, v[146:147]
	v_lshl_add_u64 v[64:65], v[64:65], 0, v[148:149]
	v_mul_f32_e32 v67, v66, v66
	v_mul_f32_e32 v66, 0xbfb8aa3b, v66
	v_mul_f32_e32 v68, v60, v67
	v_mul_f32_e32 v69, v56, v67
	v_mul_f32_e32 v56, v56, v66
	v_mul_f32_e32 v70, v61, v67
	v_mul_f32_e32 v61, v61, v66
	v_mul_f32_e32 v71, v57, v67
	v_mul_f32_e32 v57, v57, v66
	v_mul_f32_e32 v72, v62, v67
	v_mul_f32_e32 v62, v62, v66
	v_mul_f32_e32 v73, v58, v67
	v_mul_f32_e32 v58, v58, v66
	v_mul_f32_e32 v74, v63, v67
	v_mul_f32_e32 v63, v63, v66
	v_mul_f32_e32 v67, v59, v67
	v_mul_f32_e32 v59, v59, v66
	v_mul_f32_e32 v60, v60, v66
	v_exp_f32_e32 v56, v56
	v_exp_f32_e32 v61, v61
	v_exp_f32_e32 v57, v57
	v_exp_f32_e32 v62, v62
	v_exp_f32_e32 v58, v58
	v_exp_f32_e32 v63, v63
	v_exp_f32_e32 v59, v59
	v_exp_f32_e32 v60, v60
	v_add_f32_e32 v56, 1.0, v56
	v_add_f32_e32 v61, 1.0, v61
	v_add_f32_e32 v57, 1.0, v57
	v_add_f32_e32 v62, 1.0, v62
	v_add_f32_e32 v58, 1.0, v58
; __device__ __forceinline__ float fast_rcp(float x) { return __builtin_amdgcn_rcpf(x); }
; __device__ __forceinline__ float fast_exp2(float x) { return __builtin_amdgcn_exp2f(x); }
; __device__ __forceinline__ u32x4 pack8(f32x4 v0, f32x4 v1) { u32x4 w; w.x = cvt_pk_bf16(v0[0], v0[1]); w.y = cvt_pk_bf16(v0[2], v0[3]); w.z = cvt_pk_bf16(v1[0], v1[1]); w.w = cvt_pk_bf16(v1[2], v1[3]); return w; }
;     __device__ __forceinline__ void operator()(const f32x4 (&acc)[2][2][4][2], const Unit& u, int wr, int wc, int fr, int fq) const {
;         const int row0 = u.pm * BM + wr * 64 + fr, col0 = u.pn * HALF + wc * 32 + 8 * fq;
; #pragma unroll
;         for (int ai = 0; ai < 2; ++ai)
; #pragma unroll
;             for (int m = 0; m < 4; ++m) { bf16_t* rowp = O + (size_t)(row0 + ai * HALF + m * 16) * DFF + col0;
;                 const float r = rs[row0 + ai * HALF + m * 16], r2 = r * r;
;                 f32x4 h0, h1;
; #pragma unroll
;                 for (int j = 0; j < 4; ++j) {
;                     const float g0 = acc[ai][0][m][0][j], g1 = acc[ai][0][m][1][j];
;                     h0[j] = g0 * r2 * fast_rcp(1.0f + fast_exp2(g0 * (-LOG2E * r))) * acc[ai][1][m][0][j];
;                     h1[j] = g1 * r2 * fast_rcp(1.0f + fast_exp2(g1 * (-LOG2E * r))) * acc[ai][1][m][1][j]; }
;                 *(u32x4*)rowp = pack8(h0, h1); }
	v_add_f32_e32 v63, 1.0, v63
	v_add_f32_e32 v59, 1.0, v59
	v_add_f32_e32 v60, 1.0, v60
	v_rcp_f32_e32 v56, v56
	v_rcp_f32_e32 v61, v61
	v_rcp_f32_e32 v57, v57
	v_rcp_f32_e32 v62, v62
	v_rcp_f32_e32 v58, v58
	v_rcp_f32_e32 v63, v63
	v_rcp_f32_e32 v59, v59
	v_rcp_f32_e32 v60, v60
	v_mul_f32_e32 v56, v69, v56
	v_mul_f32_e32 v61, v70, v61
	v_mul_f32_e32 v57, v71, v57
	v_mul_f32_e32 v62, v72, v62
	v_mul_f32_e32 v58, v73, v58
	v_mul_f32_e32 v63, v74, v63
	v_mul_f32_e32 v59, v67, v59
	v_mul_f32_e32 v60, v68, v60
	v_mul_f32_e32 v56, v48, v56
	v_mul_f32_e32 v48, v53, v61
	v_mul_f32_e32 v53, v49, v57
	v_mul_f32_e32 v49, v54, v62
	v_mul_f32_e32 v54, v50, v58
	v_mul_f32_e32 v50, v55, v63
	v_mul_f32_e32 v51, v51, v59
	v_mul_f32_e32 v52, v52, v60
	v_cvt_pk_bf16_f32 v48, v52, v48
	v_cvt_pk_bf16_f32 v49, v49, v50
	v_cvt_pk_bf16_f32 v50, v56, v53
	v_cvt_pk_bf16_f32 v51, v54, v51
	global_store_dwordx4 v[64:65], v[48:51], off
	s_nop 1
	v_mov_b32_e32 v50, v208
	s_nop 0
	v_add_u32_e32 v48, 0x90, v144
	v_mad_i64_i32 v[48:49], s[40:41], v48, s52, v[146:147]
	v_lshl_add_u64 v[48:49], v[48:49], 0, v[148:149]
	v_mul_f32_e32 v51, v50, v50
	v_mul_f32_e32 v50, 0xbfb8aa3b, v50
	v_mul_f32_e32 v52, v44, v51
	v_mul_f32_e32 v53, v40, v51
	v_mul_f32_e32 v40, v40, v50
	v_mul_f32_e32 v54, v45, v51
	v_mul_f32_e32 v45, v45, v50
	v_mul_f32_e32 v55, v41, v51
	v_mul_f32_e32 v41, v41, v50
	v_mul_f32_e32 v56, v46, v51
	v_mul_f32_e32 v46, v46, v50
	v_mul_f32_e32 v57, v42, v51
	v_mul_f32_e32 v42, v42, v50
	v_mul_f32_e32 v58, v47, v51
	v_mul_f32_e32 v47, v47, v50
	v_mul_f32_e32 v51, v43, v51
	v_mul_f32_e32 v43, v43, v50
	v_mul_f32_e32 v44, v44, v50
	v_exp_f32_e32 v40, v40
	v_exp_f32_e32 v45, v45
	v_exp_f32_e32 v41, v41
	v_exp_f32_e32 v46, v46
	v_exp_f32_e32 v42, v42
	v_exp_f32_e32 v47, v47
	v_exp_f32_e32 v43, v43
	v_exp_f32_e32 v44, v44
	v_add_f32_e32 v40, 1.0, v40
	v_add_f32_e32 v45, 1.0, v45
	v_add_f32_e32 v41, 1.0, v41
	v_add_f32_e32 v46, 1.0, v46
	v_add_f32_e32 v42, 1.0, v42
	v_add_f32_e32 v47, 1.0, v47
	v_add_f32_e32 v43, 1.0, v43
	v_add_f32_e32 v44, 1.0, v44
	v_rcp_f32_e32 v40, v40
	v_rcp_f32_e32 v45, v45
	v_rcp_f32_e32 v41, v41
	v_rcp_f32_e32 v46, v46
	v_rcp_f32_e32 v42, v42
	v_rcp_f32_e32 v47, v47
	v_rcp_f32_e32 v43, v43
	v_rcp_f32_e32 v44, v44
	v_mul_f32_e32 v40, v53, v40
	v_mul_f32_e32 v45, v54, v45
	v_mul_f32_e32 v41, v55, v41
	v_mul_f32_e32 v46, v56, v46
	v_mul_f32_e32 v42, v57, v42
	v_mul_f32_e32 v47, v58, v47
	v_mul_f32_e32 v43, v51, v43
	v_mul_f32_e32 v44, v52, v44
	v_mul_f32_e32 v40, v32, v40
	v_mul_f32_e32 v32, v37, v45
	v_mul_f32_e32 v37, v33, v41
	v_mul_f32_e32 v33, v38, v46
	v_mul_f32_e32 v38, v34, v42
	v_mul_f32_e32 v34, v39, v47
	v_mul_f32_e32 v35, v35, v43
	v_mul_f32_e32 v36, v36, v44
	v_cvt_pk_bf16_f32 v32, v36, v32
	v_cvt_pk_bf16_f32 v33, v33, v34
	v_cvt_pk_bf16_f32 v34, v40, v37
	v_cvt_pk_bf16_f32 v35, v38, v35
	global_store_dwordx4 v[48:49], v[32:35], off
	s_nop 1
	v_mov_b32_e32 v34, v209
	s_nop 0
	v_add_u32_e32 v32, 0xa0, v144
	v_mad_i64_i32 v[32:33], s[40:41], v32, s52, v[146:147]
	v_lshl_add_u64 v[32:33], v[32:33], 0, v[148:149]
	s_mov_b64 s[40:41], s[34:35]
	v_mul_f32_e32 v35, v34, v34
	v_mul_f32_e32 v34, 0xbfb8aa3b, v34
	v_mul_f32_e32 v36, v28, v35
	v_mul_f32_e32 v37, v24, v35
	v_mul_f32_e32 v24, v24, v34
	v_mul_f32_e32 v38, v29, v35
	v_mul_f32_e32 v29, v29, v34
	v_mul_f32_e32 v39, v25, v35
	v_mul_f32_e32 v25, v25, v34
	v_mul_f32_e32 v40, v30, v35
	v_mul_f32_e32 v30, v30, v34
	v_mul_f32_e32 v41, v26, v35
	v_mul_f32_e32 v26, v26, v34
	v_mul_f32_e32 v42, v31, v35
	v_mul_f32_e32 v31, v31, v34
	v_mul_f32_e32 v35, v27, v35
	v_mul_f32_e32 v27, v27, v34
	v_mul_f32_e32 v28, v28, v34
	v_exp_f32_e32 v24, v24
	v_exp_f32_e32 v29, v29
	v_exp_f32_e32 v25, v25
	v_exp_f32_e32 v30, v30
	v_exp_f32_e32 v26, v26
	v_exp_f32_e32 v31, v31
	v_exp_f32_e32 v27, v27
	v_exp_f32_e32 v28, v28
	v_add_f32_e32 v24, 1.0, v24
	v_add_f32_e32 v29, 1.0, v29
	v_add_f32_e32 v25, 1.0, v25
	v_add_f32_e32 v30, 1.0, v30
	v_add_f32_e32 v26, 1.0, v26
	v_add_f32_e32 v31, 1.0, v31
	v_add_f32_e32 v27, 1.0, v27
	v_add_f32_e32 v28, 1.0, v28
	v_rcp_f32_e32 v24, v24
	v_rcp_f32_e32 v29, v29
	v_rcp_f32_e32 v25, v25
	v_rcp_f32_e32 v30, v30
	v_rcp_f32_e32 v26, v26
	v_rcp_f32_e32 v31, v31
	v_rcp_f32_e32 v27, v27
	v_rcp_f32_e32 v28, v28
	v_mul_f32_e32 v24, v37, v24
	v_mul_f32_e32 v29, v38, v29
	v_mul_f32_e32 v25, v39, v25
	v_mul_f32_e32 v30, v40, v30
	v_mul_f32_e32 v26, v41, v26
	v_mul_f32_e32 v31, v42, v31
	v_mul_f32_e32 v27, v35, v27
	v_mul_f32_e32 v28, v36, v28
	v_mul_f32_e32 v24, v16, v24
	v_mul_f32_e32 v16, v21, v29
	v_mul_f32_e32 v21, v17, v25
	v_mul_f32_e32 v17, v22, v30
	v_mul_f32_e32 v22, v18, v26
	v_mul_f32_e32 v18, v23, v31
	v_mul_f32_e32 v19, v19, v27
	v_mul_f32_e32 v20, v20, v28
	v_cvt_pk_bf16_f32 v16, v20, v16
	v_cvt_pk_bf16_f32 v17, v17, v18
	v_cvt_pk_bf16_f32 v18, v24, v21
	v_cvt_pk_bf16_f32 v19, v22, v19
	global_store_dwordx4 v[32:33], v[16:19], off
	s_nop 1
	v_mov_b32_e32 v18, v210
	s_nop 0
	v_add_u32_e32 v16, 0xb0, v144
	v_mad_i64_i32 v[16:17], s[6:7], v16, s52, v[146:147]
	v_lshl_add_u64 v[16:17], v[16:17], 0, v[148:149]
	v_mul_f32_e32 v19, v18, v18
	v_mul_f32_e32 v18, 0xbfb8aa3b, v18
	v_mul_f32_e32 v20, v12, v19
	v_mul_f32_e32 v21, v8, v19
	v_mul_f32_e32 v8, v8, v18
	v_mul_f32_e32 v22, v13, v19
	v_mul_f32_e32 v13, v13, v18
	v_mul_f32_e32 v23, v9, v19
	v_mul_f32_e32 v9, v9, v18
	v_mul_f32_e32 v24, v14, v19
	v_mul_f32_e32 v14, v14, v18
	v_mul_f32_e32 v25, v10, v19
	v_mul_f32_e32 v10, v10, v18
	v_mul_f32_e32 v26, v15, v19
	v_mul_f32_e32 v15, v15, v18
	v_mul_f32_e32 v19, v11, v19
	v_mul_f32_e32 v11, v11, v18
	v_mul_f32_e32 v12, v12, v18
	v_exp_f32_e32 v8, v8
	v_exp_f32_e32 v13, v13
	v_exp_f32_e32 v9, v9
	v_exp_f32_e32 v14, v14
	v_exp_f32_e32 v10, v10
	v_exp_f32_e32 v15, v15
	v_exp_f32_e32 v11, v11
	v_exp_f32_e32 v12, v12
	v_add_f32_e32 v8, 1.0, v8
	v_add_f32_e32 v13, 1.0, v13
	v_add_f32_e32 v9, 1.0, v9
	v_add_f32_e32 v14, 1.0, v14
	v_add_f32_e32 v10, 1.0, v10
	v_add_f32_e32 v15, 1.0, v15
	v_add_f32_e32 v11, 1.0, v11
	v_add_f32_e32 v12, 1.0, v12
	v_rcp_f32_e32 v8, v8
	v_rcp_f32_e32 v13, v13
	v_rcp_f32_e32 v9, v9
	v_rcp_f32_e32 v14, v14
	v_rcp_f32_e32 v10, v10
	v_rcp_f32_e32 v15, v15
	v_rcp_f32_e32 v11, v11
	v_rcp_f32_e32 v12, v12
	v_mul_f32_e32 v8, v21, v8
	v_mul_f32_e32 v13, v22, v13
	v_mul_f32_e32 v9, v23, v9
	v_mul_f32_e32 v14, v24, v14
	v_mul_f32_e32 v10, v25, v10
	v_mul_f32_e32 v15, v26, v15
	v_mul_f32_e32 v11, v19, v11
	v_mul_f32_e32 v12, v20, v12
	v_mul_f32_e32 v8, v0, v8
	v_mul_f32_e32 v0, v5, v13
	v_mul_f32_e32 v5, v1, v9
	v_mul_f32_e32 v1, v6, v14
	v_mul_f32_e32 v6, v2, v10
	v_mul_f32_e32 v2, v7, v15
	v_mul_f32_e32 v3, v3, v11
	v_mul_f32_e32 v4, v4, v12
	v_cvt_pk_bf16_f32 v0, v4, v0
	v_cvt_pk_bf16_f32 v1, v1, v2
	v_cvt_pk_bf16_f32 v2, v8, v5
	v_cvt_pk_bf16_f32 v3, v6, v3
	global_store_dwordx4 v[16:17], v[0:3], off
	s_cbranch_vccz .LBB0_793
	s_waitcnt vmcnt(0)
	s_cmpk_gt_u32 s10, 0xff
	s_cbranch_scc1 .LBB0_800
	s_barrier

; #define PG8_STAGE(bufoff, gbase, voff) do { _Pragma("unroll") for (int _i = 0; _i < 2; ++_i) \
;         __builtin_amdgcn_global_load_lds((const unsigned*)((const char*)(gbase) + (voff)[_i]), (LAS unsigned*)(lds + (bufoff) + ldsw + _i * 8192), 16, 0, 0); } while (0)
; #define PG8_LDA(dst, b, h) do { _Pragma("unroll") for (int m = 0; m < 4; ++m) _Pragma("unroll") for (int k = 0; k < 2; ++k) dst[m][k] = *(const LAS bf16x8*)(lds + PG8_SA(b, h) + aoff + m * 2048 + k * 1024); } while (0)
; #define PG8_LDB(dst, b, h) do { _Pragma("unroll") for (int n = 0; n < 2; ++n) _Pragma("unroll") for (int k = 0; k < 2; ++k) dst[n][k] = *(const LAS bf16x8*)(lds + PG8_SB(b, h) + boff + n * 2048 + k * 1024); } while (0)
; #define PG8_MMA(ai, bj, At, Bt) do { __builtin_amdgcn_s_setprio(1); _Pragma("unroll") for (int m = 0; m < 4; ++m) _Pragma("unroll") for (int n = 0; n < 2; ++n) _Pragma("unroll") for (int k = 0; k < 2; ++k) \
;         acc[ai][bj][m][n] = __builtin_amdgcn_mfma_f32_16x16x32_bf16(Bt[n][k], At[m][k], acc[ai][bj][m][n], 0, 0, 0); __builtin_amdgcn_s_setprio(0); } while (0)
; #define PG8_WAIT_V(n) asm volatile("s_waitcnt vmcnt(" #n ")" ::: "memory")
; #define PG8_WAIT_L(n) asm volatile("s_waitcnt lgkmcnt(" #n ")" ::: "memory")
; template <class Epi>
; __device__ __forceinline__ void gemm_phase(LAS unsigned char* lds, const Gemm g, const StaticOrder& S, const Epi& E) {
;     ...
;         for (int t = 0; t < nt; t += 2) {
;             const bool last = (t == nt - 2);
;             const char* a1 = cA + (size_t)(t + 1) * kstep;
;             const char* a2 = last ? nA : cA + (size_t)(t + 2) * kstep; const char* b2 = last ? nB : cB + (size_t)(t + 2) * kstep;
;             const char* a3 = a2 + kstep; const char* b3 = b2 + kstep;
;             PG8_LDB(B0, 0, 0); PG8_SCHED; PG8_LDA(At, 0, 0); PG8_STAGE(PG8_SA(1, 1), a1 + hstep, voffA);
;             PG8_WAIT_L(8); PG8_BAR; PG8_WAIT_L(0); PG8_MMA(0, 0, At, B0); PG8_BAR; PG8_SCHED;
;             PG8_LDB(B1, 0, 1); PG8_STAGE(PG8_SB(0, 0), b2, voffB);
;             PG8_BAR; PG8_WAIT_L(0); PG8_MMA(0, 1, At, B1); PG8_BAR;
;             PG8_LDA(At, 0, 1); PG8_STAGE(PG8_SA(0, 0), a2, voffA);
;             PG8_BAR; PG8_WAIT_L(0); PG8_MMA(1, 0, At, B0); PG8_BAR; PG8_SCHED;
;             PG8_STAGE(PG8_SB(0, 1), b2 + hstep, voffB);
;             PG8_WAIT_V(6); PG8_BAR; PG8_MMA(1, 1, At, B1); PG8_BAR;
.LBB0_864:
	ds_read_b128 v[148:151], v145
	ds_read_b128 v[152:155], v145 offset:1024
	ds_read_b128 v[160:163], v145 offset:2048
	ds_read_b128 v[164:167], v145 offset:3072
	s_add_u32 s44, s42, 0x100
	s_addc_u32 s45, s43, 0
	s_cmpk_eq_i32 s67, 0x54
	s_cselect_b32 s49, s41, s45
	s_cselect_b32 s48, s40, s44
	s_cselect_b32 s47, s7, s66
	s_cselect_b32 s46, s6, s65
	s_add_i32 m0, s28, 0xc000
	ds_read_b128 v[168:171], v146
	ds_read_b128 v[172:175], v146 offset:1024
	ds_read_b128 v[176:179], v146 offset:2048
	ds_read_b128 v[180:183], v146 offset:3072
	ds_read_b128 v[184:187], v146 offset:4096
	ds_read_b128 v[188:191], v146 offset:5120
	ds_read_b128 v[192:195], v146 offset:6144
	global_load_lds_dwordx4 v136, s[42:43]
	s_add_i32 m0, s28, 0xe000
	ds_read_b128 v[196:199], v146 offset:7168
	global_load_lds_dwordx4 v138, s[42:43]
	s_waitcnt lgkmcnt(8)
	s_barrier
	s_waitcnt lgkmcnt(0)
	v_mfma_f32_16x16x32_bf16 v[124:127], v[148:151], v[168:171], v[124:127]
	v_mfma_f32_16x16x32_bf16 v[120:123], v[160:163], v[168:171], v[120:123]
	v_mfma_f32_16x16x32_bf16 v[112:115], v[148:151], v[176:179], v[112:115]
	v_mfma_f32_16x16x32_bf16 v[104:107], v[160:163], v[176:179], v[104:107]
	v_mfma_f32_16x16x32_bf16 v[96:99], v[148:151], v[184:187], v[96:99]
	v_mfma_f32_16x16x32_bf16 v[88:91], v[160:163], v[184:187], v[88:91]
	v_mfma_f32_16x16x32_bf16 v[80:83], v[148:151], v[192:195], v[80:83]
	v_mfma_f32_16x16x32_bf16 v[72:75], v[160:163], v[192:195], v[72:75]
	v_mfma_f32_16x16x32_bf16 v[124:127], v[152:155], v[172:175], v[124:127]
	v_mfma_f32_16x16x32_bf16 v[120:123], v[164:167], v[172:175], v[120:123]
	v_mfma_f32_16x16x32_bf16 v[112:115], v[152:155], v[180:183], v[112:115]
	v_mfma_f32_16x16x32_bf16 v[104:107], v[164:167], v[180:183], v[104:107]
	v_mfma_f32_16x16x32_bf16 v[96:99], v[152:155], v[188:191], v[96:99]
	v_mfma_f32_16x16x32_bf16 v[88:91], v[164:167], v[188:191], v[88:91]
	v_mfma_f32_16x16x32_bf16 v[80:83], v[152:155], v[196:199], v[80:83]
	v_mfma_f32_16x16x32_bf16 v[72:75], v[164:167], v[196:199], v[72:75]
	s_barrier
	s_add_i32 s42, s55, s23
	s_add_u32 s98, s46, s2
	s_addc_u32 s99, s47, s3
	s_mov_b32 m0, s42
	ds_read_b128 v[200:203], v147
	ds_read_b128 v[204:207], v147 offset:1024
	ds_read_b128 v[208:211], v147 offset:2048
	global_load_lds_dwordx4 v132, s[46:47]
	s_add_i32 m0, s42, 0x2000
	ds_read_b128 v[212:215], v147 offset:3072
	global_load_lds_dwordx4 v128, s[46:47]
	s_barrier
	s_waitcnt lgkmcnt(0)
	v_mfma_f32_16x16x32_bf16 v[116:119], v[200:203], v[168:171], v[116:119]
	v_mfma_f32_16x16x32_bf16 v[108:111], v[208:211], v[168:171], v[108:111]
	v_mfma_f32_16x16x32_bf16 v[100:103], v[200:203], v[176:179], v[100:103]
	v_mfma_f32_16x16x32_bf16 v[92:95], v[208:211], v[176:179], v[92:95]
	v_mfma_f32_16x16x32_bf16 v[84:87], v[200:203], v[184:187], v[84:87]
	v_mfma_f32_16x16x32_bf16 v[76:79], v[208:211], v[184:187], v[76:79]
	v_mfma_f32_16x16x32_bf16 v[68:71], v[200:203], v[192:195], v[68:71]
	v_mfma_f32_16x16x32_bf16 v[64:67], v[208:211], v[192:195], v[64:67]
	v_mfma_f32_16x16x32_bf16 v[116:119], v[204:207], v[172:175], v[116:119]
	v_mfma_f32_16x16x32_bf16 v[108:111], v[212:215], v[172:175], v[108:111]
	v_mfma_f32_16x16x32_bf16 v[100:103], v[204:207], v[180:183], v[100:103]
	v_mfma_f32_16x16x32_bf16 v[92:95], v[212:215], v[180:183], v[92:95]
	v_mfma_f32_16x16x32_bf16 v[84:87], v[204:207], v[188:191], v[84:87]
	v_mfma_f32_16x16x32_bf16 v[76:79], v[212:215], v[188:191], v[76:79]
	v_mfma_f32_16x16x32_bf16 v[68:71], v[204:207], v[196:199], v[68:71]
	v_mfma_f32_16x16x32_bf16 v[64:67], v[212:215], v[196:199], v[64:67]
	s_mov_b32 m0, s28
	s_add_u32 s100, s48, s2
	s_addc_u32 s101, s49, s3
	s_barrier
	ds_read_b128 v[168:171], v146 offset:16384
	ds_read_b128 v[172:175], v146 offset:17408
	ds_read_b128 v[176:179], v146 offset:18432
	ds_read_b128 v[180:183], v146 offset:19456
	ds_read_b128 v[184:187], v146 offset:20480
	ds_read_b128 v[188:191], v146 offset:21504
	ds_read_b128 v[192:195], v146 offset:22528
	global_load_lds_dwordx4 v134, s[48:49]
	s_mov_b32 m0, s29
	ds_read_b128 v[196:199], v146 offset:23552
	global_load_lds_dwordx4 v130, s[48:49]
	s_barrier
	s_waitcnt lgkmcnt(0)
	v_mfma_f32_16x16x32_bf16 v[60:63], v[148:151], v[168:171], v[60:63]
	v_mfma_f32_16x16x32_bf16 v[56:59], v[160:163], v[168:171], v[56:59]
	v_mfma_f32_16x16x32_bf16 v[52:55], v[148:151], v[176:179], v[52:55]
	v_mfma_f32_16x16x32_bf16 v[44:47], v[160:163], v[176:179], v[44:47]
	v_mfma_f32_16x16x32_bf16 v[36:39], v[148:151], v[184:187], v[36:39]
	v_mfma_f32_16x16x32_bf16 v[28:31], v[160:163], v[184:187], v[28:31]
	v_mfma_f32_16x16x32_bf16 v[20:23], v[148:151], v[192:195], v[20:23]
	v_mfma_f32_16x16x32_bf16 v[12:15], v[160:163], v[192:195], v[12:15]
	v_mfma_f32_16x16x32_bf16 v[60:63], v[152:155], v[172:175], v[60:63]
	v_mfma_f32_16x16x32_bf16 v[56:59], v[164:167], v[172:175], v[56:59]
	v_mfma_f32_16x16x32_bf16 v[52:55], v[152:155], v[180:183], v[52:55]
	v_mfma_f32_16x16x32_bf16 v[44:47], v[164:167], v[180:183], v[44:47]
	v_mfma_f32_16x16x32_bf16 v[36:39], v[152:155], v[188:191], v[36:39]
	v_mfma_f32_16x16x32_bf16 v[28:31], v[164:167], v[188:191], v[28:31]
	v_mfma_f32_16x16x32_bf16 v[20:23], v[152:155], v[196:199], v[20:23]
	v_mfma_f32_16x16x32_bf16 v[12:15], v[164:167], v[196:199], v[12:15]
	s_barrier
	s_add_u32 s42, s46, 0x160000
	s_addc_u32 s43, s47, 0
	s_add_i32 s68, s56, s23
	s_mov_b32 m0, s68
	s_nop 0
	global_load_lds_dwordx4 v132, s[42:43]
	s_add_i32 m0, s68, 0x2000
	s_nop 0
	global_load_lds_dwordx4 v128, s[42:43]
	s_waitcnt vmcnt(6)
	s_barrier
; #define PG8_STAGE(bufoff, gbase, voff) do { _Pragma("unroll") for (int _i = 0; _i < 2; ++_i) \
;         __builtin_amdgcn_global_load_lds((const unsigned*)((const char*)(gbase) + (voff)[_i]), (LAS unsigned*)(lds + (bufoff) + ldsw + _i * 8192), 16, 0, 0); } while (0)
; #define PG8_LDA(dst, b, h) do { _Pragma("unroll") for (int m = 0; m < 4; ++m) _Pragma("unroll") for (int k = 0; k < 2; ++k) dst[m][k] = *(const LAS bf16x8*)(lds + PG8_SA(b, h) + aoff + m * 2048 + k * 1024); } while (0)
; #define PG8_LDB(dst, b, h) do { _Pragma("unroll") for (int n = 0; n < 2; ++n) _Pragma("unroll") for (int k = 0; k < 2; ++k) dst[n][k] = *(const LAS bf16x8*)(lds + PG8_SB(b, h) + boff + n * 2048 + k * 1024); } while (0)
; #define PG8_MMA(ai, bj, At, Bt) do { __builtin_amdgcn_s_setprio(1); _Pragma("unroll") for (int m = 0; m < 4; ++m) _Pragma("unroll") for (int n = 0; n < 2; ++n) _Pragma("unroll") for (int k = 0; k < 2; ++k) \
;         acc[ai][bj][m][n] = __builtin_amdgcn_mfma_f32_16x16x32_bf16(Bt[n][k], At[m][k], acc[ai][bj][m][n], 0, 0, 0); __builtin_amdgcn_s_setprio(0); } while (0)
; #define PG8_WAIT_V(n) asm volatile("s_waitcnt vmcnt(" #n ")" ::: "memory")
; #define PG8_WAIT_L(n) asm volatile("s_waitcnt lgkmcnt(" #n ")" ::: "memory")
; #define PG8_BAR __builtin_amdgcn_s_barrier()
; #define PG8_SCHED __builtin_amdgcn_sched_barrier(0)
; template <class Epi>
; __device__ __forceinline__ void gemm_phase(LAS unsigned char* lds, const Gemm g, const StaticOrder& S, const Epi& E) {
;     ...
;             PG8_WAIT_V(6); PG8_BAR; PG8_MMA(1, 1, At, B1); PG8_BAR;
;             PG8_LDB(B0, 1, 0); PG8_SCHED; PG8_LDA(At, 1, 0); PG8_STAGE(PG8_SA(0, 1), a2 + hstep, voffA);
;             PG8_WAIT_L(8); PG8_BAR; PG8_WAIT_L(0); PG8_MMA(0, 0, At, B0); PG8_BAR; PG8_SCHED;
;             PG8_LDB(B1, 1, 1); PG8_STAGE(PG8_SB(1, 0), b3, voffB);
;             PG8_BAR; PG8_WAIT_L(0); PG8_MMA(0, 1, At, B1); PG8_BAR;
;             PG8_LDA(At, 1, 1); PG8_STAGE(PG8_SA(1, 0), a3, voffA);
;             PG8_BAR; PG8_WAIT_L(0); PG8_MMA(1, 0, At, B0); PG8_BAR; PG8_SCHED;
;             PG8_STAGE(PG8_SB(1, 1), b3 + hstep, voffB);
;             PG8_WAIT_V(6); PG8_BAR; PG8_MMA(1, 1, At, B1); PG8_BAR;
	v_mfma_f32_16x16x32_bf16 v[48:51], v[200:203], v[168:171], v[48:51]
	v_mfma_f32_16x16x32_bf16 v[40:43], v[208:211], v[168:171], v[40:43]
	v_mfma_f32_16x16x32_bf16 v[32:35], v[200:203], v[176:179], v[32:35]
	v_mfma_f32_16x16x32_bf16 v[24:27], v[208:211], v[176:179], v[24:27]
	v_mfma_f32_16x16x32_bf16 v[16:19], v[200:203], v[184:187], v[16:19]
	v_mfma_f32_16x16x32_bf16 v[8:11], v[208:211], v[184:187], v[8:11]
	v_mfma_f32_16x16x32_bf16 v[4:7], v[200:203], v[192:195], v[4:7]
	v_mfma_f32_16x16x32_bf16 v[0:3], v[208:211], v[192:195], v[0:3]
	v_mfma_f32_16x16x32_bf16 v[48:51], v[204:207], v[172:175], v[48:51]
	v_mfma_f32_16x16x32_bf16 v[40:43], v[212:215], v[172:175], v[40:43]
	v_mfma_f32_16x16x32_bf16 v[32:35], v[204:207], v[180:183], v[32:35]
	v_mfma_f32_16x16x32_bf16 v[24:27], v[212:215], v[180:183], v[24:27]
	v_mfma_f32_16x16x32_bf16 v[16:19], v[204:207], v[188:191], v[16:19]
	v_mfma_f32_16x16x32_bf16 v[8:11], v[212:215], v[188:191], v[8:11]
	v_mfma_f32_16x16x32_bf16 v[4:7], v[204:207], v[196:199], v[4:7]
	v_mfma_f32_16x16x32_bf16 v[0:3], v[212:215], v[196:199], v[0:3]
	s_add_i32 s68, 0, 0x18000
	v_add_u32_e32 v164, s68, v143
	s_barrier
	ds_read_b128 v[148:151], v164
	ds_read_b128 v[152:155], v164 offset:1024
	ds_read_b128 v[160:163], v164 offset:2048
	ds_read_b128 v[164:167], v164 offset:3072
	s_add_u32 s42, s48, 0x160000
	s_addc_u32 s43, s49, 0
	s_mov_b32 m0, s33
	ds_read_b128 v[168:171], v146 offset:32768
	ds_read_b128 v[172:175], v146 offset:33792
	ds_read_b128 v[176:179], v146 offset:34816
	ds_read_b128 v[180:183], v146 offset:35840
	ds_read_b128 v[184:187], v146 offset:36864
	ds_read_b128 v[188:191], v146 offset:37888
	ds_read_b128 v[192:195], v146 offset:38912
	global_load_lds_dwordx4 v134, s[42:43]
	s_mov_b32 m0, s50
	ds_read_b128 v[196:199], v146 offset:39936
	global_load_lds_dwordx4 v130, s[42:43]
	s_waitcnt lgkmcnt(8)
	s_barrier
	s_waitcnt lgkmcnt(0)
	v_mfma_f32_16x16x32_bf16 v[124:127], v[148:151], v[168:171], v[124:127]
	v_mfma_f32_16x16x32_bf16 v[120:123], v[160:163], v[168:171], v[120:123]
	v_mfma_f32_16x16x32_bf16 v[112:115], v[148:151], v[176:179], v[112:115]
	v_mfma_f32_16x16x32_bf16 v[104:107], v[160:163], v[176:179], v[104:107]
	v_mfma_f32_16x16x32_bf16 v[96:99], v[148:151], v[184:187], v[96:99]
	v_mfma_f32_16x16x32_bf16 v[88:91], v[160:163], v[184:187], v[88:91]
	v_mfma_f32_16x16x32_bf16 v[80:83], v[148:151], v[192:195], v[80:83]
	v_mfma_f32_16x16x32_bf16 v[72:75], v[160:163], v[192:195], v[72:75]
	v_mfma_f32_16x16x32_bf16 v[124:127], v[152:155], v[172:175], v[124:127]
	v_mfma_f32_16x16x32_bf16 v[120:123], v[164:167], v[172:175], v[120:123]
	v_mfma_f32_16x16x32_bf16 v[112:115], v[152:155], v[180:183], v[112:115]
	v_mfma_f32_16x16x32_bf16 v[104:107], v[164:167], v[180:183], v[104:107]
	v_mfma_f32_16x16x32_bf16 v[96:99], v[152:155], v[188:191], v[96:99]
	v_mfma_f32_16x16x32_bf16 v[88:91], v[164:167], v[188:191], v[88:91]
	v_mfma_f32_16x16x32_bf16 v[80:83], v[152:155], v[196:199], v[80:83]
	v_mfma_f32_16x16x32_bf16 v[72:75], v[164:167], v[196:199], v[72:75]
	s_barrier
	s_add_i32 s48, 0, 0x1c000
	s_add_i32 s42, s68, s23
	v_add_u32_e32 v212, s48, v143
	s_mov_b32 m0, s42
	ds_read_b128 v[200:203], v212
	ds_read_b128 v[204:207], v212 offset:1024
	ds_read_b128 v[208:211], v212 offset:2048
	global_load_lds_dwordx4 v132, s[98:99]
	s_add_i32 m0, s42, 0x2000
	ds_read_b128 v[212:215], v212 offset:3072
	global_load_lds_dwordx4 v128, s[98:99]
	s_barrier
	s_waitcnt lgkmcnt(0)
	v_mfma_f32_16x16x32_bf16 v[116:119], v[200:203], v[168:171], v[116:119]
	v_mfma_f32_16x16x32_bf16 v[108:111], v[208:211], v[168:171], v[108:111]
	v_mfma_f32_16x16x32_bf16 v[100:103], v[200:203], v[176:179], v[100:103]
	v_mfma_f32_16x16x32_bf16 v[92:95], v[208:211], v[176:179], v[92:95]
	v_mfma_f32_16x16x32_bf16 v[84:87], v[200:203], v[184:187], v[84:87]
	v_mfma_f32_16x16x32_bf16 v[76:79], v[208:211], v[184:187], v[76:79]
	v_mfma_f32_16x16x32_bf16 v[68:71], v[200:203], v[192:195], v[68:71]
	v_mfma_f32_16x16x32_bf16 v[64:67], v[208:211], v[192:195], v[64:67]
	v_mfma_f32_16x16x32_bf16 v[116:119], v[204:207], v[172:175], v[116:119]
	v_mfma_f32_16x16x32_bf16 v[108:111], v[212:215], v[172:175], v[108:111]
	v_mfma_f32_16x16x32_bf16 v[100:103], v[204:207], v[180:183], v[100:103]
	v_mfma_f32_16x16x32_bf16 v[92:95], v[212:215], v[180:183], v[92:95]
	v_mfma_f32_16x16x32_bf16 v[84:87], v[204:207], v[188:191], v[84:87]
	v_mfma_f32_16x16x32_bf16 v[76:79], v[212:215], v[188:191], v[76:79]
	v_mfma_f32_16x16x32_bf16 v[68:71], v[204:207], v[196:199], v[68:71]
	v_mfma_f32_16x16x32_bf16 v[64:67], v[212:215], v[196:199], v[64:67]
	s_mov_b32 m0, s52
	s_barrier
	ds_read_b128 v[168:171], v146 offset:49152
	ds_read_b128 v[172:175], v146 offset:50176
	ds_read_b128 v[176:179], v146 offset:51200
	ds_read_b128 v[180:183], v146 offset:52224
	ds_read_b128 v[184:187], v146 offset:53248
	ds_read_b128 v[188:191], v146 offset:54272
	ds_read_b128 v[192:195], v146 offset:55296
	global_load_lds_dwordx4 v134, s[100:101]
	s_mov_b32 m0, s53
	ds_read_b128 v[196:199], v146 offset:56320
	global_load_lds_dwordx4 v130, s[100:101]
	s_barrier
	s_waitcnt lgkmcnt(0)
	v_mfma_f32_16x16x32_bf16 v[60:63], v[148:151], v[168:171], v[60:63]
	v_mfma_f32_16x16x32_bf16 v[56:59], v[160:163], v[168:171], v[56:59]
	v_mfma_f32_16x16x32_bf16 v[52:55], v[148:151], v[176:179], v[52:55]
	v_mfma_f32_16x16x32_bf16 v[44:47], v[160:163], v[176:179], v[44:47]
	v_mfma_f32_16x16x32_bf16 v[36:39], v[148:151], v[184:187], v[36:39]
	v_mfma_f32_16x16x32_bf16 v[28:31], v[160:163], v[184:187], v[28:31]
	v_mfma_f32_16x16x32_bf16 v[20:23], v[148:151], v[192:195], v[20:23]
	v_mfma_f32_16x16x32_bf16 v[12:15], v[160:163], v[192:195], v[12:15]
	v_mfma_f32_16x16x32_bf16 v[60:63], v[152:155], v[172:175], v[60:63]
	v_mfma_f32_16x16x32_bf16 v[56:59], v[164:167], v[172:175], v[56:59]
	v_mfma_f32_16x16x32_bf16 v[52:55], v[152:155], v[180:183], v[52:55]
	v_mfma_f32_16x16x32_bf16 v[44:47], v[164:167], v[180:183], v[44:47]
	v_mfma_f32_16x16x32_bf16 v[36:39], v[152:155], v[188:191], v[36:39]
	v_mfma_f32_16x16x32_bf16 v[28:31], v[164:167], v[188:191], v[28:31]
	v_mfma_f32_16x16x32_bf16 v[20:23], v[152:155], v[196:199], v[20:23]
	v_mfma_f32_16x16x32_bf16 v[12:15], v[164:167], v[196:199], v[12:15]
	s_barrier
; #define PG8_MMA(ai, bj, At, Bt) do { __builtin_amdgcn_s_setprio(1); _Pragma("unroll") for (int m = 0; m < 4; ++m) _Pragma("unroll") for (int n = 0; n < 2; ++n) _Pragma("unroll") for (int k = 0; k < 2; ++k) \
;         acc[ai][bj][m][n] = __builtin_amdgcn_mfma_f32_16x16x32_bf16(Bt[n][k], At[m][k], acc[ai][bj][m][n], 0, 0, 0); __builtin_amdgcn_s_setprio(0); } while (0)
; #define PG8_WAIT_V(n) asm volatile("s_waitcnt vmcnt(" #n ")" ::: "memory")
; #define PG8_BAR __builtin_amdgcn_s_barrier()
; __device__ __forceinline__ u32x4 pack8(f32x4 v0, f32x4 v1) { u32x4 w; w.x = cvt_pk_bf16(v0[0], v0[1]); w.y = cvt_pk_bf16(v0[2], v0[3]); w.z = cvt_pk_bf16(v1[0], v1[1]); w.w = cvt_pk_bf16(v1[2], v1[3]); return w; }
; template <class Epi>
; __device__ __forceinline__ void gemm_phase(LAS unsigned char* lds, const Gemm g, const StaticOrder& S, const Epi& E) {
;     ...
;             PG8_WAIT_V(6); PG8_BAR; PG8_MMA(1, 1, At, B1); PG8_BAR;
;         }
;     __device__ __forceinline__ void operator()(const f32x4 (&acc)[2][2][4][2], const Unit& u, int wr, int wc, int fr, int fq) const {
;         const int row0 = u.pm * BM + wr * 64 + fr, col0 = u.pn * BM + wc * 32 + 8 * fq;
; #pragma unroll
;         for (int ai = 0; ai < 2; ++ai)
; #pragma unroll
;             for (int m = 0; m < 4; ++m) { bf16_t* rowp = O + (size_t)(row0 + ai * HALF + m * 16) * ldc + col0;
; #pragma unroll
;                 for (int bj = 0; bj < 2; ++bj) *(u32x4*)(rowp + bj * HALF) = pack8(acc[ai][bj][m][0], acc[ai][bj][m][1]); }
	s_add_u32 s42, s46, 0x160080
	s_addc_u32 s43, s47, 0
	s_add_i32 s46, s48, s23
	s_mov_b32 m0, s46
	s_nop 0
	global_load_lds_dwordx4 v132, s[42:43]
	s_add_i32 m0, s46, 0x2000
	s_nop 0
	global_load_lds_dwordx4 v128, s[42:43]
	s_waitcnt vmcnt(6)
	s_barrier
	v_mfma_f32_16x16x32_bf16 v[48:51], v[200:203], v[168:171], v[48:51]
	v_mfma_f32_16x16x32_bf16 v[40:43], v[208:211], v[168:171], v[40:43]
	v_mfma_f32_16x16x32_bf16 v[32:35], v[200:203], v[176:179], v[32:35]
	v_mfma_f32_16x16x32_bf16 v[24:27], v[208:211], v[176:179], v[24:27]
	v_mfma_f32_16x16x32_bf16 v[16:19], v[200:203], v[184:187], v[16:19]
	v_mfma_f32_16x16x32_bf16 v[8:11], v[208:211], v[184:187], v[8:11]
	v_mfma_f32_16x16x32_bf16 v[4:7], v[200:203], v[192:195], v[4:7]
	v_mfma_f32_16x16x32_bf16 v[0:3], v[208:211], v[192:195], v[0:3]
	v_mfma_f32_16x16x32_bf16 v[48:51], v[204:207], v[172:175], v[48:51]
	v_mfma_f32_16x16x32_bf16 v[40:43], v[212:215], v[172:175], v[40:43]
	v_mfma_f32_16x16x32_bf16 v[32:35], v[204:207], v[180:183], v[32:35]
	v_mfma_f32_16x16x32_bf16 v[24:27], v[212:215], v[180:183], v[24:27]
	v_mfma_f32_16x16x32_bf16 v[16:19], v[204:207], v[188:191], v[16:19]
	v_mfma_f32_16x16x32_bf16 v[8:11], v[212:215], v[188:191], v[8:11]
	v_mfma_f32_16x16x32_bf16 v[4:7], v[204:207], v[196:199], v[4:7]
	v_mfma_f32_16x16x32_bf16 v[0:3], v[212:215], v[196:199], v[0:3]
	s_add_i32 s67, s67, 2
	s_add_u32 s65, s65, 0x100
	s_addc_u32 s66, s66, 0
	s_cmpk_gt_u32 s67, 0x55
	s_mov_b64 s[42:43], s[44:45]
	s_barrier
	s_cbranch_scc0 .LBB0_864
	v_lshl_add_u32 v148, s63, 8, v142
	v_lshl_or_b32 v140, s64, 8, v144
	v_ashrrev_i32_e32 v149, 31, v148
	v_ashrrev_i32_e32 v141, 31, v140
	v_lshlrev_b64 v[150:151], 12, v[148:149]
	v_lshl_add_u64 v[150:151], s[24:25], 0, v[150:151]
	v_lshlrev_b64 v[152:153], 1, v[140:141]
	v_lshl_add_u64 v[140:141], v[150:151], 0, v[152:153]
	v_cvt_pk_bf16_f32 v124, v124, v125
	v_cvt_pk_bf16_f32 v125, v126, v127
	v_cvt_pk_bf16_f32 v126, v120, v121
	v_cvt_pk_bf16_f32 v127, v122, v123
	global_store_dwordx4 v[140:141], v[124:127], off
	v_cvt_pk_bf16_f32 v116, v116, v117
	v_cvt_pk_bf16_f32 v117, v118, v119
	v_cvt_pk_bf16_f32 v118, v108, v109
	v_or_b32_e32 v108, 16, v148
	v_ashrrev_i32_e32 v109, 31, v108
	v_lshlrev_b64 v[108:109], 12, v[108:109]
	v_lshl_add_u64 v[108:109], s[24:25], 0, v[108:109]
	v_cvt_pk_bf16_f32 v119, v110, v111
	global_store_dwordx4 v[140:141], v[116:119], off offset:256
	s_mov_b32 s64, s61
	s_mov_b32 s63, s62
	v_lshl_add_u64 v[116:117], v[108:109], 0, v[152:153]
	v_cvt_pk_bf16_f32 v108, v112, v113
	v_cvt_pk_bf16_f32 v109, v114, v115
	v_cvt_pk_bf16_f32 v110, v104, v105
	v_cvt_pk_bf16_f32 v111, v106, v107
	global_store_dwordx4 v[116:117], v[108:111], off
	v_cvt_pk_bf16_f32 v100, v100, v101
	v_cvt_pk_bf16_f32 v101, v102, v103
	v_cvt_pk_bf16_f32 v102, v92, v93
	v_or_b32_e32 v92, 32, v148
	v_ashrrev_i32_e32 v93, 31, v92
	v_lshlrev_b64 v[92:93], 12, v[92:93]
	v_lshl_add_u64 v[92:93], s[24:25], 0, v[92:93]
	v_cvt_pk_bf16_f32 v103, v94, v95
	global_store_dwordx4 v[116:117], v[100:103], off offset:256
	s_mov_b64 s[44:45], s[6:7]
	s_mov_b64 s[42:43], s[40:41]
	v_lshl_add_u64 v[100:101], v[92:93], 0, v[152:153]
	v_cvt_pk_bf16_f32 v92, v96, v97
	v_cvt_pk_bf16_f32 v93, v98, v99
	v_cvt_pk_bf16_f32 v94, v88, v89
	v_cvt_pk_bf16_f32 v95, v90, v91
	global_store_dwordx4 v[100:101], v[92:95], off
	v_cvt_pk_bf16_f32 v84, v84, v85
	v_cvt_pk_bf16_f32 v85, v86, v87
	v_cvt_pk_bf16_f32 v86, v76, v77
	v_or_b32_e32 v76, 48, v148
	v_ashrrev_i32_e32 v77, 31, v76
	v_lshlrev_b64 v[76:77], 12, v[76:77]
	v_lshl_add_u64 v[76:77], s[24:25], 0, v[76:77]
	v_cvt_pk_bf16_f32 v87, v78, v79
	global_store_dwordx4 v[100:101], v[84:87], off offset:256
	s_nop 1
	v_lshl_add_u64 v[84:85], v[76:77], 0, v[152:153]
	v_cvt_pk_bf16_f32 v76, v80, v81
	v_cvt_pk_bf16_f32 v77, v82, v83
	v_cvt_pk_bf16_f32 v78, v72, v73
	v_cvt_pk_bf16_f32 v79, v74, v75
	global_store_dwordx4 v[84:85], v[76:79], off
	v_cvt_pk_bf16_f32 v68, v68, v69
	v_cvt_pk_bf16_f32 v69, v70, v71
	v_cvt_pk_bf16_f32 v70, v64, v65
	v_cvt_pk_bf16_f32 v71, v66, v67
	global_store_dwordx4 v[84:85], v[68:71], off offset:256
	v_cvt_pk_bf16_f32 v60, v60, v61
	v_cvt_pk_bf16_f32 v61, v62, v63
	v_cvt_pk_bf16_f32 v62, v56, v57
	v_add_co_u32_e32 v56, vcc, s57, v140
	v_lshl_add_u64 v[64:65], v[140:141], 0, s[8:9]
	s_nop 0
	v_addc_co_u32_e32 v57, vcc, 0, v141, vcc
	v_cvt_pk_bf16_f32 v63, v58, v59
	global_store_dwordx4 v[56:57], v[60:63], off
	v_cvt_pk_bf16_f32 v48, v48, v49
	v_cvt_pk_bf16_f32 v49, v50, v51
	v_cvt_pk_bf16_f32 v50, v40, v41
	v_cvt_pk_bf16_f32 v51, v42, v43
	global_store_dwordx4 v[64:65], v[48:51], off offset:256
	v_cvt_pk_bf16_f32 v40, v52, v53
	v_cvt_pk_bf16_f32 v41, v54, v55
	v_cvt_pk_bf16_f32 v42, v44, v45
	v_add_co_u32_e32 v44, vcc, s58, v140
	s_nop 0
	v_lshl_add_u64 v[48:49], v[140:141], 0, s[30:31]
	v_addc_co_u32_e32 v45, vcc, 0, v141, vcc
	v_cvt_pk_bf16_f32 v43, v46, v47
	global_store_dwordx4 v[44:45], v[40:43], off
	v_cvt_pk_bf16_f32 v32, v32, v33
	v_cvt_pk_bf16_f32 v33, v34, v35
	v_cvt_pk_bf16_f32 v34, v24, v25
	v_cvt_pk_bf16_f32 v35, v26, v27
	global_store_dwordx4 v[48:49], v[32:35], off offset:256
	v_cvt_pk_bf16_f32 v24, v36, v37
	v_cvt_pk_bf16_f32 v25, v38, v39
	v_cvt_pk_bf16_f32 v26, v28, v29
	v_add_co_u32_e32 v28, vcc, s59, v140
	s_nop 0
	v_lshl_add_u64 v[32:33], v[140:141], 0, s[34:35]
	v_addc_co_u32_e32 v29, vcc, 0, v141, vcc
	v_cvt_pk_bf16_f32 v27, v30, v31
	global_store_dwordx4 v[28:29], v[24:27], off
	v_cvt_pk_bf16_f32 v16, v16, v17
	v_cvt_pk_bf16_f32 v17, v18, v19
	v_cvt_pk_bf16_f32 v18, v8, v9
	v_cvt_pk_bf16_f32 v19, v10, v11
	global_store_dwordx4 v[32:33], v[16:19], off offset:256
	v_cvt_pk_bf16_f32 v8, v20, v21
	v_cvt_pk_bf16_f32 v9, v22, v23
	v_cvt_pk_bf16_f32 v10, v12, v13
	v_add_co_u32_e32 v12, vcc, s60, v140
	s_nop 0
	v_lshl_add_u64 v[16:17], v[140:141], 0, s[36:37]
	v_addc_co_u32_e32 v13, vcc, 0, v141, vcc
	s_and_b64 vcc, exec, s[38:39]
	v_cvt_pk_bf16_f32 v11, v14, v15
	global_store_dwordx4 v[12:13], v[8:11], off
	v_cvt_pk_bf16_f32 v4, v4, v5
	v_cvt_pk_bf16_f32 v5, v6, v7
	v_cvt_pk_bf16_f32 v6, v0, v1
	v_cvt_pk_bf16_f32 v7, v2, v3
	global_store_dwordx4 v[16:17], v[4:7], off offset:256
	s_cbranch_vccz .LBB0_857
	s_waitcnt vmcnt(0)
	s_cmpk_gt_u32 s10, 0xff
	v_readlane_b32 s62, v232, 20
	v_readlane_b32 s61, v232, 21
	s_cbranch_scc1 .LBB0_868
	s_barrier

; #define PG8_STAGE(bufoff, gbase, voff) do { _Pragma("unroll") for (int _i = 0; _i < 2; ++_i) \
;         __builtin_amdgcn_global_load_lds((const unsigned*)((const char*)(gbase) + (voff)[_i]), (LAS unsigned*)(lds + (bufoff) + ldsw + _i * 8192), 16, 0, 0); } while (0)
; #define PG8_LDA(dst, b, h) do { _Pragma("unroll") for (int m = 0; m < 4; ++m) _Pragma("unroll") for (int k = 0; k < 2; ++k) dst[m][k] = *(const LAS bf16x8*)(lds + PG8_SA(b, h) + aoff + m * 2048 + k * 1024); } while (0)
; #define PG8_LDB(dst, b, h) do { _Pragma("unroll") for (int n = 0; n < 2; ++n) _Pragma("unroll") for (int k = 0; k < 2; ++k) dst[n][k] = *(const LAS bf16x8*)(lds + PG8_SB(b, h) + boff + n * 2048 + k * 1024); } while (0)
; #define PG8_MMA(ai, bj, At, Bt) do { __builtin_amdgcn_s_setprio(1); _Pragma("unroll") for (int m = 0; m < 4; ++m) _Pragma("unroll") for (int n = 0; n < 2; ++n) _Pragma("unroll") for (int k = 0; k < 2; ++k) \
;         acc[ai][bj][m][n] = __builtin_amdgcn_mfma_f32_16x16x32_bf16(Bt[n][k], At[m][k], acc[ai][bj][m][n], 0, 0, 0); __builtin_amdgcn_s_setprio(0); } while (0)
; #define PG8_WAIT_V(n) asm volatile("s_waitcnt vmcnt(" #n ")" ::: "memory")
; #define PG8_WAIT_L(n) asm volatile("s_waitcnt lgkmcnt(" #n ")" ::: "memory")
; template <class Epi>
; __device__ __forceinline__ void gemm_phase(LAS unsigned char* lds, const Gemm g, const StaticOrder& S, const Epi& E) {
;     ...
;         for (int t = 0; t < nt; t += 2) {
;             const bool last = (t == nt - 2);
;             const char* a1 = cA + (size_t)(t + 1) * kstep;
;             const char* a2 = last ? nA : cA + (size_t)(t + 2) * kstep; const char* b2 = last ? nB : cB + (size_t)(t + 2) * kstep;
;             const char* a3 = a2 + kstep; const char* b3 = b2 + kstep;
;             PG8_LDB(B0, 0, 0); PG8_SCHED; PG8_LDA(At, 0, 0); PG8_STAGE(PG8_SA(1, 1), a1 + hstep, voffA);
;             PG8_WAIT_L(8); PG8_BAR; PG8_WAIT_L(0); PG8_MMA(0, 0, At, B0); PG8_BAR; PG8_SCHED;
;             PG8_LDB(B1, 0, 1); PG8_STAGE(PG8_SB(0, 0), b2, voffB);
;             PG8_BAR; PG8_WAIT_L(0); PG8_MMA(0, 1, At, B1); PG8_BAR;
;             PG8_LDA(At, 0, 1); PG8_STAGE(PG8_SA(0, 0), a2, voffA);
;             PG8_BAR; PG8_WAIT_L(0); PG8_MMA(1, 0, At, B0); PG8_BAR; PG8_SCHED;
;             PG8_STAGE(PG8_SB(0, 1), b2 + hstep, voffB);
;             PG8_WAIT_V(6); PG8_BAR; PG8_MMA(1, 1, At, B1); PG8_BAR;
.LBB0_999:
	ds_read_b128 v[140:143], v151
	ds_read_b128 v[144:147], v151 offset:1024
	ds_read_b128 v[154:157], v151 offset:2048
	ds_read_b128 v[160:163], v151 offset:3072
	s_add_u32 s48, s46, 0xfff80080
	s_addc_u32 s49, s47, -1
	s_cmp_eq_u32 s63, 28
	s_cselect_b32 s51, s37, s49
	s_cselect_b32 s50, s59, s48
	s_cselect_b32 s49, s35, s62
	s_cselect_b32 s48, s60, s61
	s_add_i32 m0, s28, 0xc000
	ds_read_b128 v[164:167], v152
	ds_read_b128 v[168:171], v152 offset:1024
	ds_read_b128 v[172:175], v152 offset:2048
	ds_read_b128 v[176:179], v152 offset:3072
	ds_read_b128 v[180:183], v152 offset:4096
	ds_read_b128 v[184:187], v152 offset:5120
	ds_read_b128 v[188:191], v152 offset:6144
	global_load_lds_dwordx4 v136, s[46:47]
	s_add_i32 m0, s28, 0xe000
	ds_read_b128 v[192:195], v152 offset:7168
	global_load_lds_dwordx4 v138, s[46:47]
	s_waitcnt lgkmcnt(8)
	s_barrier
	s_waitcnt lgkmcnt(0)
	v_mfma_f32_16x16x32_bf16 v[124:127], v[140:143], v[164:167], v[124:127]
	v_mfma_f32_16x16x32_bf16 v[120:123], v[154:157], v[164:167], v[120:123]
	v_mfma_f32_16x16x32_bf16 v[108:111], v[140:143], v[172:175], v[108:111]
	v_mfma_f32_16x16x32_bf16 v[104:107], v[154:157], v[172:175], v[104:107]
	v_mfma_f32_16x16x32_bf16 v[92:95], v[140:143], v[180:183], v[92:95]
	v_mfma_f32_16x16x32_bf16 v[88:91], v[154:157], v[180:183], v[88:91]
	v_mfma_f32_16x16x32_bf16 v[76:79], v[140:143], v[188:191], v[76:79]
	v_mfma_f32_16x16x32_bf16 v[72:75], v[154:157], v[188:191], v[72:75]
	v_mfma_f32_16x16x32_bf16 v[124:127], v[144:147], v[168:171], v[124:127]
	v_mfma_f32_16x16x32_bf16 v[120:123], v[160:163], v[168:171], v[120:123]
	v_mfma_f32_16x16x32_bf16 v[108:111], v[144:147], v[176:179], v[108:111]
	v_mfma_f32_16x16x32_bf16 v[104:107], v[160:163], v[176:179], v[104:107]
	v_mfma_f32_16x16x32_bf16 v[92:95], v[144:147], v[184:187], v[92:95]
	v_mfma_f32_16x16x32_bf16 v[88:91], v[160:163], v[184:187], v[88:91]
	v_mfma_f32_16x16x32_bf16 v[76:79], v[144:147], v[192:195], v[76:79]
	v_mfma_f32_16x16x32_bf16 v[72:75], v[160:163], v[192:195], v[72:75]
	s_barrier
	s_add_i32 s64, s56, s23
	s_add_u32 s98, s48, s4
	s_addc_u32 s99, s49, s5
	s_mov_b32 m0, s64
	ds_read_b128 v[196:199], v153
	ds_read_b128 v[200:203], v153 offset:1024
	ds_read_b128 v[204:207], v153 offset:2048
	global_load_lds_dwordx4 v132, s[48:49]
	s_add_i32 m0, s64, 0x2000
	ds_read_b128 v[208:211], v153 offset:3072
	global_load_lds_dwordx4 v128, s[48:49]
	s_barrier
	s_waitcnt lgkmcnt(0)
	v_mfma_f32_16x16x32_bf16 v[116:119], v[196:199], v[164:167], v[116:119]
	v_mfma_f32_16x16x32_bf16 v[112:115], v[204:207], v[164:167], v[112:115]
	v_mfma_f32_16x16x32_bf16 v[100:103], v[196:199], v[172:175], v[100:103]
	v_mfma_f32_16x16x32_bf16 v[96:99], v[204:207], v[172:175], v[96:99]
	v_mfma_f32_16x16x32_bf16 v[84:87], v[196:199], v[180:183], v[84:87]
	v_mfma_f32_16x16x32_bf16 v[80:83], v[204:207], v[180:183], v[80:83]
	v_mfma_f32_16x16x32_bf16 v[68:71], v[196:199], v[188:191], v[68:71]
	v_mfma_f32_16x16x32_bf16 v[64:67], v[204:207], v[188:191], v[64:67]
	v_mfma_f32_16x16x32_bf16 v[116:119], v[200:203], v[168:171], v[116:119]
	v_mfma_f32_16x16x32_bf16 v[112:115], v[208:211], v[168:171], v[112:115]
	v_mfma_f32_16x16x32_bf16 v[100:103], v[200:203], v[176:179], v[100:103]
	v_mfma_f32_16x16x32_bf16 v[96:99], v[208:211], v[176:179], v[96:99]
	v_mfma_f32_16x16x32_bf16 v[84:87], v[200:203], v[184:187], v[84:87]
	v_mfma_f32_16x16x32_bf16 v[80:83], v[208:211], v[184:187], v[80:83]
	v_mfma_f32_16x16x32_bf16 v[68:71], v[200:203], v[192:195], v[68:71]
	v_mfma_f32_16x16x32_bf16 v[64:67], v[208:211], v[192:195], v[64:67]
	s_mov_b32 m0, s28
	s_add_u32 s100, s50, s4
	s_addc_u32 s101, s51, s5
	s_barrier
	ds_read_b128 v[164:167], v152 offset:16384
	ds_read_b128 v[168:171], v152 offset:17408
	ds_read_b128 v[172:175], v152 offset:18432
	ds_read_b128 v[176:179], v152 offset:19456
	ds_read_b128 v[180:183], v152 offset:20480
	ds_read_b128 v[184:187], v152 offset:21504
	ds_read_b128 v[188:191], v152 offset:22528
	global_load_lds_dwordx4 v134, s[50:51]
	s_mov_b32 m0, s29
	ds_read_b128 v[192:195], v152 offset:23552
	global_load_lds_dwordx4 v130, s[50:51]
	s_barrier
	s_waitcnt lgkmcnt(0)
	v_mfma_f32_16x16x32_bf16 v[60:63], v[140:143], v[164:167], v[60:63]
	v_mfma_f32_16x16x32_bf16 v[56:59], v[154:157], v[164:167], v[56:59]
	v_mfma_f32_16x16x32_bf16 v[44:47], v[140:143], v[172:175], v[44:47]
	v_mfma_f32_16x16x32_bf16 v[40:43], v[154:157], v[172:175], v[40:43]
	v_mfma_f32_16x16x32_bf16 v[28:31], v[140:143], v[180:183], v[28:31]
	v_mfma_f32_16x16x32_bf16 v[24:27], v[154:157], v[180:183], v[24:27]
	v_mfma_f32_16x16x32_bf16 v[12:15], v[140:143], v[188:191], v[12:15]
	v_mfma_f32_16x16x32_bf16 v[8:11], v[154:157], v[188:191], v[8:11]
	v_mfma_f32_16x16x32_bf16 v[60:63], v[144:147], v[168:171], v[60:63]
	v_mfma_f32_16x16x32_bf16 v[56:59], v[160:163], v[168:171], v[56:59]
	v_mfma_f32_16x16x32_bf16 v[44:47], v[144:147], v[176:179], v[44:47]
	v_mfma_f32_16x16x32_bf16 v[40:43], v[160:163], v[176:179], v[40:43]
	v_mfma_f32_16x16x32_bf16 v[28:31], v[144:147], v[184:187], v[28:31]
	v_mfma_f32_16x16x32_bf16 v[24:27], v[160:163], v[184:187], v[24:27]
	v_mfma_f32_16x16x32_bf16 v[12:15], v[144:147], v[192:195], v[12:15]
	v_mfma_f32_16x16x32_bf16 v[8:11], v[160:163], v[192:195], v[8:11]
	s_barrier
	s_add_u32 s64, s48, 0x80000
	s_addc_u32 s65, s49, 0
	s_add_i32 s66, s57, s23
	s_mov_b32 m0, s66
	s_nop 0
	global_load_lds_dwordx4 v132, s[64:65]
	s_add_i32 m0, s66, 0x2000
	s_nop 0
	global_load_lds_dwordx4 v128, s[64:65]
	s_waitcnt vmcnt(6)
	s_barrier
; #define PG8_STAGE(bufoff, gbase, voff) do { _Pragma("unroll") for (int _i = 0; _i < 2; ++_i) \
;         __builtin_amdgcn_global_load_lds((const unsigned*)((const char*)(gbase) + (voff)[_i]), (LAS unsigned*)(lds + (bufoff) + ldsw + _i * 8192), 16, 0, 0); } while (0)
; #define PG8_LDA(dst, b, h) do { _Pragma("unroll") for (int m = 0; m < 4; ++m) _Pragma("unroll") for (int k = 0; k < 2; ++k) dst[m][k] = *(const LAS bf16x8*)(lds + PG8_SA(b, h) + aoff + m * 2048 + k * 1024); } while (0)
; #define PG8_LDB(dst, b, h) do { _Pragma("unroll") for (int n = 0; n < 2; ++n) _Pragma("unroll") for (int k = 0; k < 2; ++k) dst[n][k] = *(const LAS bf16x8*)(lds + PG8_SB(b, h) + boff + n * 2048 + k * 1024); } while (0)
; #define PG8_MMA(ai, bj, At, Bt) do { __builtin_amdgcn_s_setprio(1); _Pragma("unroll") for (int m = 0; m < 4; ++m) _Pragma("unroll") for (int n = 0; n < 2; ++n) _Pragma("unroll") for (int k = 0; k < 2; ++k) \
;         acc[ai][bj][m][n] = __builtin_amdgcn_mfma_f32_16x16x32_bf16(Bt[n][k], At[m][k], acc[ai][bj][m][n], 0, 0, 0); __builtin_amdgcn_s_setprio(0); } while (0)
; #define PG8_WAIT_V(n) asm volatile("s_waitcnt vmcnt(" #n ")" ::: "memory")
; #define PG8_WAIT_L(n) asm volatile("s_waitcnt lgkmcnt(" #n ")" ::: "memory")
; #define PG8_BAR __builtin_amdgcn_s_barrier()
; #define PG8_SCHED __builtin_amdgcn_sched_barrier(0)
; template <class Epi>
; __device__ __forceinline__ void gemm_phase(LAS unsigned char* lds, const Gemm g, const StaticOrder& S, const Epi& E) {
;     ...
;             PG8_WAIT_V(6); PG8_BAR; PG8_MMA(1, 1, At, B1); PG8_BAR;
;             PG8_LDB(B0, 1, 0); PG8_SCHED; PG8_LDA(At, 1, 0); PG8_STAGE(PG8_SA(0, 1), a2 + hstep, voffA);
;             PG8_WAIT_L(8); PG8_BAR; PG8_WAIT_L(0); PG8_MMA(0, 0, At, B0); PG8_BAR; PG8_SCHED;
;             PG8_LDB(B1, 1, 1); PG8_STAGE(PG8_SB(1, 0), b3, voffB);
;             PG8_BAR; PG8_WAIT_L(0); PG8_MMA(0, 1, At, B1); PG8_BAR;
;             PG8_LDA(At, 1, 1); PG8_STAGE(PG8_SA(1, 0), a3, voffA);
;             PG8_BAR; PG8_WAIT_L(0); PG8_MMA(1, 0, At, B0); PG8_BAR; PG8_SCHED;
;             PG8_STAGE(PG8_SB(1, 1), b3 + hstep, voffB);
;             PG8_WAIT_V(6); PG8_BAR; PG8_MMA(1, 1, At, B1); PG8_BAR;
	v_mfma_f32_16x16x32_bf16 v[52:55], v[196:199], v[164:167], v[52:55]
	v_mfma_f32_16x16x32_bf16 v[48:51], v[204:207], v[164:167], v[48:51]
	v_mfma_f32_16x16x32_bf16 v[36:39], v[196:199], v[172:175], v[36:39]
	v_mfma_f32_16x16x32_bf16 v[32:35], v[204:207], v[172:175], v[32:35]
	v_mfma_f32_16x16x32_bf16 v[20:23], v[196:199], v[180:183], v[20:23]
	v_mfma_f32_16x16x32_bf16 v[16:19], v[204:207], v[180:183], v[16:19]
	v_mfma_f32_16x16x32_bf16 v[4:7], v[196:199], v[188:191], v[4:7]
	v_mfma_f32_16x16x32_bf16 v[0:3], v[204:207], v[188:191], v[0:3]
	v_mfma_f32_16x16x32_bf16 v[52:55], v[200:203], v[168:171], v[52:55]
	v_mfma_f32_16x16x32_bf16 v[48:51], v[208:211], v[168:171], v[48:51]
	v_mfma_f32_16x16x32_bf16 v[36:39], v[200:203], v[176:179], v[36:39]
	v_mfma_f32_16x16x32_bf16 v[32:35], v[208:211], v[176:179], v[32:35]
	v_mfma_f32_16x16x32_bf16 v[20:23], v[200:203], v[184:187], v[20:23]
	v_mfma_f32_16x16x32_bf16 v[16:19], v[208:211], v[184:187], v[16:19]
	v_mfma_f32_16x16x32_bf16 v[4:7], v[200:203], v[192:195], v[4:7]
	v_mfma_f32_16x16x32_bf16 v[0:3], v[208:211], v[192:195], v[0:3]
	s_add_i32 s64, 0, 0x18000
	v_add_u32_e32 v160, s64, v149
	s_barrier
	ds_read_b128 v[140:143], v160
	ds_read_b128 v[144:147], v160 offset:1024
	ds_read_b128 v[154:157], v160 offset:2048
	ds_read_b128 v[160:163], v160 offset:3072
	s_add_u32 s50, s50, 0x80000
	s_addc_u32 s51, s51, 0
	s_mov_b32 m0, s33
	ds_read_b128 v[164:167], v152 offset:32768
	ds_read_b128 v[168:171], v152 offset:33792
	ds_read_b128 v[172:175], v152 offset:34816
	ds_read_b128 v[176:179], v152 offset:35840
	ds_read_b128 v[180:183], v152 offset:36864
	ds_read_b128 v[184:187], v152 offset:37888
	ds_read_b128 v[188:191], v152 offset:38912
	global_load_lds_dwordx4 v134, s[50:51]
	s_mov_b32 m0, s45
	ds_read_b128 v[192:195], v152 offset:39936
	global_load_lds_dwordx4 v130, s[50:51]
	s_waitcnt lgkmcnt(8)
	s_barrier
	s_waitcnt lgkmcnt(0)
	v_mfma_f32_16x16x32_bf16 v[124:127], v[140:143], v[164:167], v[124:127]
	v_mfma_f32_16x16x32_bf16 v[120:123], v[154:157], v[164:167], v[120:123]
	v_mfma_f32_16x16x32_bf16 v[108:111], v[140:143], v[172:175], v[108:111]
	v_mfma_f32_16x16x32_bf16 v[104:107], v[154:157], v[172:175], v[104:107]
	v_mfma_f32_16x16x32_bf16 v[92:95], v[140:143], v[180:183], v[92:95]
	v_mfma_f32_16x16x32_bf16 v[88:91], v[154:157], v[180:183], v[88:91]
	v_mfma_f32_16x16x32_bf16 v[76:79], v[140:143], v[188:191], v[76:79]
	v_mfma_f32_16x16x32_bf16 v[72:75], v[154:157], v[188:191], v[72:75]
	v_mfma_f32_16x16x32_bf16 v[124:127], v[144:147], v[168:171], v[124:127]
	v_mfma_f32_16x16x32_bf16 v[120:123], v[160:163], v[168:171], v[120:123]
	v_mfma_f32_16x16x32_bf16 v[108:111], v[144:147], v[176:179], v[108:111]
	v_mfma_f32_16x16x32_bf16 v[104:107], v[160:163], v[176:179], v[104:107]
	v_mfma_f32_16x16x32_bf16 v[92:95], v[144:147], v[184:187], v[92:95]
	v_mfma_f32_16x16x32_bf16 v[88:91], v[160:163], v[184:187], v[88:91]
	v_mfma_f32_16x16x32_bf16 v[76:79], v[144:147], v[192:195], v[76:79]
	v_mfma_f32_16x16x32_bf16 v[72:75], v[160:163], v[192:195], v[72:75]
	s_barrier
	s_add_i32 s50, 0, 0x1c000
	s_add_i32 s51, s64, s23
	v_add_u32_e32 v208, s50, v149
	s_mov_b32 m0, s51
	ds_read_b128 v[196:199], v208
	ds_read_b128 v[200:203], v208 offset:1024
	ds_read_b128 v[204:207], v208 offset:2048
	global_load_lds_dwordx4 v132, s[98:99]
	s_add_i32 m0, s51, 0x2000
	ds_read_b128 v[208:211], v208 offset:3072
	global_load_lds_dwordx4 v128, s[98:99]
	s_barrier
	s_waitcnt lgkmcnt(0)
	v_mfma_f32_16x16x32_bf16 v[116:119], v[196:199], v[164:167], v[116:119]
	v_mfma_f32_16x16x32_bf16 v[112:115], v[204:207], v[164:167], v[112:115]
	v_mfma_f32_16x16x32_bf16 v[100:103], v[196:199], v[172:175], v[100:103]
	v_mfma_f32_16x16x32_bf16 v[96:99], v[204:207], v[172:175], v[96:99]
	v_mfma_f32_16x16x32_bf16 v[84:87], v[196:199], v[180:183], v[84:87]
	v_mfma_f32_16x16x32_bf16 v[80:83], v[204:207], v[180:183], v[80:83]
	v_mfma_f32_16x16x32_bf16 v[68:71], v[196:199], v[188:191], v[68:71]
	v_mfma_f32_16x16x32_bf16 v[64:67], v[204:207], v[188:191], v[64:67]
	v_mfma_f32_16x16x32_bf16 v[116:119], v[200:203], v[168:171], v[116:119]
	v_mfma_f32_16x16x32_bf16 v[112:115], v[208:211], v[168:171], v[112:115]
	v_mfma_f32_16x16x32_bf16 v[100:103], v[200:203], v[176:179], v[100:103]
	v_mfma_f32_16x16x32_bf16 v[96:99], v[208:211], v[176:179], v[96:99]
	v_mfma_f32_16x16x32_bf16 v[84:87], v[200:203], v[184:187], v[84:87]
	v_mfma_f32_16x16x32_bf16 v[80:83], v[208:211], v[184:187], v[80:83]
	v_mfma_f32_16x16x32_bf16 v[68:71], v[200:203], v[192:195], v[68:71]
	v_mfma_f32_16x16x32_bf16 v[64:67], v[208:211], v[192:195], v[64:67]
	s_mov_b32 m0, s53
	s_barrier
	ds_read_b128 v[164:167], v152 offset:49152
	ds_read_b128 v[168:171], v152 offset:50176
	ds_read_b128 v[172:175], v152 offset:51200
	ds_read_b128 v[176:179], v152 offset:52224
	ds_read_b128 v[180:183], v152 offset:53248
	ds_read_b128 v[184:187], v152 offset:54272
	ds_read_b128 v[188:191], v152 offset:55296
	global_load_lds_dwordx4 v134, s[100:101]
	s_mov_b32 m0, s54
	ds_read_b128 v[192:195], v152 offset:56320
	global_load_lds_dwordx4 v130, s[100:101]
	s_barrier
	s_waitcnt lgkmcnt(0)
	v_mfma_f32_16x16x32_bf16 v[60:63], v[140:143], v[164:167], v[60:63]
	v_mfma_f32_16x16x32_bf16 v[56:59], v[154:157], v[164:167], v[56:59]
	v_mfma_f32_16x16x32_bf16 v[44:47], v[140:143], v[172:175], v[44:47]
	v_mfma_f32_16x16x32_bf16 v[40:43], v[154:157], v[172:175], v[40:43]
	v_mfma_f32_16x16x32_bf16 v[28:31], v[140:143], v[180:183], v[28:31]
	v_mfma_f32_16x16x32_bf16 v[24:27], v[154:157], v[180:183], v[24:27]
	v_mfma_f32_16x16x32_bf16 v[12:15], v[140:143], v[188:191], v[12:15]
	v_mfma_f32_16x16x32_bf16 v[8:11], v[154:157], v[188:191], v[8:11]
	v_mfma_f32_16x16x32_bf16 v[60:63], v[144:147], v[168:171], v[60:63]
	v_mfma_f32_16x16x32_bf16 v[56:59], v[160:163], v[168:171], v[56:59]
	v_mfma_f32_16x16x32_bf16 v[44:47], v[144:147], v[176:179], v[44:47]
	v_mfma_f32_16x16x32_bf16 v[40:43], v[160:163], v[176:179], v[40:43]
	v_mfma_f32_16x16x32_bf16 v[28:31], v[144:147], v[184:187], v[28:31]
	v_mfma_f32_16x16x32_bf16 v[24:27], v[160:163], v[184:187], v[24:27]
	v_mfma_f32_16x16x32_bf16 v[12:15], v[144:147], v[192:195], v[12:15]
	v_mfma_f32_16x16x32_bf16 v[8:11], v[160:163], v[192:195], v[8:11]
	s_barrier
; __device__ __forceinline__ float bf_lo(unsigned w) { return __uint_as_float(w << 16); }
; __device__ __forceinline__ float bf_hi(unsigned w) { return __uint_as_float(w & 0xffff0000u); }
; __device__ __forceinline__ float fast_rcp(float x) { return __builtin_amdgcn_rcpf(x); }
; __device__ __forceinline__ float fast_exp2(float x) { return __builtin_amdgcn_exp2f(x); }
; #define PG8_MMA(ai, bj, At, Bt) do { __builtin_amdgcn_s_setprio(1); _Pragma("unroll") for (int m = 0; m < 4; ++m) _Pragma("unroll") for (int n = 0; n < 2; ++n) _Pragma("unroll") for (int k = 0; k < 2; ++k) \
;         acc[ai][bj][m][n] = __builtin_amdgcn_mfma_f32_16x16x32_bf16(Bt[n][k], At[m][k], acc[ai][bj][m][n], 0, 0, 0); __builtin_amdgcn_s_setprio(0); } while (0)
; #define PG8_WAIT_V(n) asm volatile("s_waitcnt vmcnt(" #n ")" ::: "memory")
; #define PG8_BAR __builtin_amdgcn_s_barrier()
; __device__ __forceinline__ u32x4 pack8(f32x4 v0, f32x4 v1) { u32x4 w; w.x = cvt_pk_bf16(v0[0], v0[1]); w.y = cvt_pk_bf16(v0[2], v0[3]); w.z = cvt_pk_bf16(v1[0], v1[1]); w.w = cvt_pk_bf16(v1[2], v1[3]); return w; }
; template <class Epi>
; __device__ __forceinline__ void gemm_phase(LAS unsigned char* lds, const Gemm g, const StaticOrder& S, const Epi& E) {
;     ...
;             PG8_WAIT_V(6); PG8_BAR; PG8_MMA(1, 1, At, B1); PG8_BAR;
;         }
;     __device__ __forceinline__ void operator()(const f32x4 (&acc)[2][2][4][2], const Unit& u, int wr, int wc, int fr, int fq) const {
;     ...
;             for (int m = 0; m < 4; ++m) { const size_t ro = (size_t)(row0 + ai * HALF + m * 16) * DM + col0; const float nr = -LOG2E * rs[row0 + ai * HALF + m * 16];
; #pragma unroll
;                 for (int bj = 0; bj < 2; ++bj) {
;                     const u32x4 pw = *(const u32x4*)(PP + ro + bj * HALF);
;                     const float pv[8] = {bf_lo(pw.x), bf_hi(pw.x), bf_lo(pw.y), bf_hi(pw.y), bf_lo(pw.z), bf_hi(pw.z), bf_lo(pw.w), bf_hi(pw.w)};
;                     f32x4 t0, t1;
; #pragma unroll
;                     for (int j = 0; j < 4; ++j) {
;                         t0[j] = fast_rcp(1.0f + fast_exp2(acc[ai][bj][m][0][j] * nr)) * pv[j];
;                         t1[j] = fast_rcp(1.0f + fast_exp2(acc[ai][bj][m][1][j] * nr)) * pv[4 + j]; }
;                     *(u32x4*)(O + ro + bj * HALF) = pack8(t0, t1); } }
	s_add_u32 s48, s48, 0x80080
	s_addc_u32 s49, s49, 0
	s_add_i32 s50, s50, s23
	s_mov_b32 m0, s50
	s_nop 0
	global_load_lds_dwordx4 v132, s[48:49]
	s_add_i32 m0, s50, 0x2000
	s_nop 0
	global_load_lds_dwordx4 v128, s[48:49]
	s_waitcnt vmcnt(6)
	s_barrier
	v_mfma_f32_16x16x32_bf16 v[52:55], v[196:199], v[164:167], v[52:55]
	v_mfma_f32_16x16x32_bf16 v[48:51], v[204:207], v[164:167], v[48:51]
	v_mfma_f32_16x16x32_bf16 v[36:39], v[196:199], v[172:175], v[36:39]
	v_mfma_f32_16x16x32_bf16 v[32:35], v[204:207], v[172:175], v[32:35]
	v_mfma_f32_16x16x32_bf16 v[20:23], v[196:199], v[180:183], v[20:23]
	v_mfma_f32_16x16x32_bf16 v[16:19], v[204:207], v[180:183], v[16:19]
	v_mfma_f32_16x16x32_bf16 v[4:7], v[196:199], v[188:191], v[4:7]
	v_mfma_f32_16x16x32_bf16 v[0:3], v[204:207], v[188:191], v[0:3]
	v_mfma_f32_16x16x32_bf16 v[52:55], v[200:203], v[168:171], v[52:55]
	v_mfma_f32_16x16x32_bf16 v[48:51], v[208:211], v[168:171], v[48:51]
	v_mfma_f32_16x16x32_bf16 v[36:39], v[200:203], v[176:179], v[36:39]
	v_mfma_f32_16x16x32_bf16 v[32:35], v[208:211], v[176:179], v[32:35]
	v_mfma_f32_16x16x32_bf16 v[20:23], v[200:203], v[184:187], v[20:23]
	v_mfma_f32_16x16x32_bf16 v[16:19], v[208:211], v[184:187], v[16:19]
	v_mfma_f32_16x16x32_bf16 v[4:7], v[200:203], v[192:195], v[4:7]
	v_mfma_f32_16x16x32_bf16 v[0:3], v[208:211], v[192:195], v[0:3]
	s_add_i32 s63, s63, 2
	s_add_u32 s46, s46, 0x100
	s_addc_u32 s47, s47, 0
	s_add_u32 s61, s61, 0x100
	s_addc_u32 s62, s62, 0
	s_cmp_gt_u32 s63, 29
	s_barrier
	s_cbranch_scc0 .LBB0_999
	v_lshl_add_u32 v144, s44, 8, v148
	v_ashrrev_i32_e32 v145, 31, v144
	v_lshl_add_u64 v[140:141], v[144:145], 2, s[14:15]
	global_load_dword v164, v[140:141], off
	v_lshl_or_b32 v146, s58, 8, v150
	v_ashrrev_i32_e32 v147, 31, v146
	v_lshlrev_b64 v[142:143], 11, v[144:145]
	v_lshl_add_u64 v[142:143], v[142:143], 0, v[146:147]
	v_lshlrev_b64 v[142:143], 1, v[142:143]
	v_lshl_add_u64 v[160:161], s[20:21], 0, v[142:143]
	global_load_dwordx4 v[154:157], v[160:161], off
	global_load_dwordx4 v[220:223], v[160:161], off offset:256
	v_lshl_add_u64 v[162:163], s[24:25], 0, v[142:143]
	s_and_b64 vcc, exec, s[38:39]
	s_mov_b32 s58, s34
	s_mov_b32 s44, s36
	s_mov_b64 s[48:49], s[42:43]
	s_mov_b64 s[46:47], s[40:41]
	s_waitcnt vmcnt(0)
	v_mul_f32_e32 v145, 0xbfb8aa3b, v164
	v_mul_f32_e32 v124, v124, v145
	v_mul_f32_e32 v120, v120, v145
	v_mul_f32_e32 v125, v125, v145
	v_mul_f32_e32 v121, v121, v145
	v_mul_f32_e32 v126, v126, v145
	v_mul_f32_e32 v122, v122, v145
	v_mul_f32_e32 v127, v127, v145
	v_mul_f32_e32 v123, v123, v145
	v_exp_f32_e32 v124, v124
	v_exp_f32_e32 v120, v120
	v_exp_f32_e32 v125, v125
	v_exp_f32_e32 v121, v121
	v_exp_f32_e32 v126, v126
	v_exp_f32_e32 v122, v122
	v_exp_f32_e32 v127, v127
	v_exp_f32_e32 v123, v123
	v_add_f32_e32 v124, 1.0, v124
	v_add_f32_e32 v120, 1.0, v120
	v_add_f32_e32 v125, 1.0, v125
	v_add_f32_e32 v121, 1.0, v121
	v_add_f32_e32 v126, 1.0, v126
	v_add_f32_e32 v122, 1.0, v122
	v_add_f32_e32 v127, 1.0, v127
	v_add_f32_e32 v123, 1.0, v123
	v_rcp_f32_e32 v124, v124
	v_rcp_f32_e32 v120, v120
	v_rcp_f32_e32 v125, v125
	v_rcp_f32_e32 v121, v121
	v_rcp_f32_e32 v126, v126
	v_rcp_f32_e32 v122, v122
	v_rcp_f32_e32 v127, v127
	v_rcp_f32_e32 v123, v123
	v_lshlrev_b32_e32 v164, 16, v154
	v_and_b32_e32 v154, 0xffff0000, v154
	v_lshlrev_b32_e32 v165, 16, v155
	v_and_b32_e32 v155, 0xffff0000, v155
	v_lshlrev_b32_e32 v166, 16, v156
	v_and_b32_e32 v156, 0xffff0000, v156
	v_lshlrev_b32_e32 v167, 16, v157
	v_and_b32_e32 v157, 0xffff0000, v157
	v_mul_f32_e32 v124, v124, v164
	v_mul_f32_e32 v164, v120, v166
	v_mul_f32_e32 v120, v125, v154
	v_mul_f32_e32 v125, v121, v156
	v_mul_f32_e32 v121, v126, v165
	v_mul_f32_e32 v126, v122, v167
	v_mul_f32_e32 v122, v127, v155
	v_mul_f32_e32 v123, v123, v157
	v_cvt_pk_bf16_f32 v120, v124, v120
	v_cvt_pk_bf16_f32 v121, v121, v122
	v_cvt_pk_bf16_f32 v122, v164, v125
	v_cvt_pk_bf16_f32 v123, v126, v123
	global_store_dwordx4 v[162:163], v[120:123], off
	v_mul_f32_e32 v116, v116, v145
	v_mul_f32_e32 v112, v112, v145
	v_mul_f32_e32 v117, v117, v145
	v_mul_f32_e32 v113, v113, v145
	v_mul_f32_e32 v118, v118, v145
	v_mul_f32_e32 v114, v114, v145
	v_mul_f32_e32 v119, v119, v145
	v_mul_f32_e32 v115, v115, v145
	v_exp_f32_e32 v116, v116
	v_exp_f32_e32 v112, v112
	v_exp_f32_e32 v117, v117
	v_exp_f32_e32 v113, v113
	v_exp_f32_e32 v118, v118
	v_exp_f32_e32 v114, v114
	v_exp_f32_e32 v119, v119
	v_exp_f32_e32 v115, v115
	v_add_f32_e32 v116, 1.0, v116
	v_add_f32_e32 v112, 1.0, v112
	v_add_f32_e32 v117, 1.0, v117
	v_add_f32_e32 v113, 1.0, v113
	v_add_f32_e32 v118, 1.0, v118
	v_add_f32_e32 v114, 1.0, v114
	v_add_f32_e32 v119, 1.0, v119
	v_add_f32_e32 v115, 1.0, v115
	v_rcp_f32_e32 v116, v116
	v_rcp_f32_e32 v112, v112
	v_rcp_f32_e32 v117, v117
	v_rcp_f32_e32 v113, v113
	v_rcp_f32_e32 v118, v118
	v_rcp_f32_e32 v114, v114
	v_rcp_f32_e32 v119, v119
	v_rcp_f32_e32 v115, v115
	v_or_b32_e32 v124, 16, v144
	v_ashrrev_i32_e32 v125, 31, v124
	v_lshlrev_b64 v[124:125], 11, v[124:125]
	v_lshl_add_u64 v[124:125], v[124:125], 0, v[146:147]
	v_lshlrev_b64 v[124:125], 1, v[124:125]
	v_lshl_add_u64 v[126:127], s[20:21], 0, v[124:125]
	v_lshlrev_b32_e32 v145, 16, v220
	v_and_b32_e32 v120, 0xffff0000, v220
	v_lshlrev_b32_e32 v154, 16, v221
	v_and_b32_e32 v121, 0xffff0000, v221
	v_lshlrev_b32_e32 v155, 16, v222
	v_and_b32_e32 v122, 0xffff0000, v222
	v_lshlrev_b32_e32 v156, 16, v223
	v_and_b32_e32 v123, 0xffff0000, v223
	v_mul_f32_e32 v116, v116, v145
	v_mul_f32_e32 v145, v112, v155
	v_mul_f32_e32 v112, v117, v120
	v_mul_f32_e32 v117, v113, v122
	v_mul_f32_e32 v113, v118, v154
	v_mul_f32_e32 v118, v114, v156
	v_mul_f32_e32 v114, v119, v121
	v_mul_f32_e32 v115, v115, v123
	v_cvt_pk_bf16_f32 v112, v116, v112
	v_cvt_pk_bf16_f32 v113, v113, v114
	v_cvt_pk_bf16_f32 v114, v145, v117
	v_cvt_pk_bf16_f32 v115, v118, v115
	global_store_dwordx4 v[162:163], v[112:115], off offset:256
	global_load_dword v118, v[140:141], off offset:64
	s_nop 0
	global_load_dwordx4 v[112:115], v[126:127], off
	global_load_dwordx4 v[224:227], v[126:127], off offset:256
	v_lshl_add_u64 v[116:117], s[24:25], 0, v[124:125]
	s_waitcnt vmcnt(0)
; __device__ __forceinline__ float bf_lo(unsigned w) { return __uint_as_float(w << 16); }
; __device__ __forceinline__ float bf_hi(unsigned w) { return __uint_as_float(w & 0xffff0000u); }
; __device__ __forceinline__ float fast_rcp(float x) { return __builtin_amdgcn_rcpf(x); }
; __device__ __forceinline__ float fast_exp2(float x) { return __builtin_amdgcn_exp2f(x); }
; __device__ __forceinline__ u32x4 pack8(f32x4 v0, f32x4 v1) { u32x4 w; w.x = cvt_pk_bf16(v0[0], v0[1]); w.y = cvt_pk_bf16(v0[2], v0[3]); w.z = cvt_pk_bf16(v1[0], v1[1]); w.w = cvt_pk_bf16(v1[2], v1[3]); return w; }
;     __device__ __forceinline__ void operator()(const f32x4 (&acc)[2][2][4][2], const Unit& u, int wr, int wc, int fr, int fq) const {
;     ...
;             for (int m = 0; m < 4; ++m) { const size_t ro = (size_t)(row0 + ai * HALF + m * 16) * DM + col0; const float nr = -LOG2E * rs[row0 + ai * HALF + m * 16];
; #pragma unroll
;                 for (int bj = 0; bj < 2; ++bj) {
;                     const u32x4 pw = *(const u32x4*)(PP + ro + bj * HALF);
;                     const float pv[8] = {bf_lo(pw.x), bf_hi(pw.x), bf_lo(pw.y), bf_hi(pw.y), bf_lo(pw.z), bf_hi(pw.z), bf_lo(pw.w), bf_hi(pw.w)};
;                     f32x4 t0, t1;
; #pragma unroll
;                     for (int j = 0; j < 4; ++j) {
;                         t0[j] = fast_rcp(1.0f + fast_exp2(acc[ai][bj][m][0][j] * nr)) * pv[j];
;                         t1[j] = fast_rcp(1.0f + fast_exp2(acc[ai][bj][m][1][j] * nr)) * pv[4 + j]; }
;                     *(u32x4*)(O + ro + bj * HALF) = pack8(t0, t1); } }
	v_mul_f32_e32 v118, 0xbfb8aa3b, v118
	v_mul_f32_e32 v108, v108, v118
	v_mul_f32_e32 v104, v104, v118
	v_mul_f32_e32 v109, v109, v118
	v_mul_f32_e32 v105, v105, v118
	v_mul_f32_e32 v110, v110, v118
	v_mul_f32_e32 v106, v106, v118
	v_mul_f32_e32 v111, v111, v118
	v_mul_f32_e32 v107, v107, v118
	v_exp_f32_e32 v108, v108
	v_exp_f32_e32 v104, v104
	v_exp_f32_e32 v109, v109
	v_exp_f32_e32 v105, v105
	v_exp_f32_e32 v110, v110
	v_exp_f32_e32 v106, v106
	v_exp_f32_e32 v111, v111
	v_exp_f32_e32 v107, v107
	v_add_f32_e32 v108, 1.0, v108
	v_add_f32_e32 v104, 1.0, v104
	v_add_f32_e32 v109, 1.0, v109
	v_add_f32_e32 v105, 1.0, v105
	v_add_f32_e32 v110, 1.0, v110
	v_add_f32_e32 v106, 1.0, v106
	v_add_f32_e32 v111, 1.0, v111
	v_add_f32_e32 v107, 1.0, v107
	v_rcp_f32_e32 v108, v108
	v_rcp_f32_e32 v104, v104
	v_rcp_f32_e32 v109, v109
	v_rcp_f32_e32 v105, v105
	v_rcp_f32_e32 v110, v110
	v_rcp_f32_e32 v106, v106
	v_rcp_f32_e32 v111, v111
	v_rcp_f32_e32 v107, v107
	v_lshlrev_b32_e32 v119, 16, v112
	v_and_b32_e32 v112, 0xffff0000, v112
	v_lshlrev_b32_e32 v120, 16, v113
	v_and_b32_e32 v113, 0xffff0000, v113
	v_lshlrev_b32_e32 v121, 16, v114
	v_and_b32_e32 v114, 0xffff0000, v114
	v_lshlrev_b32_e32 v122, 16, v115
	v_and_b32_e32 v115, 0xffff0000, v115
	v_mul_f32_e32 v108, v108, v119
	v_mul_f32_e32 v119, v104, v121
	v_mul_f32_e32 v104, v109, v112
	v_mul_f32_e32 v109, v105, v114
	v_mul_f32_e32 v105, v110, v120
	v_mul_f32_e32 v110, v106, v122
	v_mul_f32_e32 v106, v111, v113
	v_mul_f32_e32 v107, v107, v115
	v_cvt_pk_bf16_f32 v104, v108, v104
	v_cvt_pk_bf16_f32 v105, v105, v106
	v_cvt_pk_bf16_f32 v106, v119, v109
	v_cvt_pk_bf16_f32 v107, v110, v107
	global_store_dwordx4 v[116:117], v[104:107], off
	v_mul_f32_e32 v100, v100, v118
	v_mul_f32_e32 v96, v96, v118
	v_mul_f32_e32 v101, v101, v118
	v_mul_f32_e32 v97, v97, v118
	v_mul_f32_e32 v102, v102, v118
	v_mul_f32_e32 v98, v98, v118
	v_mul_f32_e32 v103, v103, v118
	v_mul_f32_e32 v99, v99, v118
	v_exp_f32_e32 v100, v100
	v_exp_f32_e32 v96, v96
	v_exp_f32_e32 v101, v101
	v_exp_f32_e32 v97, v97
	v_exp_f32_e32 v102, v102
	v_exp_f32_e32 v98, v98
	v_exp_f32_e32 v103, v103
	v_exp_f32_e32 v99, v99
	v_add_f32_e32 v100, 1.0, v100
	v_add_f32_e32 v96, 1.0, v96
	v_add_f32_e32 v101, 1.0, v101
	v_add_f32_e32 v97, 1.0, v97
	v_add_f32_e32 v102, 1.0, v102
	v_add_f32_e32 v98, 1.0, v98
	v_add_f32_e32 v103, 1.0, v103
	v_add_f32_e32 v99, 1.0, v99
	v_rcp_f32_e32 v100, v100
	v_rcp_f32_e32 v96, v96
	v_rcp_f32_e32 v101, v101
	v_rcp_f32_e32 v97, v97
	v_rcp_f32_e32 v102, v102
	v_rcp_f32_e32 v98, v98
	v_rcp_f32_e32 v103, v103
	v_rcp_f32_e32 v99, v99
	v_or_b32_e32 v108, 32, v144
	v_ashrrev_i32_e32 v109, 31, v108
	v_lshlrev_b64 v[108:109], 11, v[108:109]
	v_lshl_add_u64 v[108:109], v[108:109], 0, v[146:147]
	v_lshlrev_b64 v[108:109], 1, v[108:109]
	v_lshl_add_u64 v[110:111], s[20:21], 0, v[108:109]
	v_lshlrev_b32_e32 v112, 16, v224
	v_and_b32_e32 v104, 0xffff0000, v224
	v_lshlrev_b32_e32 v113, 16, v225
	v_and_b32_e32 v105, 0xffff0000, v225
	v_lshlrev_b32_e32 v114, 16, v226
	v_and_b32_e32 v106, 0xffff0000, v226
	v_lshlrev_b32_e32 v115, 16, v227
	v_and_b32_e32 v107, 0xffff0000, v227
	v_mul_f32_e32 v100, v100, v112
	v_mul_f32_e32 v112, v96, v114
	v_mul_f32_e32 v96, v101, v104
	v_mul_f32_e32 v101, v97, v106
	v_mul_f32_e32 v97, v102, v113
	v_mul_f32_e32 v102, v98, v115
	v_mul_f32_e32 v98, v103, v105
	v_mul_f32_e32 v99, v99, v107
	v_cvt_pk_bf16_f32 v96, v100, v96
	v_cvt_pk_bf16_f32 v97, v97, v98
	v_cvt_pk_bf16_f32 v98, v112, v101
	v_cvt_pk_bf16_f32 v99, v102, v99
	global_store_dwordx4 v[116:117], v[96:99], off offset:256
	global_load_dword v102, v[140:141], off offset:128
	s_nop 0
	global_load_dwordx4 v[96:99], v[110:111], off
	global_load_dwordx4 v[220:223], v[110:111], off offset:256
	v_lshl_add_u64 v[100:101], s[24:25], 0, v[108:109]
	s_waitcnt vmcnt(0)
	v_mul_f32_e32 v102, 0xbfb8aa3b, v102
	v_mul_f32_e32 v92, v92, v102
	v_mul_f32_e32 v88, v88, v102
	v_mul_f32_e32 v93, v93, v102
	v_mul_f32_e32 v89, v89, v102
	v_mul_f32_e32 v94, v94, v102
	v_mul_f32_e32 v90, v90, v102
	v_mul_f32_e32 v95, v95, v102
	v_mul_f32_e32 v91, v91, v102
	v_exp_f32_e32 v92, v92
	v_exp_f32_e32 v88, v88
	v_exp_f32_e32 v93, v93
	v_exp_f32_e32 v89, v89
	v_exp_f32_e32 v94, v94
	v_exp_f32_e32 v90, v90
	v_exp_f32_e32 v95, v95
	v_exp_f32_e32 v91, v91
	v_add_f32_e32 v92, 1.0, v92
	v_add_f32_e32 v88, 1.0, v88
	v_add_f32_e32 v93, 1.0, v93
	v_add_f32_e32 v89, 1.0, v89
	v_add_f32_e32 v94, 1.0, v94
	v_add_f32_e32 v90, 1.0, v90
	v_add_f32_e32 v95, 1.0, v95
	v_add_f32_e32 v91, 1.0, v91
	v_rcp_f32_e32 v92, v92
	v_rcp_f32_e32 v88, v88
	v_rcp_f32_e32 v93, v93
	v_rcp_f32_e32 v89, v89
	v_rcp_f32_e32 v94, v94
	v_rcp_f32_e32 v90, v90
	v_rcp_f32_e32 v95, v95
	v_rcp_f32_e32 v91, v91
	v_lshlrev_b32_e32 v103, 16, v96
	v_and_b32_e32 v96, 0xffff0000, v96
	v_lshlrev_b32_e32 v104, 16, v97
	v_and_b32_e32 v97, 0xffff0000, v97
	v_lshlrev_b32_e32 v105, 16, v98
	v_and_b32_e32 v98, 0xffff0000, v98
	v_lshlrev_b32_e32 v106, 16, v99
	v_and_b32_e32 v99, 0xffff0000, v99
	v_mul_f32_e32 v92, v92, v103
	v_mul_f32_e32 v103, v88, v105
	v_mul_f32_e32 v88, v93, v96
	v_mul_f32_e32 v93, v89, v98
	v_mul_f32_e32 v89, v94, v104
	v_mul_f32_e32 v94, v90, v106
	v_mul_f32_e32 v90, v95, v97
	v_mul_f32_e32 v91, v91, v99
	v_cvt_pk_bf16_f32 v88, v92, v88
	v_cvt_pk_bf16_f32 v89, v89, v90
	v_cvt_pk_bf16_f32 v90, v103, v93
	v_cvt_pk_bf16_f32 v91, v94, v91
	global_store_dwordx4 v[100:101], v[88:91], off
	v_mul_f32_e32 v84, v84, v102
	v_mul_f32_e32 v80, v80, v102
	v_mul_f32_e32 v85, v85, v102
	v_mul_f32_e32 v81, v81, v102
	v_mul_f32_e32 v86, v86, v102
	v_mul_f32_e32 v82, v82, v102
	v_mul_f32_e32 v87, v87, v102
	v_mul_f32_e32 v83, v83, v102
; __device__ __forceinline__ float bf_lo(unsigned w) { return __uint_as_float(w << 16); }
; __device__ __forceinline__ float bf_hi(unsigned w) { return __uint_as_float(w & 0xffff0000u); }
; __device__ __forceinline__ float fast_rcp(float x) { return __builtin_amdgcn_rcpf(x); }
; __device__ __forceinline__ float fast_exp2(float x) { return __builtin_amdgcn_exp2f(x); }
; __device__ __forceinline__ u32x4 pack8(f32x4 v0, f32x4 v1) { u32x4 w; w.x = cvt_pk_bf16(v0[0], v0[1]); w.y = cvt_pk_bf16(v0[2], v0[3]); w.z = cvt_pk_bf16(v1[0], v1[1]); w.w = cvt_pk_bf16(v1[2], v1[3]); return w; }
;     __device__ __forceinline__ void operator()(const f32x4 (&acc)[2][2][4][2], const Unit& u, int wr, int wc, int fr, int fq) const {
;     ...
;             for (int m = 0; m < 4; ++m) { const size_t ro = (size_t)(row0 + ai * HALF + m * 16) * DM + col0; const float nr = -LOG2E * rs[row0 + ai * HALF + m * 16];
; #pragma unroll
;                 for (int bj = 0; bj < 2; ++bj) {
;                     const u32x4 pw = *(const u32x4*)(PP + ro + bj * HALF);
;                     const float pv[8] = {bf_lo(pw.x), bf_hi(pw.x), bf_lo(pw.y), bf_hi(pw.y), bf_lo(pw.z), bf_hi(pw.z), bf_lo(pw.w), bf_hi(pw.w)};
;                     f32x4 t0, t1;
; #pragma unroll
;                     for (int j = 0; j < 4; ++j) {
;                         t0[j] = fast_rcp(1.0f + fast_exp2(acc[ai][bj][m][0][j] * nr)) * pv[j];
;                         t1[j] = fast_rcp(1.0f + fast_exp2(acc[ai][bj][m][1][j] * nr)) * pv[4 + j]; }
;                     *(u32x4*)(O + ro + bj * HALF) = pack8(t0, t1); } }
	v_exp_f32_e32 v84, v84
	v_exp_f32_e32 v80, v80
	v_exp_f32_e32 v85, v85
	v_exp_f32_e32 v81, v81
	v_exp_f32_e32 v86, v86
	v_exp_f32_e32 v82, v82
	v_exp_f32_e32 v87, v87
	v_exp_f32_e32 v83, v83
	v_add_f32_e32 v84, 1.0, v84
	v_add_f32_e32 v80, 1.0, v80
	v_add_f32_e32 v85, 1.0, v85
	v_add_f32_e32 v81, 1.0, v81
	v_add_f32_e32 v86, 1.0, v86
	v_add_f32_e32 v82, 1.0, v82
	v_add_f32_e32 v87, 1.0, v87
	v_add_f32_e32 v83, 1.0, v83
	v_rcp_f32_e32 v84, v84
	v_rcp_f32_e32 v80, v80
	v_rcp_f32_e32 v85, v85
	v_rcp_f32_e32 v81, v81
	v_rcp_f32_e32 v86, v86
	v_rcp_f32_e32 v82, v82
	v_rcp_f32_e32 v87, v87
	v_rcp_f32_e32 v83, v83
	v_or_b32_e32 v92, 48, v144
	v_ashrrev_i32_e32 v93, 31, v92
	v_lshlrev_b64 v[92:93], 11, v[92:93]
	v_lshl_add_u64 v[92:93], v[92:93], 0, v[146:147]
	v_lshlrev_b64 v[92:93], 1, v[92:93]
	v_lshl_add_u64 v[94:95], s[20:21], 0, v[92:93]
	v_lshlrev_b32_e32 v96, 16, v220
	v_and_b32_e32 v88, 0xffff0000, v220
	v_lshlrev_b32_e32 v97, 16, v221
	v_and_b32_e32 v89, 0xffff0000, v221
	v_lshlrev_b32_e32 v98, 16, v222
	v_and_b32_e32 v90, 0xffff0000, v222
	v_lshlrev_b32_e32 v99, 16, v223
	v_and_b32_e32 v91, 0xffff0000, v223
	v_mul_f32_e32 v84, v84, v96
	v_mul_f32_e32 v96, v80, v98
	v_mul_f32_e32 v80, v85, v88
	v_mul_f32_e32 v85, v81, v90
	v_mul_f32_e32 v81, v86, v97
	v_mul_f32_e32 v86, v82, v99
	v_mul_f32_e32 v82, v87, v89
	v_mul_f32_e32 v83, v83, v91
	v_cvt_pk_bf16_f32 v80, v84, v80
	v_cvt_pk_bf16_f32 v81, v81, v82
	v_cvt_pk_bf16_f32 v82, v96, v85
	v_cvt_pk_bf16_f32 v83, v86, v83
	global_store_dwordx4 v[100:101], v[80:83], off offset:256
	global_load_dword v86, v[140:141], off offset:192
	s_nop 0
	global_load_dwordx4 v[80:83], v[94:95], off
	global_load_dwordx4 v[224:227], v[94:95], off offset:256
	v_lshl_add_u64 v[84:85], s[24:25], 0, v[92:93]
	s_waitcnt vmcnt(0)
	v_mul_f32_e32 v86, 0xbfb8aa3b, v86
	v_mul_f32_e32 v76, v76, v86
	v_mul_f32_e32 v72, v72, v86
	v_mul_f32_e32 v77, v77, v86
	v_mul_f32_e32 v73, v73, v86
	v_mul_f32_e32 v78, v78, v86
	v_mul_f32_e32 v74, v74, v86
	v_mul_f32_e32 v79, v79, v86
	v_mul_f32_e32 v75, v75, v86
	v_exp_f32_e32 v76, v76
	v_exp_f32_e32 v72, v72
	v_exp_f32_e32 v77, v77
	v_exp_f32_e32 v73, v73
	v_exp_f32_e32 v78, v78
	v_exp_f32_e32 v74, v74
	v_exp_f32_e32 v79, v79
	v_exp_f32_e32 v75, v75
	v_add_f32_e32 v76, 1.0, v76
	v_add_f32_e32 v72, 1.0, v72
	v_add_f32_e32 v77, 1.0, v77
	v_add_f32_e32 v73, 1.0, v73
	v_add_f32_e32 v78, 1.0, v78
	v_add_f32_e32 v74, 1.0, v74
	v_add_f32_e32 v79, 1.0, v79
	v_add_f32_e32 v75, 1.0, v75
	v_rcp_f32_e32 v76, v76
	v_rcp_f32_e32 v72, v72
	v_rcp_f32_e32 v77, v77
	v_rcp_f32_e32 v73, v73
	v_rcp_f32_e32 v78, v78
	v_rcp_f32_e32 v74, v74
	v_rcp_f32_e32 v79, v79
	v_rcp_f32_e32 v75, v75
	v_lshlrev_b32_e32 v87, 16, v80
	v_and_b32_e32 v80, 0xffff0000, v80
	v_lshlrev_b32_e32 v88, 16, v81
	v_and_b32_e32 v81, 0xffff0000, v81
	v_lshlrev_b32_e32 v89, 16, v82
	v_and_b32_e32 v82, 0xffff0000, v82
	v_lshlrev_b32_e32 v90, 16, v83
	v_and_b32_e32 v83, 0xffff0000, v83
	v_mul_f32_e32 v76, v76, v87
	v_mul_f32_e32 v87, v72, v89
	v_mul_f32_e32 v72, v77, v80
	v_mul_f32_e32 v77, v73, v82
	v_mul_f32_e32 v73, v78, v88
	v_mul_f32_e32 v78, v74, v90
	v_mul_f32_e32 v74, v79, v81
	v_mul_f32_e32 v75, v75, v83
	v_cvt_pk_bf16_f32 v72, v76, v72
	v_cvt_pk_bf16_f32 v73, v73, v74
	v_cvt_pk_bf16_f32 v74, v87, v77
	v_cvt_pk_bf16_f32 v75, v78, v75
	global_store_dwordx4 v[84:85], v[72:75], off
	v_mul_f32_e32 v68, v68, v86
	v_mul_f32_e32 v64, v64, v86
	v_mul_f32_e32 v69, v69, v86
	v_mul_f32_e32 v65, v65, v86
	v_mul_f32_e32 v70, v70, v86
	v_mul_f32_e32 v66, v66, v86
	v_mul_f32_e32 v71, v71, v86
	v_mul_f32_e32 v67, v67, v86
	v_exp_f32_e32 v68, v68
	v_exp_f32_e32 v64, v64
	v_exp_f32_e32 v69, v69
	v_exp_f32_e32 v65, v65
	v_exp_f32_e32 v70, v70
	v_exp_f32_e32 v66, v66
	v_exp_f32_e32 v71, v71
	v_exp_f32_e32 v67, v67
	v_add_f32_e32 v68, 1.0, v68
	v_add_f32_e32 v64, 1.0, v64
	v_add_f32_e32 v69, 1.0, v69
	v_add_f32_e32 v65, 1.0, v65
	v_add_f32_e32 v70, 1.0, v70
	v_add_f32_e32 v66, 1.0, v66
	v_add_f32_e32 v71, 1.0, v71
	v_add_f32_e32 v67, 1.0, v67
	v_rcp_f32_e32 v68, v68
	v_rcp_f32_e32 v64, v64
	v_rcp_f32_e32 v69, v69
	v_rcp_f32_e32 v65, v65
	v_rcp_f32_e32 v70, v70
	v_rcp_f32_e32 v66, v66
	v_rcp_f32_e32 v71, v71
	v_rcp_f32_e32 v67, v67
	v_lshl_add_u64 v[76:77], v[142:143], 0, s[2:3]
	v_lshl_add_u64 v[78:79], s[20:21], 0, v[76:77]
	v_lshlrev_b32_e32 v80, 16, v224
	v_and_b32_e32 v72, 0xffff0000, v224
	v_lshlrev_b32_e32 v81, 16, v225
	v_and_b32_e32 v73, 0xffff0000, v225
	v_lshlrev_b32_e32 v82, 16, v226
	v_and_b32_e32 v74, 0xffff0000, v226
	v_lshlrev_b32_e32 v83, 16, v227
	v_and_b32_e32 v75, 0xffff0000, v227
	v_mul_f32_e32 v68, v68, v80
	v_mul_f32_e32 v80, v64, v82
	v_mul_f32_e32 v64, v69, v72
	v_mul_f32_e32 v69, v65, v74
	v_mul_f32_e32 v65, v70, v81
	v_mul_f32_e32 v70, v66, v83
	v_mul_f32_e32 v66, v71, v73
	v_mul_f32_e32 v67, v67, v75
	v_cvt_pk_bf16_f32 v64, v68, v64
	v_cvt_pk_bf16_f32 v65, v65, v66
	v_cvt_pk_bf16_f32 v66, v80, v69
	v_cvt_pk_bf16_f32 v67, v70, v67
	global_store_dwordx4 v[84:85], v[64:67], off offset:256
	global_load_dword v70, v[140:141], off offset:512
	s_nop 0
	global_load_dwordx4 v[64:67], v[78:79], off
	global_load_dwordx4 v[220:223], v[78:79], off offset:256
	v_lshl_add_u64 v[68:69], s[24:25], 0, v[76:77]
	s_waitcnt vmcnt(0)
; __device__ __forceinline__ float bf_lo(unsigned w) { return __uint_as_float(w << 16); }
; __device__ __forceinline__ float bf_hi(unsigned w) { return __uint_as_float(w & 0xffff0000u); }
; __device__ __forceinline__ float fast_rcp(float x) { return __builtin_amdgcn_rcpf(x); }
; __device__ __forceinline__ float fast_exp2(float x) { return __builtin_amdgcn_exp2f(x); }
; __device__ __forceinline__ u32x4 pack8(f32x4 v0, f32x4 v1) { u32x4 w; w.x = cvt_pk_bf16(v0[0], v0[1]); w.y = cvt_pk_bf16(v0[2], v0[3]); w.z = cvt_pk_bf16(v1[0], v1[1]); w.w = cvt_pk_bf16(v1[2], v1[3]); return w; }
;     __device__ __forceinline__ void operator()(const f32x4 (&acc)[2][2][4][2], const Unit& u, int wr, int wc, int fr, int fq) const {
;     ...
;             for (int m = 0; m < 4; ++m) { const size_t ro = (size_t)(row0 + ai * HALF + m * 16) * DM + col0; const float nr = -LOG2E * rs[row0 + ai * HALF + m * 16];
; #pragma unroll
;                 for (int bj = 0; bj < 2; ++bj) {
;                     const u32x4 pw = *(const u32x4*)(PP + ro + bj * HALF);
;                     const float pv[8] = {bf_lo(pw.x), bf_hi(pw.x), bf_lo(pw.y), bf_hi(pw.y), bf_lo(pw.z), bf_hi(pw.z), bf_lo(pw.w), bf_hi(pw.w)};
;                     f32x4 t0, t1;
; #pragma unroll
;                     for (int j = 0; j < 4; ++j) {
;                         t0[j] = fast_rcp(1.0f + fast_exp2(acc[ai][bj][m][0][j] * nr)) * pv[j];
;                         t1[j] = fast_rcp(1.0f + fast_exp2(acc[ai][bj][m][1][j] * nr)) * pv[4 + j]; }
;                     *(u32x4*)(O + ro + bj * HALF) = pack8(t0, t1); } }
	v_mul_f32_e32 v70, 0xbfb8aa3b, v70
	v_mul_f32_e32 v60, v60, v70
	v_mul_f32_e32 v56, v56, v70
	v_mul_f32_e32 v61, v61, v70
	v_mul_f32_e32 v57, v57, v70
	v_mul_f32_e32 v62, v62, v70
	v_mul_f32_e32 v58, v58, v70
	v_mul_f32_e32 v63, v63, v70
	v_mul_f32_e32 v59, v59, v70
	v_exp_f32_e32 v60, v60
	v_exp_f32_e32 v56, v56
	v_exp_f32_e32 v61, v61
	v_exp_f32_e32 v57, v57
	v_exp_f32_e32 v62, v62
	v_exp_f32_e32 v58, v58
	v_exp_f32_e32 v63, v63
	v_exp_f32_e32 v59, v59
	v_add_f32_e32 v60, 1.0, v60
	v_add_f32_e32 v56, 1.0, v56
	v_add_f32_e32 v61, 1.0, v61
	v_add_f32_e32 v57, 1.0, v57
	v_add_f32_e32 v62, 1.0, v62
	v_add_f32_e32 v58, 1.0, v58
	v_add_f32_e32 v63, 1.0, v63
	v_add_f32_e32 v59, 1.0, v59
	v_rcp_f32_e32 v60, v60
	v_rcp_f32_e32 v56, v56
	v_rcp_f32_e32 v61, v61
	v_rcp_f32_e32 v57, v57
	v_rcp_f32_e32 v62, v62
	v_rcp_f32_e32 v58, v58
	v_rcp_f32_e32 v63, v63
	v_rcp_f32_e32 v59, v59
	v_lshlrev_b32_e32 v71, 16, v64
	v_and_b32_e32 v64, 0xffff0000, v64
	v_lshlrev_b32_e32 v72, 16, v65
	v_and_b32_e32 v65, 0xffff0000, v65
	v_lshlrev_b32_e32 v73, 16, v66
	v_and_b32_e32 v66, 0xffff0000, v66
	v_lshlrev_b32_e32 v74, 16, v67
	v_and_b32_e32 v67, 0xffff0000, v67
	v_mul_f32_e32 v60, v60, v71
	v_mul_f32_e32 v71, v56, v73
	v_mul_f32_e32 v56, v61, v64
	v_mul_f32_e32 v61, v57, v66
	v_mul_f32_e32 v57, v62, v72
	v_mul_f32_e32 v62, v58, v74
	v_mul_f32_e32 v58, v63, v65
	v_mul_f32_e32 v59, v59, v67
	v_cvt_pk_bf16_f32 v56, v60, v56
	v_cvt_pk_bf16_f32 v57, v57, v58
	v_cvt_pk_bf16_f32 v58, v71, v61
	v_cvt_pk_bf16_f32 v59, v62, v59
	global_store_dwordx4 v[68:69], v[56:59], off
	v_mul_f32_e32 v52, v52, v70
	v_mul_f32_e32 v48, v48, v70
	v_mul_f32_e32 v53, v53, v70
	v_mul_f32_e32 v49, v49, v70
	v_mul_f32_e32 v54, v54, v70
	v_mul_f32_e32 v50, v50, v70
	v_mul_f32_e32 v55, v55, v70
	v_mul_f32_e32 v51, v51, v70
	v_exp_f32_e32 v52, v52
	v_exp_f32_e32 v48, v48
	v_exp_f32_e32 v53, v53
	v_exp_f32_e32 v49, v49
	v_exp_f32_e32 v54, v54
	v_exp_f32_e32 v50, v50
	v_exp_f32_e32 v55, v55
	v_exp_f32_e32 v51, v51
	v_add_f32_e32 v52, 1.0, v52
	v_add_f32_e32 v48, 1.0, v48
	v_add_f32_e32 v53, 1.0, v53
	v_add_f32_e32 v49, 1.0, v49
	v_add_f32_e32 v54, 1.0, v54
	v_add_f32_e32 v50, 1.0, v50
	v_add_f32_e32 v55, 1.0, v55
	v_add_f32_e32 v51, 1.0, v51
	v_rcp_f32_e32 v52, v52
	v_rcp_f32_e32 v48, v48
	v_rcp_f32_e32 v53, v53
	v_rcp_f32_e32 v49, v49
	v_rcp_f32_e32 v54, v54
	v_rcp_f32_e32 v50, v50
	v_rcp_f32_e32 v55, v55
	v_rcp_f32_e32 v51, v51
	v_lshl_add_u64 v[60:61], v[142:143], 0, s[6:7]
	v_lshl_add_u64 v[62:63], s[20:21], 0, v[60:61]
	v_lshlrev_b32_e32 v64, 16, v220
	v_and_b32_e32 v56, 0xffff0000, v220
	v_lshlrev_b32_e32 v65, 16, v221
	v_and_b32_e32 v57, 0xffff0000, v221
	v_lshlrev_b32_e32 v66, 16, v222
	v_and_b32_e32 v58, 0xffff0000, v222
	v_lshlrev_b32_e32 v67, 16, v223
	v_and_b32_e32 v59, 0xffff0000, v223
	v_mul_f32_e32 v52, v52, v64
	v_mul_f32_e32 v64, v48, v66
	v_mul_f32_e32 v48, v53, v56
	v_mul_f32_e32 v53, v49, v58
	v_mul_f32_e32 v49, v54, v65
	v_mul_f32_e32 v54, v50, v67
	v_mul_f32_e32 v50, v55, v57
	v_mul_f32_e32 v51, v51, v59
	v_cvt_pk_bf16_f32 v48, v52, v48
	v_cvt_pk_bf16_f32 v49, v49, v50
	v_cvt_pk_bf16_f32 v50, v64, v53
	v_cvt_pk_bf16_f32 v51, v54, v51
	global_store_dwordx4 v[68:69], v[48:51], off offset:256
	global_load_dword v54, v[140:141], off offset:576
	s_nop 0
	global_load_dwordx4 v[48:51], v[62:63], off
	global_load_dwordx4 v[224:227], v[62:63], off offset:256
	v_lshl_add_u64 v[52:53], s[24:25], 0, v[60:61]
	s_waitcnt vmcnt(0)
	v_mul_f32_e32 v54, 0xbfb8aa3b, v54
	v_mul_f32_e32 v44, v44, v54
	v_mul_f32_e32 v40, v40, v54
	v_mul_f32_e32 v45, v45, v54
	v_mul_f32_e32 v41, v41, v54
	v_mul_f32_e32 v46, v46, v54
	v_mul_f32_e32 v42, v42, v54
	v_mul_f32_e32 v47, v47, v54
	v_mul_f32_e32 v43, v43, v54
	v_exp_f32_e32 v44, v44
	v_exp_f32_e32 v40, v40
	v_exp_f32_e32 v45, v45
	v_exp_f32_e32 v41, v41
	v_exp_f32_e32 v46, v46
	v_exp_f32_e32 v42, v42
	v_exp_f32_e32 v47, v47
	v_exp_f32_e32 v43, v43
	v_add_f32_e32 v44, 1.0, v44
	v_add_f32_e32 v40, 1.0, v40
	v_add_f32_e32 v45, 1.0, v45
	v_add_f32_e32 v41, 1.0, v41
	v_add_f32_e32 v46, 1.0, v46
	v_add_f32_e32 v42, 1.0, v42
	v_add_f32_e32 v47, 1.0, v47
	v_add_f32_e32 v43, 1.0, v43
	v_rcp_f32_e32 v44, v44
	v_rcp_f32_e32 v40, v40
	v_rcp_f32_e32 v45, v45
	v_rcp_f32_e32 v41, v41
	v_rcp_f32_e32 v46, v46
	v_rcp_f32_e32 v42, v42
	v_rcp_f32_e32 v47, v47
	v_rcp_f32_e32 v43, v43
	v_lshlrev_b32_e32 v55, 16, v48
	v_and_b32_e32 v48, 0xffff0000, v48
	v_lshlrev_b32_e32 v56, 16, v49
	v_and_b32_e32 v49, 0xffff0000, v49
	v_lshlrev_b32_e32 v57, 16, v50
	v_and_b32_e32 v50, 0xffff0000, v50
	v_lshlrev_b32_e32 v58, 16, v51
	v_and_b32_e32 v51, 0xffff0000, v51
	v_mul_f32_e32 v44, v44, v55
	v_mul_f32_e32 v55, v40, v57
	v_mul_f32_e32 v40, v45, v48
	v_mul_f32_e32 v45, v41, v50
	v_mul_f32_e32 v41, v46, v56
	v_mul_f32_e32 v46, v42, v58
	v_mul_f32_e32 v42, v47, v49
	v_mul_f32_e32 v43, v43, v51
	v_cvt_pk_bf16_f32 v40, v44, v40
	v_cvt_pk_bf16_f32 v41, v41, v42
	v_cvt_pk_bf16_f32 v42, v55, v45
	v_cvt_pk_bf16_f32 v43, v46, v43
	global_store_dwordx4 v[52:53], v[40:43], off
	v_mul_f32_e32 v36, v36, v54
	v_mul_f32_e32 v32, v32, v54
	v_mul_f32_e32 v37, v37, v54
	v_mul_f32_e32 v33, v33, v54
	v_mul_f32_e32 v38, v38, v54
	v_mul_f32_e32 v34, v34, v54
	v_mul_f32_e32 v39, v39, v54
	v_mul_f32_e32 v35, v35, v54
	v_exp_f32_e32 v36, v36
	v_exp_f32_e32 v32, v32
	v_exp_f32_e32 v37, v37
	v_exp_f32_e32 v33, v33
	v_exp_f32_e32 v38, v38
	v_exp_f32_e32 v34, v34
	v_exp_f32_e32 v39, v39
	v_exp_f32_e32 v35, v35
	v_add_f32_e32 v36, 1.0, v36
	v_add_f32_e32 v32, 1.0, v32
	v_add_f32_e32 v37, 1.0, v37
	v_add_f32_e32 v33, 1.0, v33
	v_add_f32_e32 v38, 1.0, v38
	v_add_f32_e32 v34, 1.0, v34
	v_add_f32_e32 v39, 1.0, v39
	v_add_f32_e32 v35, 1.0, v35
	v_rcp_f32_e32 v36, v36
	v_rcp_f32_e32 v32, v32
	v_rcp_f32_e32 v37, v37
	v_rcp_f32_e32 v33, v33
	v_rcp_f32_e32 v38, v38
	v_rcp_f32_e32 v34, v34
	v_rcp_f32_e32 v39, v39
	v_rcp_f32_e32 v35, v35
	v_lshl_add_u64 v[44:45], v[142:143], 0, s[8:9]
	v_lshl_add_u64 v[46:47], s[20:21], 0, v[44:45]
	v_lshlrev_b32_e32 v48, 16, v224
	v_and_b32_e32 v40, 0xffff0000, v224
	v_lshlrev_b32_e32 v49, 16, v225
	v_and_b32_e32 v41, 0xffff0000, v225
	v_lshlrev_b32_e32 v50, 16, v226
	v_and_b32_e32 v42, 0xffff0000, v226
	v_lshlrev_b32_e32 v51, 16, v227
	v_and_b32_e32 v43, 0xffff0000, v227
	v_mul_f32_e32 v36, v36, v48
	v_mul_f32_e32 v48, v32, v50
	v_mul_f32_e32 v32, v37, v40
	v_mul_f32_e32 v37, v33, v42
	v_mul_f32_e32 v33, v38, v49
	v_mul_f32_e32 v38, v34, v51
	v_mul_f32_e32 v34, v39, v41
	v_mul_f32_e32 v35, v35, v43
	v_cvt_pk_bf16_f32 v32, v36, v32
	v_cvt_pk_bf16_f32 v33, v33, v34
	v_cvt_pk_bf16_f32 v34, v48, v37
	v_cvt_pk_bf16_f32 v35, v38, v35
	global_store_dwordx4 v[52:53], v[32:35], off offset:256
	global_load_dword v38, v[140:141], off offset:640
	s_nop 0
	global_load_dwordx4 v[32:35], v[46:47], off
	global_load_dwordx4 v[220:223], v[46:47], off offset:256
	v_lshl_add_u64 v[36:37], s[24:25], 0, v[44:45]
	s_waitcnt vmcnt(0)
; __device__ __forceinline__ float bf_lo(unsigned w) { return __uint_as_float(w << 16); }
; __device__ __forceinline__ float bf_hi(unsigned w) { return __uint_as_float(w & 0xffff0000u); }
; __device__ __forceinline__ float fast_rcp(float x) { return __builtin_amdgcn_rcpf(x); }
; __device__ __forceinline__ float fast_exp2(float x) { return __builtin_amdgcn_exp2f(x); }
; __device__ __forceinline__ u32x4 pack8(f32x4 v0, f32x4 v1) { u32x4 w; w.x = cvt_pk_bf16(v0[0], v0[1]); w.y = cvt_pk_bf16(v0[2], v0[3]); w.z = cvt_pk_bf16(v1[0], v1[1]); w.w = cvt_pk_bf16(v1[2], v1[3]); return w; }
;     __device__ __forceinline__ void operator()(const f32x4 (&acc)[2][2][4][2], const Unit& u, int wr, int wc, int fr, int fq) const {
;     ...
;             for (int m = 0; m < 4; ++m) { const size_t ro = (size_t)(row0 + ai * HALF + m * 16) * DM + col0; const float nr = -LOG2E * rs[row0 + ai * HALF + m * 16];
; #pragma unroll
;                 for (int bj = 0; bj < 2; ++bj) {
;                     const u32x4 pw = *(const u32x4*)(PP + ro + bj * HALF);
;                     const float pv[8] = {bf_lo(pw.x), bf_hi(pw.x), bf_lo(pw.y), bf_hi(pw.y), bf_lo(pw.z), bf_hi(pw.z), bf_lo(pw.w), bf_hi(pw.w)};
;                     f32x4 t0, t1;
; #pragma unroll
;                     for (int j = 0; j < 4; ++j) {
;                         t0[j] = fast_rcp(1.0f + fast_exp2(acc[ai][bj][m][0][j] * nr)) * pv[j];
;                         t1[j] = fast_rcp(1.0f + fast_exp2(acc[ai][bj][m][1][j] * nr)) * pv[4 + j]; }
;                     *(u32x4*)(O + ro + bj * HALF) = pack8(t0, t1); } }
	v_mul_f32_e32 v38, 0xbfb8aa3b, v38
	v_mul_f32_e32 v28, v28, v38
	v_mul_f32_e32 v24, v24, v38
	v_mul_f32_e32 v29, v29, v38
	v_mul_f32_e32 v25, v25, v38
	v_mul_f32_e32 v30, v30, v38
	v_mul_f32_e32 v26, v26, v38
	v_mul_f32_e32 v31, v31, v38
	v_mul_f32_e32 v27, v27, v38
	v_exp_f32_e32 v28, v28
	v_exp_f32_e32 v24, v24
	v_exp_f32_e32 v29, v29
	v_exp_f32_e32 v25, v25
	v_exp_f32_e32 v30, v30
	v_exp_f32_e32 v26, v26
	v_exp_f32_e32 v31, v31
	v_exp_f32_e32 v27, v27
	v_add_f32_e32 v28, 1.0, v28
	v_add_f32_e32 v24, 1.0, v24
	v_add_f32_e32 v29, 1.0, v29
	v_add_f32_e32 v25, 1.0, v25
	v_add_f32_e32 v30, 1.0, v30
	v_add_f32_e32 v26, 1.0, v26
	v_add_f32_e32 v31, 1.0, v31
	v_add_f32_e32 v27, 1.0, v27
	v_rcp_f32_e32 v28, v28
	v_rcp_f32_e32 v24, v24
	v_rcp_f32_e32 v29, v29
	v_rcp_f32_e32 v25, v25
	v_rcp_f32_e32 v30, v30
	v_rcp_f32_e32 v26, v26
	v_rcp_f32_e32 v31, v31
	v_rcp_f32_e32 v27, v27
	v_lshlrev_b32_e32 v39, 16, v32
	v_and_b32_e32 v32, 0xffff0000, v32
	v_lshlrev_b32_e32 v40, 16, v33
	v_and_b32_e32 v33, 0xffff0000, v33
	v_lshlrev_b32_e32 v41, 16, v34
	v_and_b32_e32 v34, 0xffff0000, v34
	v_lshlrev_b32_e32 v42, 16, v35
	v_and_b32_e32 v35, 0xffff0000, v35
	v_mul_f32_e32 v28, v28, v39
	v_mul_f32_e32 v39, v24, v41
	v_mul_f32_e32 v24, v29, v32
	v_mul_f32_e32 v29, v25, v34
	v_mul_f32_e32 v25, v30, v40
	v_mul_f32_e32 v30, v26, v42
	v_mul_f32_e32 v26, v31, v33
	v_mul_f32_e32 v27, v27, v35
	v_cvt_pk_bf16_f32 v24, v28, v24
	v_cvt_pk_bf16_f32 v25, v25, v26
	v_cvt_pk_bf16_f32 v26, v39, v29
	v_cvt_pk_bf16_f32 v27, v30, v27
	global_store_dwordx4 v[36:37], v[24:27], off
	v_mul_f32_e32 v20, v20, v38
	v_mul_f32_e32 v16, v16, v38
	v_mul_f32_e32 v21, v21, v38
	v_mul_f32_e32 v17, v17, v38
	v_mul_f32_e32 v22, v22, v38
	v_mul_f32_e32 v18, v18, v38
	v_mul_f32_e32 v23, v23, v38
	v_mul_f32_e32 v19, v19, v38
	v_exp_f32_e32 v20, v20
	v_exp_f32_e32 v16, v16
	v_exp_f32_e32 v21, v21
	v_exp_f32_e32 v17, v17
	v_exp_f32_e32 v22, v22
	v_exp_f32_e32 v18, v18
	v_exp_f32_e32 v23, v23
	v_exp_f32_e32 v19, v19
	v_add_f32_e32 v20, 1.0, v20
	v_add_f32_e32 v16, 1.0, v16
	v_add_f32_e32 v21, 1.0, v21
	v_add_f32_e32 v17, 1.0, v17
	v_add_f32_e32 v22, 1.0, v22
	v_add_f32_e32 v18, 1.0, v18
	v_add_f32_e32 v23, 1.0, v23
	v_add_f32_e32 v19, 1.0, v19
	v_rcp_f32_e32 v20, v20
	v_rcp_f32_e32 v16, v16
	v_rcp_f32_e32 v21, v21
	v_rcp_f32_e32 v17, v17
	v_rcp_f32_e32 v22, v22
	v_rcp_f32_e32 v18, v18
	v_rcp_f32_e32 v23, v23
	v_rcp_f32_e32 v19, v19
	v_lshl_add_u64 v[28:29], v[142:143], 0, s[30:31]
	v_lshl_add_u64 v[30:31], s[20:21], 0, v[28:29]
	v_lshlrev_b32_e32 v32, 16, v220
	v_and_b32_e32 v24, 0xffff0000, v220
	v_lshlrev_b32_e32 v33, 16, v221
	v_and_b32_e32 v25, 0xffff0000, v221
	v_lshlrev_b32_e32 v34, 16, v222
	v_and_b32_e32 v26, 0xffff0000, v222
	v_lshlrev_b32_e32 v35, 16, v223
	v_and_b32_e32 v27, 0xffff0000, v223
	v_mul_f32_e32 v20, v20, v32
	v_mul_f32_e32 v32, v16, v34
	v_mul_f32_e32 v16, v21, v24
	v_mul_f32_e32 v21, v17, v26
	v_mul_f32_e32 v17, v22, v33
	v_mul_f32_e32 v22, v18, v35
	v_mul_f32_e32 v18, v23, v25
	v_mul_f32_e32 v19, v19, v27
	v_cvt_pk_bf16_f32 v16, v20, v16
	v_cvt_pk_bf16_f32 v17, v17, v18
	v_cvt_pk_bf16_f32 v18, v32, v21
	v_cvt_pk_bf16_f32 v19, v22, v19
	global_store_dwordx4 v[36:37], v[16:19], off offset:256
	global_load_dword v22, v[140:141], off offset:704
	s_nop 0
	global_load_dwordx4 v[16:19], v[30:31], off
	global_load_dwordx4 v[224:227], v[30:31], off offset:256
	v_lshl_add_u64 v[20:21], s[24:25], 0, v[28:29]
	s_waitcnt vmcnt(0)
	v_mul_f32_e32 v22, 0xbfb8aa3b, v22
	v_mul_f32_e32 v12, v12, v22
	v_mul_f32_e32 v8, v8, v22
	v_mul_f32_e32 v13, v13, v22
	v_mul_f32_e32 v9, v9, v22
	v_mul_f32_e32 v14, v14, v22
	v_mul_f32_e32 v10, v10, v22
	v_mul_f32_e32 v15, v15, v22
	v_mul_f32_e32 v11, v11, v22
	v_exp_f32_e32 v12, v12
	v_exp_f32_e32 v8, v8
	v_exp_f32_e32 v13, v13
	v_exp_f32_e32 v9, v9
	v_exp_f32_e32 v14, v14
	v_exp_f32_e32 v10, v10
	v_exp_f32_e32 v15, v15
	v_exp_f32_e32 v11, v11
	v_add_f32_e32 v12, 1.0, v12
	v_add_f32_e32 v8, 1.0, v8
	v_add_f32_e32 v13, 1.0, v13
	v_add_f32_e32 v9, 1.0, v9
	v_add_f32_e32 v14, 1.0, v14
	v_add_f32_e32 v10, 1.0, v10
	v_add_f32_e32 v15, 1.0, v15
	v_add_f32_e32 v11, 1.0, v11
	v_rcp_f32_e32 v12, v12
	v_rcp_f32_e32 v8, v8
	v_rcp_f32_e32 v13, v13
	v_rcp_f32_e32 v9, v9
	v_rcp_f32_e32 v14, v14
	v_rcp_f32_e32 v10, v10
	v_rcp_f32_e32 v15, v15
	v_rcp_f32_e32 v11, v11
	v_lshlrev_b32_e32 v23, 16, v16
	v_and_b32_e32 v16, 0xffff0000, v16
	v_lshlrev_b32_e32 v24, 16, v17
	v_and_b32_e32 v17, 0xffff0000, v17
	v_lshlrev_b32_e32 v25, 16, v18
	v_and_b32_e32 v18, 0xffff0000, v18
	v_lshlrev_b32_e32 v26, 16, v19
	v_and_b32_e32 v19, 0xffff0000, v19
	v_mul_f32_e32 v12, v12, v23
	v_mul_f32_e32 v23, v8, v25
	v_mul_f32_e32 v8, v13, v16
	v_mul_f32_e32 v13, v9, v18
	v_mul_f32_e32 v9, v14, v24
	v_mul_f32_e32 v14, v10, v26
	v_mul_f32_e32 v10, v15, v17
	v_mul_f32_e32 v11, v11, v19
	v_cvt_pk_bf16_f32 v8, v12, v8
	v_cvt_pk_bf16_f32 v9, v9, v10
	v_cvt_pk_bf16_f32 v10, v23, v13
	v_cvt_pk_bf16_f32 v11, v14, v11
	global_store_dwordx4 v[20:21], v[8:11], off
	v_mul_f32_e32 v4, v4, v22
	v_mul_f32_e32 v0, v0, v22
	v_mul_f32_e32 v5, v5, v22
	v_mul_f32_e32 v1, v1, v22
	v_mul_f32_e32 v6, v6, v22
	v_mul_f32_e32 v2, v2, v22
	v_mul_f32_e32 v7, v7, v22
	v_mul_f32_e32 v3, v3, v22
	v_exp_f32_e32 v4, v4
	v_exp_f32_e32 v0, v0
	v_exp_f32_e32 v5, v5
	v_exp_f32_e32 v1, v1
	v_exp_f32_e32 v6, v6
	v_exp_f32_e32 v2, v2
	v_exp_f32_e32 v7, v7
	v_exp_f32_e32 v3, v3
	v_add_f32_e32 v4, 1.0, v4
	v_add_f32_e32 v0, 1.0, v0
	v_add_f32_e32 v5, 1.0, v5
	v_add_f32_e32 v1, 1.0, v1
	v_add_f32_e32 v6, 1.0, v6
	v_add_f32_e32 v2, 1.0, v2
	v_add_f32_e32 v7, 1.0, v7
	v_add_f32_e32 v3, 1.0, v3
	v_rcp_f32_e32 v4, v4
	v_rcp_f32_e32 v0, v0
	v_rcp_f32_e32 v5, v5
	v_rcp_f32_e32 v1, v1
	v_rcp_f32_e32 v6, v6
	v_rcp_f32_e32 v2, v2
	v_rcp_f32_e32 v7, v7
	v_rcp_f32_e32 v3, v3
	v_lshlrev_b32_e32 v12, 16, v224
	v_and_b32_e32 v8, 0xffff0000, v224
	v_lshlrev_b32_e32 v13, 16, v225
	v_and_b32_e32 v9, 0xffff0000, v225
	v_lshlrev_b32_e32 v14, 16, v226
	v_and_b32_e32 v10, 0xffff0000, v226
	v_lshlrev_b32_e32 v15, 16, v227
	v_and_b32_e32 v11, 0xffff0000, v227
	v_mul_f32_e32 v4, v4, v12
	v_mul_f32_e32 v12, v0, v14
	v_mul_f32_e32 v0, v5, v8
	v_mul_f32_e32 v5, v1, v10
	v_mul_f32_e32 v1, v6, v13
	v_mul_f32_e32 v6, v2, v15
	v_mul_f32_e32 v2, v7, v9
	v_mul_f32_e32 v3, v3, v11
	v_cvt_pk_bf16_f32 v0, v4, v0
	v_cvt_pk_bf16_f32 v1, v1, v2
	v_cvt_pk_bf16_f32 v2, v12, v5
	v_cvt_pk_bf16_f32 v3, v6, v3
	global_store_dwordx4 v[20:21], v[0:3], off offset:256
	s_cbranch_vccz .LBB0_996
	s_waitcnt vmcnt(0)
	s_cmpk_gt_u32 s10, 0xff
	s_cbranch_scc1 .LBB0_1003
	s_barrier
